# scan compute loop hand-scheduled (2 rows x 8 k per lane, half the LDS reads) + attention lazy softmax rescale (threshold 8 log2 units)
# speedup vs baseline: 1.0335x; 1.0335x over previous
.LBB0_1623:
	v_and_b32_e32 v0, 7, v221
	v_lshrrev_b32_e32 v2, 3, v221
	v_lshlrev_b32_e32 v222, 5, v0
	v_lshlrev_b32_e32 v2, 3, v2
	v_add_u32_e32 v223, s50, v2
	v_cmp_eq_u32_e32 vcc, 0, v0
	v_lshlrev_b32_e32 v3, 3, v221
	v_add_u32_e32 v3, 0x14800, v3
	v_mov_b32_e32 v4, 0xe200
	v_cndmask_b32_e32 v137, v3, v223, vcc
	v_cndmask_b32_e32 v136, 0, v4, vcc
	s_mov_b32 s13, 0
	v_mov_b32_e32 v2, 0
	v_mov_b32_e32 v3, 0
	v_mov_b32_e32 v4, 0
	v_mov_b32_e32 v5, 0
	v_mov_b32_e32 v6, 0
	v_mov_b32_e32 v7, 0
	v_mov_b32_e32 v8, 0
	v_mov_b32_e32 v9, 0
	v_mov_b32_e32 v10, 0
	v_mov_b32_e32 v11, 0
	v_mov_b32_e32 v12, 0
	v_mov_b32_e32 v13, 0
	v_mov_b32_e32 v14, 0
	v_mov_b32_e32 v15, 0
	v_mov_b32_e32 v16, 0
	v_mov_b32_e32 v17, 0
.Lscan_chunk:
	s_and_b32 s10, s13, 1
	s_mul_i32 s16, s10, 0xe200
	v_add_u32_e32 v225, s16, v222
	v_add_u32_e32 v224, s16, v223
	v_mov_b32_e32 v134, s16
	v_mad_u32_u24 v135, v136, s10, v137
	s_waitcnt lgkmcnt(0)
	s_barrier
	ds_read_b128 v[20:23], v225 offset:0
	ds_read_b128 v[24:27], v225 offset:16
	ds_read_b128 v[28:31], v225 offset:32768
	ds_read_b128 v[32:35], v225 offset:32784
	ds_read_b64 v[60:61], v224 offset:40960
	ds_read_b128 v[36:39], v225 offset:24576
	ds_read_b128 v[40:43], v225 offset:24592
	ds_read_b64 v[62:63], v134 offset:57344
	ds_read_b128 v[44:47], v225 offset:16384
	ds_read_b128 v[48:51], v225 offset:16400
	ds_read_b128 v[52:55], v225 offset:8192
	ds_read_b128 v[56:59], v225 offset:8208
	s_waitcnt lgkmcnt(8)
	v_pk_mul_f32 v[108:109], v[2:3], v[20:21] op_sel_hi:[1,0]
	v_pk_mul_f32 v[110:111], v[4:5], v[20:21] op_sel:[0,1]
	v_pk_mul_f32 v[112:113], v[2:3], v[28:29] op_sel_hi:[1,0]
	v_pk_mul_f32 v[114:115], v[4:5], v[28:29] op_sel:[0,1]
	ds_read_b128 v[64:67], v225 offset:256
	v_pk_fma_f32 v[108:109], v[6:7], v[22:23], v[108:109] op_sel_hi:[1,0,1]
	v_pk_fma_f32 v[110:111], v[8:9], v[22:23], v[110:111] op_sel:[0,1,0]
	v_pk_fma_f32 v[112:113], v[6:7], v[30:31], v[112:113] op_sel_hi:[1,0,1]
	v_pk_fma_f32 v[114:115], v[8:9], v[30:31], v[114:115] op_sel:[0,1,0]
	ds_read_b128 v[68:71], v225 offset:272
	v_pk_fma_f32 v[108:109], v[10:11], v[24:25], v[108:109] op_sel_hi:[1,0,1]
	v_pk_fma_f32 v[110:111], v[12:13], v[24:25], v[110:111] op_sel:[0,1,0]
	v_pk_fma_f32 v[112:113], v[10:11], v[32:33], v[112:113] op_sel_hi:[1,0,1]
	v_pk_fma_f32 v[114:115], v[12:13], v[32:33], v[114:115] op_sel:[0,1,0]
	ds_read_b128 v[72:75], v225 offset:33024
	v_pk_fma_f32 v[108:109], v[14:15], v[26:27], v[108:109] op_sel_hi:[1,0,1]
	v_pk_fma_f32 v[110:111], v[16:17], v[26:27], v[110:111] op_sel:[0,1,0]
	v_pk_fma_f32 v[112:113], v[14:15], v[34:35], v[112:113] op_sel_hi:[1,0,1]
	v_pk_fma_f32 v[114:115], v[16:17], v[34:35], v[114:115] op_sel:[0,1,0]
	ds_read_b128 v[76:79], v225 offset:33040
	v_pk_add_f32 v[108:109], v[108:109], v[110:111]
	v_pk_add_f32 v[112:113], v[112:113], v[114:115]
	s_waitcnt lgkmcnt(10)
	v_pk_mul_f32 v[116:117], v[60:61], v[36:37] op_sel_hi:[1,0]
	v_pk_mul_f32 v[118:119], v[60:61], v[36:37] op_sel:[0,1]
	v_pk_mul_f32 v[120:121], v[60:61], v[38:39] op_sel_hi:[1,0]
	v_pk_mul_f32 v[122:123], v[60:61], v[38:39] op_sel:[0,1]
	ds_read_b64 v[104:105], v224 offset:41216
	ds_read_b128 v[80:83], v225 offset:24832
	v_add_f32_dpp v108, v108, v108 quad_perm:[1,0,3,2] row_mask:0xf bank_mask:0xf bound_ctrl:1
	v_add_f32_dpp v109, v109, v109 quad_perm:[1,0,3,2] row_mask:0xf bank_mask:0xf bound_ctrl:1
	v_add_f32_dpp v112, v112, v112 quad_perm:[1,0,3,2] row_mask:0xf bank_mask:0xf bound_ctrl:1
	v_add_f32_dpp v113, v113, v113 quad_perm:[1,0,3,2] row_mask:0xf bank_mask:0xf bound_ctrl:1
	s_waitcnt lgkmcnt(11)
	v_pk_mul_f32 v[124:125], v[60:61], v[40:41] op_sel_hi:[1,0]
	v_pk_mul_f32 v[126:127], v[60:61], v[40:41] op_sel:[0,1]
	v_pk_mul_f32 v[128:129], v[60:61], v[42:43] op_sel_hi:[1,0]
	v_pk_mul_f32 v[130:131], v[60:61], v[42:43] op_sel:[0,1]
	ds_read_b128 v[84:87], v225 offset:24848
	ds_read_b64 v[106:107], v134 offset:57352
	v_add_f32_dpp v108, v108, v108 quad_perm:[2,3,0,1] row_mask:0xf bank_mask:0xf bound_ctrl:1
	v_add_f32_dpp v109, v109, v109 quad_perm:[2,3,0,1] row_mask:0xf bank_mask:0xf bound_ctrl:1
	v_add_f32_dpp v112, v112, v112 quad_perm:[2,3,0,1] row_mask:0xf bank_mask:0xf bound_ctrl:1
	v_add_f32_dpp v113, v113, v113 quad_perm:[2,3,0,1] row_mask:0xf bank_mask:0xf bound_ctrl:1
	ds_read_b128 v[88:91], v225 offset:16640
	s_nop 0
	v_add_f32_dpp v108, v108, v108 row_half_mirror row_mask:0xf bank_mask:0xf bound_ctrl:1
	v_add_f32_dpp v109, v109, v109 row_half_mirror row_mask:0xf bank_mask:0xf bound_ctrl:1
	v_add_f32_dpp v112, v112, v112 row_half_mirror row_mask:0xf bank_mask:0xf bound_ctrl:1
	v_add_f32_dpp v113, v113, v113 row_half_mirror row_mask:0xf bank_mask:0xf bound_ctrl:1
	ds_read_b128 v[92:95], v225 offset:16656
	s_waitcnt lgkmcnt(12)
	s_nop 0
	v_pk_fma_f32 v[116:117], v[108:109], v[44:45], v[116:117] op_sel_hi:[1,0,1] neg_lo:[1,0,0] neg_hi:[1,0,0]
	v_pk_fma_f32 v[118:119], v[108:109], v[44:45], v[118:119] op_sel:[0,1,0] neg_lo:[1,0,0] neg_hi:[1,0,0]
	v_pk_fma_f32 v[120:121], v[108:109], v[46:47], v[120:121] op_sel_hi:[1,0,1] neg_lo:[1,0,0] neg_hi:[1,0,0]
	v_pk_fma_f32 v[122:123], v[108:109], v[46:47], v[122:123] op_sel:[0,1,0] neg_lo:[1,0,0] neg_hi:[1,0,0]
	v_pk_fma_f32 v[124:125], v[108:109], v[48:49], v[124:125] op_sel_hi:[1,0,1] neg_lo:[1,0,0] neg_hi:[1,0,0]
	v_pk_fma_f32 v[126:127], v[108:109], v[48:49], v[126:127] op_sel:[0,1,0] neg_lo:[1,0,0] neg_hi:[1,0,0]
	v_pk_fma_f32 v[128:129], v[108:109], v[50:51], v[128:129] op_sel_hi:[1,0,1] neg_lo:[1,0,0] neg_hi:[1,0,0]
	v_pk_fma_f32 v[130:131], v[108:109], v[50:51], v[130:131] op_sel:[0,1,0] neg_lo:[1,0,0] neg_hi:[1,0,0]
	ds_read_b128 v[96:99], v225 offset:8448
	v_pk_fma_f32 v[132:133], v[108:109], v[62:63], v[112:113] op_sel_hi:[1,0,1] neg_lo:[1,0,0] neg_hi:[1,0,0]
	ds_read_b128 v[100:103], v225 offset:8464
	s_waitcnt lgkmcnt(12)
	v_pk_fma_f32 v[2:3], v[2:3], v[52:53], v[116:117] op_sel_hi:[1,0,1]
	v_pk_fma_f32 v[4:5], v[4:5], v[52:53], v[118:119] op_sel:[0,1,0]
	v_pk_fma_f32 v[6:7], v[6:7], v[54:55], v[120:121] op_sel_hi:[1,0,1]
	v_pk_fma_f32 v[8:9], v[8:9], v[54:55], v[122:123] op_sel:[0,1,0]
	v_pk_fma_f32 v[132:133], v[60:61], v[62:63], v[132:133] op_sel:[0,1,0]
	v_pk_fma_f32 v[10:11], v[10:11], v[56:57], v[124:125] op_sel_hi:[1,0,1]
	v_pk_fma_f32 v[12:13], v[12:13], v[56:57], v[126:127] op_sel:[0,1,0]
	v_pk_fma_f32 v[14:15], v[14:15], v[58:59], v[128:129] op_sel_hi:[1,0,1]
	v_pk_fma_f32 v[16:17], v[16:17], v[58:59], v[130:131] op_sel:[0,1,0]
	ds_write_b64 v135, v[132:133] offset:49152
	s_waitcnt lgkmcnt(9)
	v_pk_mul_f32 v[108:109], v[2:3], v[64:65] op_sel_hi:[1,0]
	v_pk_mul_f32 v[110:111], v[4:5], v[64:65] op_sel:[0,1]
	v_pk_mul_f32 v[112:113], v[2:3], v[72:73] op_sel_hi:[1,0]
	v_pk_mul_f32 v[114:115], v[4:5], v[72:73] op_sel:[0,1]
	ds_read_b128 v[20:23], v225 offset:512
	v_pk_fma_f32 v[108:109], v[6:7], v[66:67], v[108:109] op_sel_hi:[1,0,1]
	v_pk_fma_f32 v[110:111], v[8:9], v[66:67], v[110:111] op_sel:[0,1,0]
	v_pk_fma_f32 v[112:113], v[6:7], v[74:75], v[112:113] op_sel_hi:[1,0,1]
	v_pk_fma_f32 v[114:115], v[8:9], v[74:75], v[114:115] op_sel:[0,1,0]
	ds_read_b128 v[24:27], v225 offset:528
	v_pk_fma_f32 v[108:109], v[10:11], v[68:69], v[108:109] op_sel_hi:[1,0,1]
	v_pk_fma_f32 v[110:111], v[12:13], v[68:69], v[110:111] op_sel:[0,1,0]
	v_pk_fma_f32 v[112:113], v[10:11], v[76:77], v[112:113] op_sel_hi:[1,0,1]
	v_pk_fma_f32 v[114:115], v[12:13], v[76:77], v[114:115] op_sel:[0,1,0]
	ds_read_b128 v[28:31], v225 offset:33280
	v_pk_fma_f32 v[108:109], v[14:15], v[70:71], v[108:109] op_sel_hi:[1,0,1]
	v_pk_fma_f32 v[110:111], v[16:17], v[70:71], v[110:111] op_sel:[0,1,0]
	v_pk_fma_f32 v[112:113], v[14:15], v[78:79], v[112:113] op_sel_hi:[1,0,1]
	v_pk_fma_f32 v[114:115], v[16:17], v[78:79], v[114:115] op_sel:[0,1,0]
	ds_read_b128 v[32:35], v225 offset:33296
	v_pk_add_f32 v[108:109], v[108:109], v[110:111]
	v_pk_add_f32 v[112:113], v[112:113], v[114:115]
	s_waitcnt lgkmcnt(11)
	v_pk_mul_f32 v[116:117], v[104:105], v[80:81] op_sel_hi:[1,0]
	v_pk_mul_f32 v[118:119], v[104:105], v[80:81] op_sel:[0,1]
	v_pk_mul_f32 v[120:121], v[104:105], v[82:83] op_sel_hi:[1,0]
	v_pk_mul_f32 v[122:123], v[104:105], v[82:83] op_sel:[0,1]
	ds_read_b64 v[60:61], v224 offset:41472
	ds_read_b128 v[36:39], v225 offset:25088
	v_add_f32_dpp v108, v108, v108 quad_perm:[1,0,3,2] row_mask:0xf bank_mask:0xf bound_ctrl:1
	v_add_f32_dpp v109, v109, v109 quad_perm:[1,0,3,2] row_mask:0xf bank_mask:0xf bound_ctrl:1
	v_add_f32_dpp v112, v112, v112 quad_perm:[1,0,3,2] row_mask:0xf bank_mask:0xf bound_ctrl:1
	v_add_f32_dpp v113, v113, v113 quad_perm:[1,0,3,2] row_mask:0xf bank_mask:0xf bound_ctrl:1
	s_waitcnt lgkmcnt(12)
	v_pk_mul_f32 v[124:125], v[104:105], v[84:85] op_sel_hi:[1,0]
	v_pk_mul_f32 v[126:127], v[104:105], v[84:85] op_sel:[0,1]
	v_pk_mul_f32 v[128:129], v[104:105], v[86:87] op_sel_hi:[1,0]
	v_pk_mul_f32 v[130:131], v[104:105], v[86:87] op_sel:[0,1]
	ds_read_b128 v[40:43], v225 offset:25104
	ds_read_b64 v[62:63], v134 offset:57360
	v_add_f32_dpp v108, v108, v108 quad_perm:[2,3,0,1] row_mask:0xf bank_mask:0xf bound_ctrl:1
	v_add_f32_dpp v109, v109, v109 quad_perm:[2,3,0,1] row_mask:0xf bank_mask:0xf bound_ctrl:1
	v_add_f32_dpp v112, v112, v112 quad_perm:[2,3,0,1] row_mask:0xf bank_mask:0xf bound_ctrl:1
	v_add_f32_dpp v113, v113, v113 quad_perm:[2,3,0,1] row_mask:0xf bank_mask:0xf bound_ctrl:1
	ds_read_b128 v[44:47], v225 offset:16896
	s_nop 0
	v_add_f32_dpp v108, v108, v108 row_half_mirror row_mask:0xf bank_mask:0xf bound_ctrl:1
	v_add_f32_dpp v109, v109, v109 row_half_mirror row_mask:0xf bank_mask:0xf bound_ctrl:1
	v_add_f32_dpp v112, v112, v112 row_half_mirror row_mask:0xf bank_mask:0xf bound_ctrl:1
	v_add_f32_dpp v113, v113, v113 row_half_mirror row_mask:0xf bank_mask:0xf bound_ctrl:1
	ds_read_b128 v[48:51], v225 offset:16912
	s_waitcnt lgkmcnt(13)
	s_nop 0
	v_pk_fma_f32 v[116:117], v[108:109], v[88:89], v[116:117] op_sel_hi:[1,0,1] neg_lo:[1,0,0] neg_hi:[1,0,0]
	v_pk_fma_f32 v[118:119], v[108:109], v[88:89], v[118:119] op_sel:[0,1,0] neg_lo:[1,0,0] neg_hi:[1,0,0]
	v_pk_fma_f32 v[120:121], v[108:109], v[90:91], v[120:121] op_sel_hi:[1,0,1] neg_lo:[1,0,0] neg_hi:[1,0,0]
	v_pk_fma_f32 v[122:123], v[108:109], v[90:91], v[122:123] op_sel:[0,1,0] neg_lo:[1,0,0] neg_hi:[1,0,0]
	v_pk_fma_f32 v[124:125], v[108:109], v[92:93], v[124:125] op_sel_hi:[1,0,1] neg_lo:[1,0,0] neg_hi:[1,0,0]
	v_pk_fma_f32 v[126:127], v[108:109], v[92:93], v[126:127] op_sel:[0,1,0] neg_lo:[1,0,0] neg_hi:[1,0,0]
	v_pk_fma_f32 v[128:129], v[108:109], v[94:95], v[128:129] op_sel_hi:[1,0,1] neg_lo:[1,0,0] neg_hi:[1,0,0]
	v_pk_fma_f32 v[130:131], v[108:109], v[94:95], v[130:131] op_sel:[0,1,0] neg_lo:[1,0,0] neg_hi:[1,0,0]
	ds_read_b128 v[52:55], v225 offset:8704
	v_pk_fma_f32 v[132:133], v[108:109], v[106:107], v[112:113] op_sel_hi:[1,0,1] neg_lo:[1,0,0] neg_hi:[1,0,0]
	ds_read_b128 v[56:59], v225 offset:8720
	s_waitcnt lgkmcnt(13)
	v_pk_fma_f32 v[2:3], v[2:3], v[96:97], v[116:117] op_sel_hi:[1,0,1]
	v_pk_fma_f32 v[4:5], v[4:5], v[96:97], v[118:119] op_sel:[0,1,0]
	v_pk_fma_f32 v[6:7], v[6:7], v[98:99], v[120:121] op_sel_hi:[1,0,1]
	v_pk_fma_f32 v[8:9], v[8:9], v[98:99], v[122:123] op_sel:[0,1,0]
	v_pk_fma_f32 v[132:133], v[104:105], v[106:107], v[132:133] op_sel:[0,1,0]
	v_pk_fma_f32 v[10:11], v[10:11], v[100:101], v[124:125] op_sel_hi:[1,0,1]
	v_pk_fma_f32 v[12:13], v[12:13], v[100:101], v[126:127] op_sel:[0,1,0]
	v_pk_fma_f32 v[14:15], v[14:15], v[102:103], v[128:129] op_sel_hi:[1,0,1]
	v_pk_fma_f32 v[16:17], v[16:17], v[102:103], v[130:131] op_sel:[0,1,0]
	ds_write_b64 v135, v[132:133] offset:49408
	s_waitcnt lgkmcnt(9)
	v_pk_mul_f32 v[108:109], v[2:3], v[20:21] op_sel_hi:[1,0]
	v_pk_mul_f32 v[110:111], v[4:5], v[20:21] op_sel:[0,1]
	v_pk_mul_f32 v[112:113], v[2:3], v[28:29] op_sel_hi:[1,0]
	v_pk_mul_f32 v[114:115], v[4:5], v[28:29] op_sel:[0,1]
	ds_read_b128 v[64:67], v225 offset:768
	v_pk_fma_f32 v[108:109], v[6:7], v[22:23], v[108:109] op_sel_hi:[1,0,1]
	v_pk_fma_f32 v[110:111], v[8:9], v[22:23], v[110:111] op_sel:[0,1,0]
	v_pk_fma_f32 v[112:113], v[6:7], v[30:31], v[112:113] op_sel_hi:[1,0,1]
	v_pk_fma_f32 v[114:115], v[8:9], v[30:31], v[114:115] op_sel:[0,1,0]
	ds_read_b128 v[68:71], v225 offset:784
	v_pk_fma_f32 v[108:109], v[10:11], v[24:25], v[108:109] op_sel_hi:[1,0,1]
	v_pk_fma_f32 v[110:111], v[12:13], v[24:25], v[110:111] op_sel:[0,1,0]
	v_pk_fma_f32 v[112:113], v[10:11], v[32:33], v[112:113] op_sel_hi:[1,0,1]
	v_pk_fma_f32 v[114:115], v[12:13], v[32:33], v[114:115] op_sel:[0,1,0]
	ds_read_b128 v[72:75], v225 offset:33536
	v_pk_fma_f32 v[108:109], v[14:15], v[26:27], v[108:109] op_sel_hi:[1,0,1]
	v_pk_fma_f32 v[110:111], v[16:17], v[26:27], v[110:111] op_sel:[0,1,0]
	v_pk_fma_f32 v[112:113], v[14:15], v[34:35], v[112:113] op_sel_hi:[1,0,1]
	v_pk_fma_f32 v[114:115], v[16:17], v[34:35], v[114:115] op_sel:[0,1,0]
	ds_read_b128 v[76:79], v225 offset:33552
	v_pk_add_f32 v[108:109], v[108:109], v[110:111]
	v_pk_add_f32 v[112:113], v[112:113], v[114:115]
	s_waitcnt lgkmcnt(11)
	v_pk_mul_f32 v[116:117], v[60:61], v[36:37] op_sel_hi:[1,0]
	v_pk_mul_f32 v[118:119], v[60:61], v[36:37] op_sel:[0,1]
	v_pk_mul_f32 v[120:121], v[60:61], v[38:39] op_sel_hi:[1,0]
	v_pk_mul_f32 v[122:123], v[60:61], v[38:39] op_sel:[0,1]
	ds_read_b64 v[104:105], v224 offset:41728
	ds_read_b128 v[80:83], v225 offset:25344
	v_add_f32_dpp v108, v108, v108 quad_perm:[1,0,3,2] row_mask:0xf bank_mask:0xf bound_ctrl:1
	v_add_f32_dpp v109, v109, v109 quad_perm:[1,0,3,2] row_mask:0xf bank_mask:0xf bound_ctrl:1
	v_add_f32_dpp v112, v112, v112 quad_perm:[1,0,3,2] row_mask:0xf bank_mask:0xf bound_ctrl:1
	v_add_f32_dpp v113, v113, v113 quad_perm:[1,0,3,2] row_mask:0xf bank_mask:0xf bound_ctrl:1
	s_waitcnt lgkmcnt(12)
	v_pk_mul_f32 v[124:125], v[60:61], v[40:41] op_sel_hi:[1,0]
	v_pk_mul_f32 v[126:127], v[60:61], v[40:41] op_sel:[0,1]
	v_pk_mul_f32 v[128:129], v[60:61], v[42:43] op_sel_hi:[1,0]
	v_pk_mul_f32 v[130:131], v[60:61], v[42:43] op_sel:[0,1]
	ds_read_b128 v[84:87], v225 offset:25360
	ds_read_b64 v[106:107], v134 offset:57368
	v_add_f32_dpp v108, v108, v108 quad_perm:[2,3,0,1] row_mask:0xf bank_mask:0xf bound_ctrl:1
	v_add_f32_dpp v109, v109, v109 quad_perm:[2,3,0,1] row_mask:0xf bank_mask:0xf bound_ctrl:1
	v_add_f32_dpp v112, v112, v112 quad_perm:[2,3,0,1] row_mask:0xf bank_mask:0xf bound_ctrl:1
	v_add_f32_dpp v113, v113, v113 quad_perm:[2,3,0,1] row_mask:0xf bank_mask:0xf bound_ctrl:1
	ds_read_b128 v[88:91], v225 offset:17152
	s_nop 0
	v_add_f32_dpp v108, v108, v108 row_half_mirror row_mask:0xf bank_mask:0xf bound_ctrl:1
	v_add_f32_dpp v109, v109, v109 row_half_mirror row_mask:0xf bank_mask:0xf bound_ctrl:1
	v_add_f32_dpp v112, v112, v112 row_half_mirror row_mask:0xf bank_mask:0xf bound_ctrl:1
	v_add_f32_dpp v113, v113, v113 row_half_mirror row_mask:0xf bank_mask:0xf bound_ctrl:1
	ds_read_b128 v[92:95], v225 offset:17168
	s_waitcnt lgkmcnt(13)
	s_nop 0
	v_pk_fma_f32 v[116:117], v[108:109], v[44:45], v[116:117] op_sel_hi:[1,0,1] neg_lo:[1,0,0] neg_hi:[1,0,0]
	v_pk_fma_f32 v[118:119], v[108:109], v[44:45], v[118:119] op_sel:[0,1,0] neg_lo:[1,0,0] neg_hi:[1,0,0]
	v_pk_fma_f32 v[120:121], v[108:109], v[46:47], v[120:121] op_sel_hi:[1,0,1] neg_lo:[1,0,0] neg_hi:[1,0,0]
	v_pk_fma_f32 v[122:123], v[108:109], v[46:47], v[122:123] op_sel:[0,1,0] neg_lo:[1,0,0] neg_hi:[1,0,0]
	v_pk_fma_f32 v[124:125], v[108:109], v[48:49], v[124:125] op_sel_hi:[1,0,1] neg_lo:[1,0,0] neg_hi:[1,0,0]
	v_pk_fma_f32 v[126:127], v[108:109], v[48:49], v[126:127] op_sel:[0,1,0] neg_lo:[1,0,0] neg_hi:[1,0,0]
	v_pk_fma_f32 v[128:129], v[108:109], v[50:51], v[128:129] op_sel_hi:[1,0,1] neg_lo:[1,0,0] neg_hi:[1,0,0]
	v_pk_fma_f32 v[130:131], v[108:109], v[50:51], v[130:131] op_sel:[0,1,0] neg_lo:[1,0,0] neg_hi:[1,0,0]
	ds_read_b128 v[96:99], v225 offset:8960
	v_pk_fma_f32 v[132:133], v[108:109], v[62:63], v[112:113] op_sel_hi:[1,0,1] neg_lo:[1,0,0] neg_hi:[1,0,0]
	ds_read_b128 v[100:103], v225 offset:8976
	s_waitcnt lgkmcnt(13)
	v_pk_fma_f32 v[2:3], v[2:3], v[52:53], v[116:117] op_sel_hi:[1,0,1]
	v_pk_fma_f32 v[4:5], v[4:5], v[52:53], v[118:119] op_sel:[0,1,0]
	v_pk_fma_f32 v[6:7], v[6:7], v[54:55], v[120:121] op_sel_hi:[1,0,1]
	v_pk_fma_f32 v[8:9], v[8:9], v[54:55], v[122:123] op_sel:[0,1,0]
	v_pk_fma_f32 v[132:133], v[60:61], v[62:63], v[132:133] op_sel:[0,1,0]
	v_pk_fma_f32 v[10:11], v[10:11], v[56:57], v[124:125] op_sel_hi:[1,0,1]
	v_pk_fma_f32 v[12:13], v[12:13], v[56:57], v[126:127] op_sel:[0,1,0]
	v_pk_fma_f32 v[14:15], v[14:15], v[58:59], v[128:129] op_sel_hi:[1,0,1]
	v_pk_fma_f32 v[16:17], v[16:17], v[58:59], v[130:131] op_sel:[0,1,0]
	ds_write_b64 v135, v[132:133] offset:49664
	s_waitcnt lgkmcnt(9)
	v_pk_mul_f32 v[108:109], v[2:3], v[64:65] op_sel_hi:[1,0]
	v_pk_mul_f32 v[110:111], v[4:5], v[64:65] op_sel:[0,1]
	v_pk_mul_f32 v[112:113], v[2:3], v[72:73] op_sel_hi:[1,0]
	v_pk_mul_f32 v[114:115], v[4:5], v[72:73] op_sel:[0,1]
	ds_read_b128 v[20:23], v225 offset:1024
	v_pk_fma_f32 v[108:109], v[6:7], v[66:67], v[108:109] op_sel_hi:[1,0,1]
	v_pk_fma_f32 v[110:111], v[8:9], v[66:67], v[110:111] op_sel:[0,1,0]
	v_pk_fma_f32 v[112:113], v[6:7], v[74:75], v[112:113] op_sel_hi:[1,0,1]
	v_pk_fma_f32 v[114:115], v[8:9], v[74:75], v[114:115] op_sel:[0,1,0]
	ds_read_b128 v[24:27], v225 offset:1040
	v_pk_fma_f32 v[108:109], v[10:11], v[68:69], v[108:109] op_sel_hi:[1,0,1]
	v_pk_fma_f32 v[110:111], v[12:13], v[68:69], v[110:111] op_sel:[0,1,0]
	v_pk_fma_f32 v[112:113], v[10:11], v[76:77], v[112:113] op_sel_hi:[1,0,1]
	v_pk_fma_f32 v[114:115], v[12:13], v[76:77], v[114:115] op_sel:[0,1,0]
	ds_read_b128 v[28:31], v225 offset:33792
	v_pk_fma_f32 v[108:109], v[14:15], v[70:71], v[108:109] op_sel_hi:[1,0,1]
	v_pk_fma_f32 v[110:111], v[16:17], v[70:71], v[110:111] op_sel:[0,1,0]
	v_pk_fma_f32 v[112:113], v[14:15], v[78:79], v[112:113] op_sel_hi:[1,0,1]
	v_pk_fma_f32 v[114:115], v[16:17], v[78:79], v[114:115] op_sel:[0,1,0]
	ds_read_b128 v[32:35], v225 offset:33808
	v_pk_add_f32 v[108:109], v[108:109], v[110:111]
	v_pk_add_f32 v[112:113], v[112:113], v[114:115]
	s_waitcnt lgkmcnt(11)
	v_pk_mul_f32 v[116:117], v[104:105], v[80:81] op_sel_hi:[1,0]
	v_pk_mul_f32 v[118:119], v[104:105], v[80:81] op_sel:[0,1]
	v_pk_mul_f32 v[120:121], v[104:105], v[82:83] op_sel_hi:[1,0]
	v_pk_mul_f32 v[122:123], v[104:105], v[82:83] op_sel:[0,1]
	ds_read_b64 v[60:61], v224 offset:41984
	ds_read_b128 v[36:39], v225 offset:25600
	v_add_f32_dpp v108, v108, v108 quad_perm:[1,0,3,2] row_mask:0xf bank_mask:0xf bound_ctrl:1
	v_add_f32_dpp v109, v109, v109 quad_perm:[1,0,3,2] row_mask:0xf bank_mask:0xf bound_ctrl:1
	v_add_f32_dpp v112, v112, v112 quad_perm:[1,0,3,2] row_mask:0xf bank_mask:0xf bound_ctrl:1
	v_add_f32_dpp v113, v113, v113 quad_perm:[1,0,3,2] row_mask:0xf bank_mask:0xf bound_ctrl:1
	s_waitcnt lgkmcnt(12)
	v_pk_mul_f32 v[124:125], v[104:105], v[84:85] op_sel_hi:[1,0]
	v_pk_mul_f32 v[126:127], v[104:105], v[84:85] op_sel:[0,1]
	v_pk_mul_f32 v[128:129], v[104:105], v[86:87] op_sel_hi:[1,0]
	v_pk_mul_f32 v[130:131], v[104:105], v[86:87] op_sel:[0,1]
	ds_read_b128 v[40:43], v225 offset:25616
	ds_read_b64 v[62:63], v134 offset:57376
	v_add_f32_dpp v108, v108, v108 quad_perm:[2,3,0,1] row_mask:0xf bank_mask:0xf bound_ctrl:1
	v_add_f32_dpp v109, v109, v109 quad_perm:[2,3,0,1] row_mask:0xf bank_mask:0xf bound_ctrl:1
	v_add_f32_dpp v112, v112, v112 quad_perm:[2,3,0,1] row_mask:0xf bank_mask:0xf bound_ctrl:1
	v_add_f32_dpp v113, v113, v113 quad_perm:[2,3,0,1] row_mask:0xf bank_mask:0xf bound_ctrl:1
	ds_read_b128 v[44:47], v225 offset:17408
	s_nop 0
	v_add_f32_dpp v108, v108, v108 row_half_mirror row_mask:0xf bank_mask:0xf bound_ctrl:1
	v_add_f32_dpp v109, v109, v109 row_half_mirror row_mask:0xf bank_mask:0xf bound_ctrl:1
	v_add_f32_dpp v112, v112, v112 row_half_mirror row_mask:0xf bank_mask:0xf bound_ctrl:1
	v_add_f32_dpp v113, v113, v113 row_half_mirror row_mask:0xf bank_mask:0xf bound_ctrl:1
	ds_read_b128 v[48:51], v225 offset:17424
	s_waitcnt lgkmcnt(13)
	s_nop 0
	v_pk_fma_f32 v[116:117], v[108:109], v[88:89], v[116:117] op_sel_hi:[1,0,1] neg_lo:[1,0,0] neg_hi:[1,0,0]
	v_pk_fma_f32 v[118:119], v[108:109], v[88:89], v[118:119] op_sel:[0,1,0] neg_lo:[1,0,0] neg_hi:[1,0,0]
	v_pk_fma_f32 v[120:121], v[108:109], v[90:91], v[120:121] op_sel_hi:[1,0,1] neg_lo:[1,0,0] neg_hi:[1,0,0]
	v_pk_fma_f32 v[122:123], v[108:109], v[90:91], v[122:123] op_sel:[0,1,0] neg_lo:[1,0,0] neg_hi:[1,0,0]
	v_pk_fma_f32 v[124:125], v[108:109], v[92:93], v[124:125] op_sel_hi:[1,0,1] neg_lo:[1,0,0] neg_hi:[1,0,0]
	v_pk_fma_f32 v[126:127], v[108:109], v[92:93], v[126:127] op_sel:[0,1,0] neg_lo:[1,0,0] neg_hi:[1,0,0]
	v_pk_fma_f32 v[128:129], v[108:109], v[94:95], v[128:129] op_sel_hi:[1,0,1] neg_lo:[1,0,0] neg_hi:[1,0,0]
	v_pk_fma_f32 v[130:131], v[108:109], v[94:95], v[130:131] op_sel:[0,1,0] neg_lo:[1,0,0] neg_hi:[1,0,0]
	ds_read_b128 v[52:55], v225 offset:9216
	v_pk_fma_f32 v[132:133], v[108:109], v[106:107], v[112:113] op_sel_hi:[1,0,1] neg_lo:[1,0,0] neg_hi:[1,0,0]
	ds_read_b128 v[56:59], v225 offset:9232
	s_waitcnt lgkmcnt(13)
	v_pk_fma_f32 v[2:3], v[2:3], v[96:97], v[116:117] op_sel_hi:[1,0,1]
	v_pk_fma_f32 v[4:5], v[4:5], v[96:97], v[118:119] op_sel:[0,1,0]
	v_pk_fma_f32 v[6:7], v[6:7], v[98:99], v[120:121] op_sel_hi:[1,0,1]
	v_pk_fma_f32 v[8:9], v[8:9], v[98:99], v[122:123] op_sel:[0,1,0]
	v_pk_fma_f32 v[132:133], v[104:105], v[106:107], v[132:133] op_sel:[0,1,0]
	v_pk_fma_f32 v[10:11], v[10:11], v[100:101], v[124:125] op_sel_hi:[1,0,1]
	v_pk_fma_f32 v[12:13], v[12:13], v[100:101], v[126:127] op_sel:[0,1,0]
	v_pk_fma_f32 v[14:15], v[14:15], v[102:103], v[128:129] op_sel_hi:[1,0,1]
	v_pk_fma_f32 v[16:17], v[16:17], v[102:103], v[130:131] op_sel:[0,1,0]
	ds_write_b64 v135, v[132:133] offset:49920
	s_waitcnt lgkmcnt(9)
	v_pk_mul_f32 v[108:109], v[2:3], v[20:21] op_sel_hi:[1,0]
	v_pk_mul_f32 v[110:111], v[4:5], v[20:21] op_sel:[0,1]
	v_pk_mul_f32 v[112:113], v[2:3], v[28:29] op_sel_hi:[1,0]
	v_pk_mul_f32 v[114:115], v[4:5], v[28:29] op_sel:[0,1]
	ds_read_b128 v[64:67], v225 offset:1280
	v_pk_fma_f32 v[108:109], v[6:7], v[22:23], v[108:109] op_sel_hi:[1,0,1]
	v_pk_fma_f32 v[110:111], v[8:9], v[22:23], v[110:111] op_sel:[0,1,0]
	v_pk_fma_f32 v[112:113], v[6:7], v[30:31], v[112:113] op_sel_hi:[1,0,1]
	v_pk_fma_f32 v[114:115], v[8:9], v[30:31], v[114:115] op_sel:[0,1,0]
	ds_read_b128 v[68:71], v225 offset:1296
	v_pk_fma_f32 v[108:109], v[10:11], v[24:25], v[108:109] op_sel_hi:[1,0,1]
	v_pk_fma_f32 v[110:111], v[12:13], v[24:25], v[110:111] op_sel:[0,1,0]
	v_pk_fma_f32 v[112:113], v[10:11], v[32:33], v[112:113] op_sel_hi:[1,0,1]
	v_pk_fma_f32 v[114:115], v[12:13], v[32:33], v[114:115] op_sel:[0,1,0]
	ds_read_b128 v[72:75], v225 offset:34048
	v_pk_fma_f32 v[108:109], v[14:15], v[26:27], v[108:109] op_sel_hi:[1,0,1]
	v_pk_fma_f32 v[110:111], v[16:17], v[26:27], v[110:111] op_sel:[0,1,0]
	v_pk_fma_f32 v[112:113], v[14:15], v[34:35], v[112:113] op_sel_hi:[1,0,1]
	v_pk_fma_f32 v[114:115], v[16:17], v[34:35], v[114:115] op_sel:[0,1,0]
	ds_read_b128 v[76:79], v225 offset:34064
	v_pk_add_f32 v[108:109], v[108:109], v[110:111]
	v_pk_add_f32 v[112:113], v[112:113], v[114:115]
	s_waitcnt lgkmcnt(11)
	v_pk_mul_f32 v[116:117], v[60:61], v[36:37] op_sel_hi:[1,0]
	v_pk_mul_f32 v[118:119], v[60:61], v[36:37] op_sel:[0,1]
	v_pk_mul_f32 v[120:121], v[60:61], v[38:39] op_sel_hi:[1,0]
	v_pk_mul_f32 v[122:123], v[60:61], v[38:39] op_sel:[0,1]
	ds_read_b64 v[104:105], v224 offset:42240
	ds_read_b128 v[80:83], v225 offset:25856
	v_add_f32_dpp v108, v108, v108 quad_perm:[1,0,3,2] row_mask:0xf bank_mask:0xf bound_ctrl:1
	v_add_f32_dpp v109, v109, v109 quad_perm:[1,0,3,2] row_mask:0xf bank_mask:0xf bound_ctrl:1
	v_add_f32_dpp v112, v112, v112 quad_perm:[1,0,3,2] row_mask:0xf bank_mask:0xf bound_ctrl:1
	v_add_f32_dpp v113, v113, v113 quad_perm:[1,0,3,2] row_mask:0xf bank_mask:0xf bound_ctrl:1
	s_waitcnt lgkmcnt(12)
	v_pk_mul_f32 v[124:125], v[60:61], v[40:41] op_sel_hi:[1,0]
	v_pk_mul_f32 v[126:127], v[60:61], v[40:41] op_sel:[0,1]
	v_pk_mul_f32 v[128:129], v[60:61], v[42:43] op_sel_hi:[1,0]
	v_pk_mul_f32 v[130:131], v[60:61], v[42:43] op_sel:[0,1]
	ds_read_b128 v[84:87], v225 offset:25872
	ds_read_b64 v[106:107], v134 offset:57384
	v_add_f32_dpp v108, v108, v108 quad_perm:[2,3,0,1] row_mask:0xf bank_mask:0xf bound_ctrl:1
	v_add_f32_dpp v109, v109, v109 quad_perm:[2,3,0,1] row_mask:0xf bank_mask:0xf bound_ctrl:1
	v_add_f32_dpp v112, v112, v112 quad_perm:[2,3,0,1] row_mask:0xf bank_mask:0xf bound_ctrl:1
	v_add_f32_dpp v113, v113, v113 quad_perm:[2,3,0,1] row_mask:0xf bank_mask:0xf bound_ctrl:1
	ds_read_b128 v[88:91], v225 offset:17664
	s_nop 0
	v_add_f32_dpp v108, v108, v108 row_half_mirror row_mask:0xf bank_mask:0xf bound_ctrl:1
	v_add_f32_dpp v109, v109, v109 row_half_mirror row_mask:0xf bank_mask:0xf bound_ctrl:1
	v_add_f32_dpp v112, v112, v112 row_half_mirror row_mask:0xf bank_mask:0xf bound_ctrl:1
	v_add_f32_dpp v113, v113, v113 row_half_mirror row_mask:0xf bank_mask:0xf bound_ctrl:1
	ds_read_b128 v[92:95], v225 offset:17680
	s_waitcnt lgkmcnt(13)
	s_nop 0
	v_pk_fma_f32 v[116:117], v[108:109], v[44:45], v[116:117] op_sel_hi:[1,0,1] neg_lo:[1,0,0] neg_hi:[1,0,0]
	v_pk_fma_f32 v[118:119], v[108:109], v[44:45], v[118:119] op_sel:[0,1,0] neg_lo:[1,0,0] neg_hi:[1,0,0]
	v_pk_fma_f32 v[120:121], v[108:109], v[46:47], v[120:121] op_sel_hi:[1,0,1] neg_lo:[1,0,0] neg_hi:[1,0,0]
	v_pk_fma_f32 v[122:123], v[108:109], v[46:47], v[122:123] op_sel:[0,1,0] neg_lo:[1,0,0] neg_hi:[1,0,0]
	v_pk_fma_f32 v[124:125], v[108:109], v[48:49], v[124:125] op_sel_hi:[1,0,1] neg_lo:[1,0,0] neg_hi:[1,0,0]
	v_pk_fma_f32 v[126:127], v[108:109], v[48:49], v[126:127] op_sel:[0,1,0] neg_lo:[1,0,0] neg_hi:[1,0,0]
	v_pk_fma_f32 v[128:129], v[108:109], v[50:51], v[128:129] op_sel_hi:[1,0,1] neg_lo:[1,0,0] neg_hi:[1,0,0]
	v_pk_fma_f32 v[130:131], v[108:109], v[50:51], v[130:131] op_sel:[0,1,0] neg_lo:[1,0,0] neg_hi:[1,0,0]
	ds_read_b128 v[96:99], v225 offset:9472
	v_pk_fma_f32 v[132:133], v[108:109], v[62:63], v[112:113] op_sel_hi:[1,0,1] neg_lo:[1,0,0] neg_hi:[1,0,0]
	ds_read_b128 v[100:103], v225 offset:9488
	s_waitcnt lgkmcnt(13)
	v_pk_fma_f32 v[2:3], v[2:3], v[52:53], v[116:117] op_sel_hi:[1,0,1]
	v_pk_fma_f32 v[4:5], v[4:5], v[52:53], v[118:119] op_sel:[0,1,0]
	v_pk_fma_f32 v[6:7], v[6:7], v[54:55], v[120:121] op_sel_hi:[1,0,1]
	v_pk_fma_f32 v[8:9], v[8:9], v[54:55], v[122:123] op_sel:[0,1,0]
	v_pk_fma_f32 v[132:133], v[60:61], v[62:63], v[132:133] op_sel:[0,1,0]
	v_pk_fma_f32 v[10:11], v[10:11], v[56:57], v[124:125] op_sel_hi:[1,0,1]
	v_pk_fma_f32 v[12:13], v[12:13], v[56:57], v[126:127] op_sel:[0,1,0]
	v_pk_fma_f32 v[14:15], v[14:15], v[58:59], v[128:129] op_sel_hi:[1,0,1]
	v_pk_fma_f32 v[16:17], v[16:17], v[58:59], v[130:131] op_sel:[0,1,0]
	ds_write_b64 v135, v[132:133] offset:50176
	s_waitcnt lgkmcnt(9)
	v_pk_mul_f32 v[108:109], v[2:3], v[64:65] op_sel_hi:[1,0]
	v_pk_mul_f32 v[110:111], v[4:5], v[64:65] op_sel:[0,1]
	v_pk_mul_f32 v[112:113], v[2:3], v[72:73] op_sel_hi:[1,0]
	v_pk_mul_f32 v[114:115], v[4:5], v[72:73] op_sel:[0,1]
	ds_read_b128 v[20:23], v225 offset:1536
	v_pk_fma_f32 v[108:109], v[6:7], v[66:67], v[108:109] op_sel_hi:[1,0,1]
	v_pk_fma_f32 v[110:111], v[8:9], v[66:67], v[110:111] op_sel:[0,1,0]
	v_pk_fma_f32 v[112:113], v[6:7], v[74:75], v[112:113] op_sel_hi:[1,0,1]
	v_pk_fma_f32 v[114:115], v[8:9], v[74:75], v[114:115] op_sel:[0,1,0]
	ds_read_b128 v[24:27], v225 offset:1552
	v_pk_fma_f32 v[108:109], v[10:11], v[68:69], v[108:109] op_sel_hi:[1,0,1]
	v_pk_fma_f32 v[110:111], v[12:13], v[68:69], v[110:111] op_sel:[0,1,0]
	v_pk_fma_f32 v[112:113], v[10:11], v[76:77], v[112:113] op_sel_hi:[1,0,1]
	v_pk_fma_f32 v[114:115], v[12:13], v[76:77], v[114:115] op_sel:[0,1,0]
	ds_read_b128 v[28:31], v225 offset:34304
	v_pk_fma_f32 v[108:109], v[14:15], v[70:71], v[108:109] op_sel_hi:[1,0,1]
	v_pk_fma_f32 v[110:111], v[16:17], v[70:71], v[110:111] op_sel:[0,1,0]
	v_pk_fma_f32 v[112:113], v[14:15], v[78:79], v[112:113] op_sel_hi:[1,0,1]
	v_pk_fma_f32 v[114:115], v[16:17], v[78:79], v[114:115] op_sel:[0,1,0]
	ds_read_b128 v[32:35], v225 offset:34320
	v_pk_add_f32 v[108:109], v[108:109], v[110:111]
	v_pk_add_f32 v[112:113], v[112:113], v[114:115]
	s_waitcnt lgkmcnt(11)
	v_pk_mul_f32 v[116:117], v[104:105], v[80:81] op_sel_hi:[1,0]
	v_pk_mul_f32 v[118:119], v[104:105], v[80:81] op_sel:[0,1]
	v_pk_mul_f32 v[120:121], v[104:105], v[82:83] op_sel_hi:[1,0]
	v_pk_mul_f32 v[122:123], v[104:105], v[82:83] op_sel:[0,1]
	ds_read_b64 v[60:61], v224 offset:42496
	ds_read_b128 v[36:39], v225 offset:26112
	v_add_f32_dpp v108, v108, v108 quad_perm:[1,0,3,2] row_mask:0xf bank_mask:0xf bound_ctrl:1
	v_add_f32_dpp v109, v109, v109 quad_perm:[1,0,3,2] row_mask:0xf bank_mask:0xf bound_ctrl:1
	v_add_f32_dpp v112, v112, v112 quad_perm:[1,0,3,2] row_mask:0xf bank_mask:0xf bound_ctrl:1
	v_add_f32_dpp v113, v113, v113 quad_perm:[1,0,3,2] row_mask:0xf bank_mask:0xf bound_ctrl:1
	s_waitcnt lgkmcnt(12)
	v_pk_mul_f32 v[124:125], v[104:105], v[84:85] op_sel_hi:[1,0]
	v_pk_mul_f32 v[126:127], v[104:105], v[84:85] op_sel:[0,1]
	v_pk_mul_f32 v[128:129], v[104:105], v[86:87] op_sel_hi:[1,0]
	v_pk_mul_f32 v[130:131], v[104:105], v[86:87] op_sel:[0,1]
	ds_read_b128 v[40:43], v225 offset:26128
	ds_read_b64 v[62:63], v134 offset:57392
	v_add_f32_dpp v108, v108, v108 quad_perm:[2,3,0,1] row_mask:0xf bank_mask:0xf bound_ctrl:1
	v_add_f32_dpp v109, v109, v109 quad_perm:[2,3,0,1] row_mask:0xf bank_mask:0xf bound_ctrl:1
	v_add_f32_dpp v112, v112, v112 quad_perm:[2,3,0,1] row_mask:0xf bank_mask:0xf bound_ctrl:1
	v_add_f32_dpp v113, v113, v113 quad_perm:[2,3,0,1] row_mask:0xf bank_mask:0xf bound_ctrl:1
	ds_read_b128 v[44:47], v225 offset:17920
	s_nop 0
	v_add_f32_dpp v108, v108, v108 row_half_mirror row_mask:0xf bank_mask:0xf bound_ctrl:1
	v_add_f32_dpp v109, v109, v109 row_half_mirror row_mask:0xf bank_mask:0xf bound_ctrl:1
	v_add_f32_dpp v112, v112, v112 row_half_mirror row_mask:0xf bank_mask:0xf bound_ctrl:1
	v_add_f32_dpp v113, v113, v113 row_half_mirror row_mask:0xf bank_mask:0xf bound_ctrl:1
	ds_read_b128 v[48:51], v225 offset:17936
	s_waitcnt lgkmcnt(13)
	s_nop 0
	v_pk_fma_f32 v[116:117], v[108:109], v[88:89], v[116:117] op_sel_hi:[1,0,1] neg_lo:[1,0,0] neg_hi:[1,0,0]
	v_pk_fma_f32 v[118:119], v[108:109], v[88:89], v[118:119] op_sel:[0,1,0] neg_lo:[1,0,0] neg_hi:[1,0,0]
	v_pk_fma_f32 v[120:121], v[108:109], v[90:91], v[120:121] op_sel_hi:[1,0,1] neg_lo:[1,0,0] neg_hi:[1,0,0]
	v_pk_fma_f32 v[122:123], v[108:109], v[90:91], v[122:123] op_sel:[0,1,0] neg_lo:[1,0,0] neg_hi:[1,0,0]
	v_pk_fma_f32 v[124:125], v[108:109], v[92:93], v[124:125] op_sel_hi:[1,0,1] neg_lo:[1,0,0] neg_hi:[1,0,0]
	v_pk_fma_f32 v[126:127], v[108:109], v[92:93], v[126:127] op_sel:[0,1,0] neg_lo:[1,0,0] neg_hi:[1,0,0]
	v_pk_fma_f32 v[128:129], v[108:109], v[94:95], v[128:129] op_sel_hi:[1,0,1] neg_lo:[1,0,0] neg_hi:[1,0,0]
	v_pk_fma_f32 v[130:131], v[108:109], v[94:95], v[130:131] op_sel:[0,1,0] neg_lo:[1,0,0] neg_hi:[1,0,0]
	ds_read_b128 v[52:55], v225 offset:9728
	v_pk_fma_f32 v[132:133], v[108:109], v[106:107], v[112:113] op_sel_hi:[1,0,1] neg_lo:[1,0,0] neg_hi:[1,0,0]
	ds_read_b128 v[56:59], v225 offset:9744
	s_waitcnt lgkmcnt(13)
	v_pk_fma_f32 v[2:3], v[2:3], v[96:97], v[116:117] op_sel_hi:[1,0,1]
	v_pk_fma_f32 v[4:5], v[4:5], v[96:97], v[118:119] op_sel:[0,1,0]
	v_pk_fma_f32 v[6:7], v[6:7], v[98:99], v[120:121] op_sel_hi:[1,0,1]
	v_pk_fma_f32 v[8:9], v[8:9], v[98:99], v[122:123] op_sel:[0,1,0]
	v_pk_fma_f32 v[132:133], v[104:105], v[106:107], v[132:133] op_sel:[0,1,0]
	v_pk_fma_f32 v[10:11], v[10:11], v[100:101], v[124:125] op_sel_hi:[1,0,1]
	v_pk_fma_f32 v[12:13], v[12:13], v[100:101], v[126:127] op_sel:[0,1,0]
	v_pk_fma_f32 v[14:15], v[14:15], v[102:103], v[128:129] op_sel_hi:[1,0,1]
	v_pk_fma_f32 v[16:17], v[16:17], v[102:103], v[130:131] op_sel:[0,1,0]
	ds_write_b64 v135, v[132:133] offset:50432
	s_waitcnt lgkmcnt(9)
	v_pk_mul_f32 v[108:109], v[2:3], v[20:21] op_sel_hi:[1,0]
	v_pk_mul_f32 v[110:111], v[4:5], v[20:21] op_sel:[0,1]
	v_pk_mul_f32 v[112:113], v[2:3], v[28:29] op_sel_hi:[1,0]
	v_pk_mul_f32 v[114:115], v[4:5], v[28:29] op_sel:[0,1]
	ds_read_b128 v[64:67], v225 offset:1792
	v_pk_fma_f32 v[108:109], v[6:7], v[22:23], v[108:109] op_sel_hi:[1,0,1]
	v_pk_fma_f32 v[110:111], v[8:9], v[22:23], v[110:111] op_sel:[0,1,0]
	v_pk_fma_f32 v[112:113], v[6:7], v[30:31], v[112:113] op_sel_hi:[1,0,1]
	v_pk_fma_f32 v[114:115], v[8:9], v[30:31], v[114:115] op_sel:[0,1,0]
	ds_read_b128 v[68:71], v225 offset:1808
	v_pk_fma_f32 v[108:109], v[10:11], v[24:25], v[108:109] op_sel_hi:[1,0,1]
	v_pk_fma_f32 v[110:111], v[12:13], v[24:25], v[110:111] op_sel:[0,1,0]
	v_pk_fma_f32 v[112:113], v[10:11], v[32:33], v[112:113] op_sel_hi:[1,0,1]
	v_pk_fma_f32 v[114:115], v[12:13], v[32:33], v[114:115] op_sel:[0,1,0]
	ds_read_b128 v[72:75], v225 offset:34560
	v_pk_fma_f32 v[108:109], v[14:15], v[26:27], v[108:109] op_sel_hi:[1,0,1]
	v_pk_fma_f32 v[110:111], v[16:17], v[26:27], v[110:111] op_sel:[0,1,0]
	v_pk_fma_f32 v[112:113], v[14:15], v[34:35], v[112:113] op_sel_hi:[1,0,1]
	v_pk_fma_f32 v[114:115], v[16:17], v[34:35], v[114:115] op_sel:[0,1,0]
	ds_read_b128 v[76:79], v225 offset:34576
	v_pk_add_f32 v[108:109], v[108:109], v[110:111]
	v_pk_add_f32 v[112:113], v[112:113], v[114:115]
	s_waitcnt lgkmcnt(11)
	v_pk_mul_f32 v[116:117], v[60:61], v[36:37] op_sel_hi:[1,0]
	v_pk_mul_f32 v[118:119], v[60:61], v[36:37] op_sel:[0,1]
	v_pk_mul_f32 v[120:121], v[60:61], v[38:39] op_sel_hi:[1,0]
	v_pk_mul_f32 v[122:123], v[60:61], v[38:39] op_sel:[0,1]
	ds_read_b64 v[104:105], v224 offset:42752
	ds_read_b128 v[80:83], v225 offset:26368
	v_add_f32_dpp v108, v108, v108 quad_perm:[1,0,3,2] row_mask:0xf bank_mask:0xf bound_ctrl:1
	v_add_f32_dpp v109, v109, v109 quad_perm:[1,0,3,2] row_mask:0xf bank_mask:0xf bound_ctrl:1
	v_add_f32_dpp v112, v112, v112 quad_perm:[1,0,3,2] row_mask:0xf bank_mask:0xf bound_ctrl:1
	v_add_f32_dpp v113, v113, v113 quad_perm:[1,0,3,2] row_mask:0xf bank_mask:0xf bound_ctrl:1
	s_waitcnt lgkmcnt(12)
	v_pk_mul_f32 v[124:125], v[60:61], v[40:41] op_sel_hi:[1,0]
	v_pk_mul_f32 v[126:127], v[60:61], v[40:41] op_sel:[0,1]
	v_pk_mul_f32 v[128:129], v[60:61], v[42:43] op_sel_hi:[1,0]
	v_pk_mul_f32 v[130:131], v[60:61], v[42:43] op_sel:[0,1]
	ds_read_b128 v[84:87], v225 offset:26384
	ds_read_b64 v[106:107], v134 offset:57400
	v_add_f32_dpp v108, v108, v108 quad_perm:[2,3,0,1] row_mask:0xf bank_mask:0xf bound_ctrl:1
	v_add_f32_dpp v109, v109, v109 quad_perm:[2,3,0,1] row_mask:0xf bank_mask:0xf bound_ctrl:1
	v_add_f32_dpp v112, v112, v112 quad_perm:[2,3,0,1] row_mask:0xf bank_mask:0xf bound_ctrl:1
	v_add_f32_dpp v113, v113, v113 quad_perm:[2,3,0,1] row_mask:0xf bank_mask:0xf bound_ctrl:1
	ds_read_b128 v[88:91], v225 offset:18176
	s_nop 0
	v_add_f32_dpp v108, v108, v108 row_half_mirror row_mask:0xf bank_mask:0xf bound_ctrl:1
	v_add_f32_dpp v109, v109, v109 row_half_mirror row_mask:0xf bank_mask:0xf bound_ctrl:1
	v_add_f32_dpp v112, v112, v112 row_half_mirror row_mask:0xf bank_mask:0xf bound_ctrl:1
	v_add_f32_dpp v113, v113, v113 row_half_mirror row_mask:0xf bank_mask:0xf bound_ctrl:1
	ds_read_b128 v[92:95], v225 offset:18192
	s_waitcnt lgkmcnt(13)
	s_nop 0
	v_pk_fma_f32 v[116:117], v[108:109], v[44:45], v[116:117] op_sel_hi:[1,0,1] neg_lo:[1,0,0] neg_hi:[1,0,0]
	v_pk_fma_f32 v[118:119], v[108:109], v[44:45], v[118:119] op_sel:[0,1,0] neg_lo:[1,0,0] neg_hi:[1,0,0]
	v_pk_fma_f32 v[120:121], v[108:109], v[46:47], v[120:121] op_sel_hi:[1,0,1] neg_lo:[1,0,0] neg_hi:[1,0,0]
	v_pk_fma_f32 v[122:123], v[108:109], v[46:47], v[122:123] op_sel:[0,1,0] neg_lo:[1,0,0] neg_hi:[1,0,0]
	v_pk_fma_f32 v[124:125], v[108:109], v[48:49], v[124:125] op_sel_hi:[1,0,1] neg_lo:[1,0,0] neg_hi:[1,0,0]
	v_pk_fma_f32 v[126:127], v[108:109], v[48:49], v[126:127] op_sel:[0,1,0] neg_lo:[1,0,0] neg_hi:[1,0,0]
	v_pk_fma_f32 v[128:129], v[108:109], v[50:51], v[128:129] op_sel_hi:[1,0,1] neg_lo:[1,0,0] neg_hi:[1,0,0]
	v_pk_fma_f32 v[130:131], v[108:109], v[50:51], v[130:131] op_sel:[0,1,0] neg_lo:[1,0,0] neg_hi:[1,0,0]
	ds_read_b128 v[96:99], v225 offset:9984
	v_pk_fma_f32 v[132:133], v[108:109], v[62:63], v[112:113] op_sel_hi:[1,0,1] neg_lo:[1,0,0] neg_hi:[1,0,0]
	ds_read_b128 v[100:103], v225 offset:10000
	s_waitcnt lgkmcnt(13)
	v_pk_fma_f32 v[2:3], v[2:3], v[52:53], v[116:117] op_sel_hi:[1,0,1]
	v_pk_fma_f32 v[4:5], v[4:5], v[52:53], v[118:119] op_sel:[0,1,0]
	v_pk_fma_f32 v[6:7], v[6:7], v[54:55], v[120:121] op_sel_hi:[1,0,1]
	v_pk_fma_f32 v[8:9], v[8:9], v[54:55], v[122:123] op_sel:[0,1,0]
	v_pk_fma_f32 v[132:133], v[60:61], v[62:63], v[132:133] op_sel:[0,1,0]
	v_pk_fma_f32 v[10:11], v[10:11], v[56:57], v[124:125] op_sel_hi:[1,0,1]
	v_pk_fma_f32 v[12:13], v[12:13], v[56:57], v[126:127] op_sel:[0,1,0]
	v_pk_fma_f32 v[14:15], v[14:15], v[58:59], v[128:129] op_sel_hi:[1,0,1]
	v_pk_fma_f32 v[16:17], v[16:17], v[58:59], v[130:131] op_sel:[0,1,0]
	ds_write_b64 v135, v[132:133] offset:50688
	s_waitcnt lgkmcnt(9)
	v_pk_mul_f32 v[108:109], v[2:3], v[64:65] op_sel_hi:[1,0]
	v_pk_mul_f32 v[110:111], v[4:5], v[64:65] op_sel:[0,1]
	v_pk_mul_f32 v[112:113], v[2:3], v[72:73] op_sel_hi:[1,0]
	v_pk_mul_f32 v[114:115], v[4:5], v[72:73] op_sel:[0,1]
	ds_read_b128 v[20:23], v225 offset:2048
	v_pk_fma_f32 v[108:109], v[6:7], v[66:67], v[108:109] op_sel_hi:[1,0,1]
	v_pk_fma_f32 v[110:111], v[8:9], v[66:67], v[110:111] op_sel:[0,1,0]
	v_pk_fma_f32 v[112:113], v[6:7], v[74:75], v[112:113] op_sel_hi:[1,0,1]
	v_pk_fma_f32 v[114:115], v[8:9], v[74:75], v[114:115] op_sel:[0,1,0]
	ds_read_b128 v[24:27], v225 offset:2064
	v_pk_fma_f32 v[108:109], v[10:11], v[68:69], v[108:109] op_sel_hi:[1,0,1]
	v_pk_fma_f32 v[110:111], v[12:13], v[68:69], v[110:111] op_sel:[0,1,0]
	v_pk_fma_f32 v[112:113], v[10:11], v[76:77], v[112:113] op_sel_hi:[1,0,1]
	v_pk_fma_f32 v[114:115], v[12:13], v[76:77], v[114:115] op_sel:[0,1,0]
	ds_read_b128 v[28:31], v225 offset:34816
	v_pk_fma_f32 v[108:109], v[14:15], v[70:71], v[108:109] op_sel_hi:[1,0,1]
	v_pk_fma_f32 v[110:111], v[16:17], v[70:71], v[110:111] op_sel:[0,1,0]
	v_pk_fma_f32 v[112:113], v[14:15], v[78:79], v[112:113] op_sel_hi:[1,0,1]
	v_pk_fma_f32 v[114:115], v[16:17], v[78:79], v[114:115] op_sel:[0,1,0]
	ds_read_b128 v[32:35], v225 offset:34832
	v_pk_add_f32 v[108:109], v[108:109], v[110:111]
	v_pk_add_f32 v[112:113], v[112:113], v[114:115]
	s_waitcnt lgkmcnt(11)
	v_pk_mul_f32 v[116:117], v[104:105], v[80:81] op_sel_hi:[1,0]
	v_pk_mul_f32 v[118:119], v[104:105], v[80:81] op_sel:[0,1]
	v_pk_mul_f32 v[120:121], v[104:105], v[82:83] op_sel_hi:[1,0]
	v_pk_mul_f32 v[122:123], v[104:105], v[82:83] op_sel:[0,1]
	ds_read_b64 v[60:61], v224 offset:43008
	ds_read_b128 v[36:39], v225 offset:26624
	v_add_f32_dpp v108, v108, v108 quad_perm:[1,0,3,2] row_mask:0xf bank_mask:0xf bound_ctrl:1
	v_add_f32_dpp v109, v109, v109 quad_perm:[1,0,3,2] row_mask:0xf bank_mask:0xf bound_ctrl:1
	v_add_f32_dpp v112, v112, v112 quad_perm:[1,0,3,2] row_mask:0xf bank_mask:0xf bound_ctrl:1
	v_add_f32_dpp v113, v113, v113 quad_perm:[1,0,3,2] row_mask:0xf bank_mask:0xf bound_ctrl:1
	s_waitcnt lgkmcnt(12)
	v_pk_mul_f32 v[124:125], v[104:105], v[84:85] op_sel_hi:[1,0]
	v_pk_mul_f32 v[126:127], v[104:105], v[84:85] op_sel:[0,1]
	v_pk_mul_f32 v[128:129], v[104:105], v[86:87] op_sel_hi:[1,0]
	v_pk_mul_f32 v[130:131], v[104:105], v[86:87] op_sel:[0,1]
	ds_read_b128 v[40:43], v225 offset:26640
	ds_read_b64 v[62:63], v134 offset:57408
	v_add_f32_dpp v108, v108, v108 quad_perm:[2,3,0,1] row_mask:0xf bank_mask:0xf bound_ctrl:1
	v_add_f32_dpp v109, v109, v109 quad_perm:[2,3,0,1] row_mask:0xf bank_mask:0xf bound_ctrl:1
	v_add_f32_dpp v112, v112, v112 quad_perm:[2,3,0,1] row_mask:0xf bank_mask:0xf bound_ctrl:1
	v_add_f32_dpp v113, v113, v113 quad_perm:[2,3,0,1] row_mask:0xf bank_mask:0xf bound_ctrl:1
	ds_read_b128 v[44:47], v225 offset:18432
	s_nop 0
	v_add_f32_dpp v108, v108, v108 row_half_mirror row_mask:0xf bank_mask:0xf bound_ctrl:1
	v_add_f32_dpp v109, v109, v109 row_half_mirror row_mask:0xf bank_mask:0xf bound_ctrl:1
	v_add_f32_dpp v112, v112, v112 row_half_mirror row_mask:0xf bank_mask:0xf bound_ctrl:1
	v_add_f32_dpp v113, v113, v113 row_half_mirror row_mask:0xf bank_mask:0xf bound_ctrl:1
	ds_read_b128 v[48:51], v225 offset:18448
	s_waitcnt lgkmcnt(13)
	s_nop 0
	v_pk_fma_f32 v[116:117], v[108:109], v[88:89], v[116:117] op_sel_hi:[1,0,1] neg_lo:[1,0,0] neg_hi:[1,0,0]
	v_pk_fma_f32 v[118:119], v[108:109], v[88:89], v[118:119] op_sel:[0,1,0] neg_lo:[1,0,0] neg_hi:[1,0,0]
	v_pk_fma_f32 v[120:121], v[108:109], v[90:91], v[120:121] op_sel_hi:[1,0,1] neg_lo:[1,0,0] neg_hi:[1,0,0]
	v_pk_fma_f32 v[122:123], v[108:109], v[90:91], v[122:123] op_sel:[0,1,0] neg_lo:[1,0,0] neg_hi:[1,0,0]
	v_pk_fma_f32 v[124:125], v[108:109], v[92:93], v[124:125] op_sel_hi:[1,0,1] neg_lo:[1,0,0] neg_hi:[1,0,0]
	v_pk_fma_f32 v[126:127], v[108:109], v[92:93], v[126:127] op_sel:[0,1,0] neg_lo:[1,0,0] neg_hi:[1,0,0]
	v_pk_fma_f32 v[128:129], v[108:109], v[94:95], v[128:129] op_sel_hi:[1,0,1] neg_lo:[1,0,0] neg_hi:[1,0,0]
	v_pk_fma_f32 v[130:131], v[108:109], v[94:95], v[130:131] op_sel:[0,1,0] neg_lo:[1,0,0] neg_hi:[1,0,0]
	ds_read_b128 v[52:55], v225 offset:10240
	v_pk_fma_f32 v[132:133], v[108:109], v[106:107], v[112:113] op_sel_hi:[1,0,1] neg_lo:[1,0,0] neg_hi:[1,0,0]
	ds_read_b128 v[56:59], v225 offset:10256
	s_waitcnt lgkmcnt(13)
	v_pk_fma_f32 v[2:3], v[2:3], v[96:97], v[116:117] op_sel_hi:[1,0,1]
	v_pk_fma_f32 v[4:5], v[4:5], v[96:97], v[118:119] op_sel:[0,1,0]
	v_pk_fma_f32 v[6:7], v[6:7], v[98:99], v[120:121] op_sel_hi:[1,0,1]
	v_pk_fma_f32 v[8:9], v[8:9], v[98:99], v[122:123] op_sel:[0,1,0]
	v_pk_fma_f32 v[132:133], v[104:105], v[106:107], v[132:133] op_sel:[0,1,0]
	v_pk_fma_f32 v[10:11], v[10:11], v[100:101], v[124:125] op_sel_hi:[1,0,1]
	v_pk_fma_f32 v[12:13], v[12:13], v[100:101], v[126:127] op_sel:[0,1,0]
	v_pk_fma_f32 v[14:15], v[14:15], v[102:103], v[128:129] op_sel_hi:[1,0,1]
	v_pk_fma_f32 v[16:17], v[16:17], v[102:103], v[130:131] op_sel:[0,1,0]
	ds_write_b64 v135, v[132:133] offset:50944
	s_waitcnt lgkmcnt(9)
	v_pk_mul_f32 v[108:109], v[2:3], v[20:21] op_sel_hi:[1,0]
	v_pk_mul_f32 v[110:111], v[4:5], v[20:21] op_sel:[0,1]
	v_pk_mul_f32 v[112:113], v[2:3], v[28:29] op_sel_hi:[1,0]
	v_pk_mul_f32 v[114:115], v[4:5], v[28:29] op_sel:[0,1]
	ds_read_b128 v[64:67], v225 offset:2304
	v_pk_fma_f32 v[108:109], v[6:7], v[22:23], v[108:109] op_sel_hi:[1,0,1]
	v_pk_fma_f32 v[110:111], v[8:9], v[22:23], v[110:111] op_sel:[0,1,0]
	v_pk_fma_f32 v[112:113], v[6:7], v[30:31], v[112:113] op_sel_hi:[1,0,1]
	v_pk_fma_f32 v[114:115], v[8:9], v[30:31], v[114:115] op_sel:[0,1,0]
	ds_read_b128 v[68:71], v225 offset:2320
	v_pk_fma_f32 v[108:109], v[10:11], v[24:25], v[108:109] op_sel_hi:[1,0,1]
	v_pk_fma_f32 v[110:111], v[12:13], v[24:25], v[110:111] op_sel:[0,1,0]
	v_pk_fma_f32 v[112:113], v[10:11], v[32:33], v[112:113] op_sel_hi:[1,0,1]
	v_pk_fma_f32 v[114:115], v[12:13], v[32:33], v[114:115] op_sel:[0,1,0]
	ds_read_b128 v[72:75], v225 offset:35072
	v_pk_fma_f32 v[108:109], v[14:15], v[26:27], v[108:109] op_sel_hi:[1,0,1]
	v_pk_fma_f32 v[110:111], v[16:17], v[26:27], v[110:111] op_sel:[0,1,0]
	v_pk_fma_f32 v[112:113], v[14:15], v[34:35], v[112:113] op_sel_hi:[1,0,1]
	v_pk_fma_f32 v[114:115], v[16:17], v[34:35], v[114:115] op_sel:[0,1,0]
	ds_read_b128 v[76:79], v225 offset:35088
	v_pk_add_f32 v[108:109], v[108:109], v[110:111]
	v_pk_add_f32 v[112:113], v[112:113], v[114:115]
	s_waitcnt lgkmcnt(11)
	v_pk_mul_f32 v[116:117], v[60:61], v[36:37] op_sel_hi:[1,0]
	v_pk_mul_f32 v[118:119], v[60:61], v[36:37] op_sel:[0,1]
	v_pk_mul_f32 v[120:121], v[60:61], v[38:39] op_sel_hi:[1,0]
	v_pk_mul_f32 v[122:123], v[60:61], v[38:39] op_sel:[0,1]
	ds_read_b64 v[104:105], v224 offset:43264
	ds_read_b128 v[80:83], v225 offset:26880
	v_add_f32_dpp v108, v108, v108 quad_perm:[1,0,3,2] row_mask:0xf bank_mask:0xf bound_ctrl:1
	v_add_f32_dpp v109, v109, v109 quad_perm:[1,0,3,2] row_mask:0xf bank_mask:0xf bound_ctrl:1
	v_add_f32_dpp v112, v112, v112 quad_perm:[1,0,3,2] row_mask:0xf bank_mask:0xf bound_ctrl:1
	v_add_f32_dpp v113, v113, v113 quad_perm:[1,0,3,2] row_mask:0xf bank_mask:0xf bound_ctrl:1
	s_waitcnt lgkmcnt(12)
	v_pk_mul_f32 v[124:125], v[60:61], v[40:41] op_sel_hi:[1,0]
	v_pk_mul_f32 v[126:127], v[60:61], v[40:41] op_sel:[0,1]
	v_pk_mul_f32 v[128:129], v[60:61], v[42:43] op_sel_hi:[1,0]
	v_pk_mul_f32 v[130:131], v[60:61], v[42:43] op_sel:[0,1]
	ds_read_b128 v[84:87], v225 offset:26896
	ds_read_b64 v[106:107], v134 offset:57416
	v_add_f32_dpp v108, v108, v108 quad_perm:[2,3,0,1] row_mask:0xf bank_mask:0xf bound_ctrl:1
	v_add_f32_dpp v109, v109, v109 quad_perm:[2,3,0,1] row_mask:0xf bank_mask:0xf bound_ctrl:1
	v_add_f32_dpp v112, v112, v112 quad_perm:[2,3,0,1] row_mask:0xf bank_mask:0xf bound_ctrl:1
	v_add_f32_dpp v113, v113, v113 quad_perm:[2,3,0,1] row_mask:0xf bank_mask:0xf bound_ctrl:1
	ds_read_b128 v[88:91], v225 offset:18688
	s_nop 0
	v_add_f32_dpp v108, v108, v108 row_half_mirror row_mask:0xf bank_mask:0xf bound_ctrl:1
	v_add_f32_dpp v109, v109, v109 row_half_mirror row_mask:0xf bank_mask:0xf bound_ctrl:1
	v_add_f32_dpp v112, v112, v112 row_half_mirror row_mask:0xf bank_mask:0xf bound_ctrl:1
	v_add_f32_dpp v113, v113, v113 row_half_mirror row_mask:0xf bank_mask:0xf bound_ctrl:1
	ds_read_b128 v[92:95], v225 offset:18704
	s_waitcnt lgkmcnt(13)
	s_nop 0
	v_pk_fma_f32 v[116:117], v[108:109], v[44:45], v[116:117] op_sel_hi:[1,0,1] neg_lo:[1,0,0] neg_hi:[1,0,0]
	v_pk_fma_f32 v[118:119], v[108:109], v[44:45], v[118:119] op_sel:[0,1,0] neg_lo:[1,0,0] neg_hi:[1,0,0]
	v_pk_fma_f32 v[120:121], v[108:109], v[46:47], v[120:121] op_sel_hi:[1,0,1] neg_lo:[1,0,0] neg_hi:[1,0,0]
	v_pk_fma_f32 v[122:123], v[108:109], v[46:47], v[122:123] op_sel:[0,1,0] neg_lo:[1,0,0] neg_hi:[1,0,0]
	v_pk_fma_f32 v[124:125], v[108:109], v[48:49], v[124:125] op_sel_hi:[1,0,1] neg_lo:[1,0,0] neg_hi:[1,0,0]
	v_pk_fma_f32 v[126:127], v[108:109], v[48:49], v[126:127] op_sel:[0,1,0] neg_lo:[1,0,0] neg_hi:[1,0,0]
	v_pk_fma_f32 v[128:129], v[108:109], v[50:51], v[128:129] op_sel_hi:[1,0,1] neg_lo:[1,0,0] neg_hi:[1,0,0]
	v_pk_fma_f32 v[130:131], v[108:109], v[50:51], v[130:131] op_sel:[0,1,0] neg_lo:[1,0,0] neg_hi:[1,0,0]
	ds_read_b128 v[96:99], v225 offset:10496
	v_pk_fma_f32 v[132:133], v[108:109], v[62:63], v[112:113] op_sel_hi:[1,0,1] neg_lo:[1,0,0] neg_hi:[1,0,0]
	ds_read_b128 v[100:103], v225 offset:10512
	s_waitcnt lgkmcnt(13)
	v_pk_fma_f32 v[2:3], v[2:3], v[52:53], v[116:117] op_sel_hi:[1,0,1]
	v_pk_fma_f32 v[4:5], v[4:5], v[52:53], v[118:119] op_sel:[0,1,0]
	v_pk_fma_f32 v[6:7], v[6:7], v[54:55], v[120:121] op_sel_hi:[1,0,1]
	v_pk_fma_f32 v[8:9], v[8:9], v[54:55], v[122:123] op_sel:[0,1,0]
	v_pk_fma_f32 v[132:133], v[60:61], v[62:63], v[132:133] op_sel:[0,1,0]
	v_pk_fma_f32 v[10:11], v[10:11], v[56:57], v[124:125] op_sel_hi:[1,0,1]
	v_pk_fma_f32 v[12:13], v[12:13], v[56:57], v[126:127] op_sel:[0,1,0]
	v_pk_fma_f32 v[14:15], v[14:15], v[58:59], v[128:129] op_sel_hi:[1,0,1]
	v_pk_fma_f32 v[16:17], v[16:17], v[58:59], v[130:131] op_sel:[0,1,0]
	ds_write_b64 v135, v[132:133] offset:51200
	s_waitcnt lgkmcnt(9)
	v_pk_mul_f32 v[108:109], v[2:3], v[64:65] op_sel_hi:[1,0]
	v_pk_mul_f32 v[110:111], v[4:5], v[64:65] op_sel:[0,1]
	v_pk_mul_f32 v[112:113], v[2:3], v[72:73] op_sel_hi:[1,0]
	v_pk_mul_f32 v[114:115], v[4:5], v[72:73] op_sel:[0,1]
	ds_read_b128 v[20:23], v225 offset:2560
	v_pk_fma_f32 v[108:109], v[6:7], v[66:67], v[108:109] op_sel_hi:[1,0,1]
	v_pk_fma_f32 v[110:111], v[8:9], v[66:67], v[110:111] op_sel:[0,1,0]
	v_pk_fma_f32 v[112:113], v[6:7], v[74:75], v[112:113] op_sel_hi:[1,0,1]
	v_pk_fma_f32 v[114:115], v[8:9], v[74:75], v[114:115] op_sel:[0,1,0]
	ds_read_b128 v[24:27], v225 offset:2576
	v_pk_fma_f32 v[108:109], v[10:11], v[68:69], v[108:109] op_sel_hi:[1,0,1]
	v_pk_fma_f32 v[110:111], v[12:13], v[68:69], v[110:111] op_sel:[0,1,0]
	v_pk_fma_f32 v[112:113], v[10:11], v[76:77], v[112:113] op_sel_hi:[1,0,1]
	v_pk_fma_f32 v[114:115], v[12:13], v[76:77], v[114:115] op_sel:[0,1,0]
	ds_read_b128 v[28:31], v225 offset:35328
	v_pk_fma_f32 v[108:109], v[14:15], v[70:71], v[108:109] op_sel_hi:[1,0,1]
	v_pk_fma_f32 v[110:111], v[16:17], v[70:71], v[110:111] op_sel:[0,1,0]
	v_pk_fma_f32 v[112:113], v[14:15], v[78:79], v[112:113] op_sel_hi:[1,0,1]
	v_pk_fma_f32 v[114:115], v[16:17], v[78:79], v[114:115] op_sel:[0,1,0]
	ds_read_b128 v[32:35], v225 offset:35344
	v_pk_add_f32 v[108:109], v[108:109], v[110:111]
	v_pk_add_f32 v[112:113], v[112:113], v[114:115]
	s_waitcnt lgkmcnt(11)
	v_pk_mul_f32 v[116:117], v[104:105], v[80:81] op_sel_hi:[1,0]
	v_pk_mul_f32 v[118:119], v[104:105], v[80:81] op_sel:[0,1]
	v_pk_mul_f32 v[120:121], v[104:105], v[82:83] op_sel_hi:[1,0]
	v_pk_mul_f32 v[122:123], v[104:105], v[82:83] op_sel:[0,1]
	ds_read_b64 v[60:61], v224 offset:43520
	ds_read_b128 v[36:39], v225 offset:27136
	v_add_f32_dpp v108, v108, v108 quad_perm:[1,0,3,2] row_mask:0xf bank_mask:0xf bound_ctrl:1
	v_add_f32_dpp v109, v109, v109 quad_perm:[1,0,3,2] row_mask:0xf bank_mask:0xf bound_ctrl:1
	v_add_f32_dpp v112, v112, v112 quad_perm:[1,0,3,2] row_mask:0xf bank_mask:0xf bound_ctrl:1
	v_add_f32_dpp v113, v113, v113 quad_perm:[1,0,3,2] row_mask:0xf bank_mask:0xf bound_ctrl:1
	s_waitcnt lgkmcnt(12)
	v_pk_mul_f32 v[124:125], v[104:105], v[84:85] op_sel_hi:[1,0]
	v_pk_mul_f32 v[126:127], v[104:105], v[84:85] op_sel:[0,1]
	v_pk_mul_f32 v[128:129], v[104:105], v[86:87] op_sel_hi:[1,0]
	v_pk_mul_f32 v[130:131], v[104:105], v[86:87] op_sel:[0,1]
	ds_read_b128 v[40:43], v225 offset:27152
	ds_read_b64 v[62:63], v134 offset:57424
	v_add_f32_dpp v108, v108, v108 quad_perm:[2,3,0,1] row_mask:0xf bank_mask:0xf bound_ctrl:1
	v_add_f32_dpp v109, v109, v109 quad_perm:[2,3,0,1] row_mask:0xf bank_mask:0xf bound_ctrl:1
	v_add_f32_dpp v112, v112, v112 quad_perm:[2,3,0,1] row_mask:0xf bank_mask:0xf bound_ctrl:1
	v_add_f32_dpp v113, v113, v113 quad_perm:[2,3,0,1] row_mask:0xf bank_mask:0xf bound_ctrl:1
	ds_read_b128 v[44:47], v225 offset:18944
	s_nop 0
	v_add_f32_dpp v108, v108, v108 row_half_mirror row_mask:0xf bank_mask:0xf bound_ctrl:1
	v_add_f32_dpp v109, v109, v109 row_half_mirror row_mask:0xf bank_mask:0xf bound_ctrl:1
	v_add_f32_dpp v112, v112, v112 row_half_mirror row_mask:0xf bank_mask:0xf bound_ctrl:1
	v_add_f32_dpp v113, v113, v113 row_half_mirror row_mask:0xf bank_mask:0xf bound_ctrl:1
	ds_read_b128 v[48:51], v225 offset:18960
	s_waitcnt lgkmcnt(13)
	s_nop 0
	v_pk_fma_f32 v[116:117], v[108:109], v[88:89], v[116:117] op_sel_hi:[1,0,1] neg_lo:[1,0,0] neg_hi:[1,0,0]
	v_pk_fma_f32 v[118:119], v[108:109], v[88:89], v[118:119] op_sel:[0,1,0] neg_lo:[1,0,0] neg_hi:[1,0,0]
	v_pk_fma_f32 v[120:121], v[108:109], v[90:91], v[120:121] op_sel_hi:[1,0,1] neg_lo:[1,0,0] neg_hi:[1,0,0]
	v_pk_fma_f32 v[122:123], v[108:109], v[90:91], v[122:123] op_sel:[0,1,0] neg_lo:[1,0,0] neg_hi:[1,0,0]
	v_pk_fma_f32 v[124:125], v[108:109], v[92:93], v[124:125] op_sel_hi:[1,0,1] neg_lo:[1,0,0] neg_hi:[1,0,0]
	v_pk_fma_f32 v[126:127], v[108:109], v[92:93], v[126:127] op_sel:[0,1,0] neg_lo:[1,0,0] neg_hi:[1,0,0]
	v_pk_fma_f32 v[128:129], v[108:109], v[94:95], v[128:129] op_sel_hi:[1,0,1] neg_lo:[1,0,0] neg_hi:[1,0,0]
	v_pk_fma_f32 v[130:131], v[108:109], v[94:95], v[130:131] op_sel:[0,1,0] neg_lo:[1,0,0] neg_hi:[1,0,0]
	ds_read_b128 v[52:55], v225 offset:10752
	v_pk_fma_f32 v[132:133], v[108:109], v[106:107], v[112:113] op_sel_hi:[1,0,1] neg_lo:[1,0,0] neg_hi:[1,0,0]
	ds_read_b128 v[56:59], v225 offset:10768
	s_waitcnt lgkmcnt(13)
	v_pk_fma_f32 v[2:3], v[2:3], v[96:97], v[116:117] op_sel_hi:[1,0,1]
	v_pk_fma_f32 v[4:5], v[4:5], v[96:97], v[118:119] op_sel:[0,1,0]
	v_pk_fma_f32 v[6:7], v[6:7], v[98:99], v[120:121] op_sel_hi:[1,0,1]
	v_pk_fma_f32 v[8:9], v[8:9], v[98:99], v[122:123] op_sel:[0,1,0]
	v_pk_fma_f32 v[132:133], v[104:105], v[106:107], v[132:133] op_sel:[0,1,0]
	v_pk_fma_f32 v[10:11], v[10:11], v[100:101], v[124:125] op_sel_hi:[1,0,1]
	v_pk_fma_f32 v[12:13], v[12:13], v[100:101], v[126:127] op_sel:[0,1,0]
	v_pk_fma_f32 v[14:15], v[14:15], v[102:103], v[128:129] op_sel_hi:[1,0,1]
	v_pk_fma_f32 v[16:17], v[16:17], v[102:103], v[130:131] op_sel:[0,1,0]
	ds_write_b64 v135, v[132:133] offset:51456
	s_waitcnt lgkmcnt(9)
	v_pk_mul_f32 v[108:109], v[2:3], v[20:21] op_sel_hi:[1,0]
	v_pk_mul_f32 v[110:111], v[4:5], v[20:21] op_sel:[0,1]
	v_pk_mul_f32 v[112:113], v[2:3], v[28:29] op_sel_hi:[1,0]
	v_pk_mul_f32 v[114:115], v[4:5], v[28:29] op_sel:[0,1]
	ds_read_b128 v[64:67], v225 offset:2816
	v_pk_fma_f32 v[108:109], v[6:7], v[22:23], v[108:109] op_sel_hi:[1,0,1]
	v_pk_fma_f32 v[110:111], v[8:9], v[22:23], v[110:111] op_sel:[0,1,0]
	v_pk_fma_f32 v[112:113], v[6:7], v[30:31], v[112:113] op_sel_hi:[1,0,1]
	v_pk_fma_f32 v[114:115], v[8:9], v[30:31], v[114:115] op_sel:[0,1,0]
	ds_read_b128 v[68:71], v225 offset:2832
	v_pk_fma_f32 v[108:109], v[10:11], v[24:25], v[108:109] op_sel_hi:[1,0,1]
	v_pk_fma_f32 v[110:111], v[12:13], v[24:25], v[110:111] op_sel:[0,1,0]
	v_pk_fma_f32 v[112:113], v[10:11], v[32:33], v[112:113] op_sel_hi:[1,0,1]
	v_pk_fma_f32 v[114:115], v[12:13], v[32:33], v[114:115] op_sel:[0,1,0]
	ds_read_b128 v[72:75], v225 offset:35584
	v_pk_fma_f32 v[108:109], v[14:15], v[26:27], v[108:109] op_sel_hi:[1,0,1]
	v_pk_fma_f32 v[110:111], v[16:17], v[26:27], v[110:111] op_sel:[0,1,0]
	v_pk_fma_f32 v[112:113], v[14:15], v[34:35], v[112:113] op_sel_hi:[1,0,1]
	v_pk_fma_f32 v[114:115], v[16:17], v[34:35], v[114:115] op_sel:[0,1,0]
	ds_read_b128 v[76:79], v225 offset:35600
	v_pk_add_f32 v[108:109], v[108:109], v[110:111]
	v_pk_add_f32 v[112:113], v[112:113], v[114:115]
	s_waitcnt lgkmcnt(11)
	v_pk_mul_f32 v[116:117], v[60:61], v[36:37] op_sel_hi:[1,0]
	v_pk_mul_f32 v[118:119], v[60:61], v[36:37] op_sel:[0,1]
	v_pk_mul_f32 v[120:121], v[60:61], v[38:39] op_sel_hi:[1,0]
	v_pk_mul_f32 v[122:123], v[60:61], v[38:39] op_sel:[0,1]
	ds_read_b64 v[104:105], v224 offset:43776
	ds_read_b128 v[80:83], v225 offset:27392
	v_add_f32_dpp v108, v108, v108 quad_perm:[1,0,3,2] row_mask:0xf bank_mask:0xf bound_ctrl:1
	v_add_f32_dpp v109, v109, v109 quad_perm:[1,0,3,2] row_mask:0xf bank_mask:0xf bound_ctrl:1
	v_add_f32_dpp v112, v112, v112 quad_perm:[1,0,3,2] row_mask:0xf bank_mask:0xf bound_ctrl:1
	v_add_f32_dpp v113, v113, v113 quad_perm:[1,0,3,2] row_mask:0xf bank_mask:0xf bound_ctrl:1
	s_waitcnt lgkmcnt(12)
	v_pk_mul_f32 v[124:125], v[60:61], v[40:41] op_sel_hi:[1,0]
	v_pk_mul_f32 v[126:127], v[60:61], v[40:41] op_sel:[0,1]
	v_pk_mul_f32 v[128:129], v[60:61], v[42:43] op_sel_hi:[1,0]
	v_pk_mul_f32 v[130:131], v[60:61], v[42:43] op_sel:[0,1]
	ds_read_b128 v[84:87], v225 offset:27408
	ds_read_b64 v[106:107], v134 offset:57432
	v_add_f32_dpp v108, v108, v108 quad_perm:[2,3,0,1] row_mask:0xf bank_mask:0xf bound_ctrl:1
	v_add_f32_dpp v109, v109, v109 quad_perm:[2,3,0,1] row_mask:0xf bank_mask:0xf bound_ctrl:1
	v_add_f32_dpp v112, v112, v112 quad_perm:[2,3,0,1] row_mask:0xf bank_mask:0xf bound_ctrl:1
	v_add_f32_dpp v113, v113, v113 quad_perm:[2,3,0,1] row_mask:0xf bank_mask:0xf bound_ctrl:1
	ds_read_b128 v[88:91], v225 offset:19200
	s_nop 0
	v_add_f32_dpp v108, v108, v108 row_half_mirror row_mask:0xf bank_mask:0xf bound_ctrl:1
	v_add_f32_dpp v109, v109, v109 row_half_mirror row_mask:0xf bank_mask:0xf bound_ctrl:1
	v_add_f32_dpp v112, v112, v112 row_half_mirror row_mask:0xf bank_mask:0xf bound_ctrl:1
	v_add_f32_dpp v113, v113, v113 row_half_mirror row_mask:0xf bank_mask:0xf bound_ctrl:1
	ds_read_b128 v[92:95], v225 offset:19216
	s_waitcnt lgkmcnt(13)
	s_nop 0
	v_pk_fma_f32 v[116:117], v[108:109], v[44:45], v[116:117] op_sel_hi:[1,0,1] neg_lo:[1,0,0] neg_hi:[1,0,0]
	v_pk_fma_f32 v[118:119], v[108:109], v[44:45], v[118:119] op_sel:[0,1,0] neg_lo:[1,0,0] neg_hi:[1,0,0]
	v_pk_fma_f32 v[120:121], v[108:109], v[46:47], v[120:121] op_sel_hi:[1,0,1] neg_lo:[1,0,0] neg_hi:[1,0,0]
	v_pk_fma_f32 v[122:123], v[108:109], v[46:47], v[122:123] op_sel:[0,1,0] neg_lo:[1,0,0] neg_hi:[1,0,0]
	v_pk_fma_f32 v[124:125], v[108:109], v[48:49], v[124:125] op_sel_hi:[1,0,1] neg_lo:[1,0,0] neg_hi:[1,0,0]
	v_pk_fma_f32 v[126:127], v[108:109], v[48:49], v[126:127] op_sel:[0,1,0] neg_lo:[1,0,0] neg_hi:[1,0,0]
	v_pk_fma_f32 v[128:129], v[108:109], v[50:51], v[128:129] op_sel_hi:[1,0,1] neg_lo:[1,0,0] neg_hi:[1,0,0]
	v_pk_fma_f32 v[130:131], v[108:109], v[50:51], v[130:131] op_sel:[0,1,0] neg_lo:[1,0,0] neg_hi:[1,0,0]
	ds_read_b128 v[96:99], v225 offset:11008
	v_pk_fma_f32 v[132:133], v[108:109], v[62:63], v[112:113] op_sel_hi:[1,0,1] neg_lo:[1,0,0] neg_hi:[1,0,0]
	ds_read_b128 v[100:103], v225 offset:11024
	s_waitcnt lgkmcnt(13)
	v_pk_fma_f32 v[2:3], v[2:3], v[52:53], v[116:117] op_sel_hi:[1,0,1]
	v_pk_fma_f32 v[4:5], v[4:5], v[52:53], v[118:119] op_sel:[0,1,0]
	v_pk_fma_f32 v[6:7], v[6:7], v[54:55], v[120:121] op_sel_hi:[1,0,1]
	v_pk_fma_f32 v[8:9], v[8:9], v[54:55], v[122:123] op_sel:[0,1,0]
	v_pk_fma_f32 v[132:133], v[60:61], v[62:63], v[132:133] op_sel:[0,1,0]
	v_pk_fma_f32 v[10:11], v[10:11], v[56:57], v[124:125] op_sel_hi:[1,0,1]
	v_pk_fma_f32 v[12:13], v[12:13], v[56:57], v[126:127] op_sel:[0,1,0]
	v_pk_fma_f32 v[14:15], v[14:15], v[58:59], v[128:129] op_sel_hi:[1,0,1]
	v_pk_fma_f32 v[16:17], v[16:17], v[58:59], v[130:131] op_sel:[0,1,0]
	ds_write_b64 v135, v[132:133] offset:51712
	s_waitcnt lgkmcnt(9)
	v_pk_mul_f32 v[108:109], v[2:3], v[64:65] op_sel_hi:[1,0]
	v_pk_mul_f32 v[110:111], v[4:5], v[64:65] op_sel:[0,1]
	v_pk_mul_f32 v[112:113], v[2:3], v[72:73] op_sel_hi:[1,0]
	v_pk_mul_f32 v[114:115], v[4:5], v[72:73] op_sel:[0,1]
	ds_read_b128 v[20:23], v225 offset:3072
	v_pk_fma_f32 v[108:109], v[6:7], v[66:67], v[108:109] op_sel_hi:[1,0,1]
	v_pk_fma_f32 v[110:111], v[8:9], v[66:67], v[110:111] op_sel:[0,1,0]
	v_pk_fma_f32 v[112:113], v[6:7], v[74:75], v[112:113] op_sel_hi:[1,0,1]
	v_pk_fma_f32 v[114:115], v[8:9], v[74:75], v[114:115] op_sel:[0,1,0]
	ds_read_b128 v[24:27], v225 offset:3088
	v_pk_fma_f32 v[108:109], v[10:11], v[68:69], v[108:109] op_sel_hi:[1,0,1]
	v_pk_fma_f32 v[110:111], v[12:13], v[68:69], v[110:111] op_sel:[0,1,0]
	v_pk_fma_f32 v[112:113], v[10:11], v[76:77], v[112:113] op_sel_hi:[1,0,1]
	v_pk_fma_f32 v[114:115], v[12:13], v[76:77], v[114:115] op_sel:[0,1,0]
	ds_read_b128 v[28:31], v225 offset:35840
	v_pk_fma_f32 v[108:109], v[14:15], v[70:71], v[108:109] op_sel_hi:[1,0,1]
	v_pk_fma_f32 v[110:111], v[16:17], v[70:71], v[110:111] op_sel:[0,1,0]
	v_pk_fma_f32 v[112:113], v[14:15], v[78:79], v[112:113] op_sel_hi:[1,0,1]
	v_pk_fma_f32 v[114:115], v[16:17], v[78:79], v[114:115] op_sel:[0,1,0]
	ds_read_b128 v[32:35], v225 offset:35856
	v_pk_add_f32 v[108:109], v[108:109], v[110:111]
	v_pk_add_f32 v[112:113], v[112:113], v[114:115]
	s_waitcnt lgkmcnt(11)
	v_pk_mul_f32 v[116:117], v[104:105], v[80:81] op_sel_hi:[1,0]
	v_pk_mul_f32 v[118:119], v[104:105], v[80:81] op_sel:[0,1]
	v_pk_mul_f32 v[120:121], v[104:105], v[82:83] op_sel_hi:[1,0]
	v_pk_mul_f32 v[122:123], v[104:105], v[82:83] op_sel:[0,1]
	ds_read_b64 v[60:61], v224 offset:44032
	ds_read_b128 v[36:39], v225 offset:27648
	v_add_f32_dpp v108, v108, v108 quad_perm:[1,0,3,2] row_mask:0xf bank_mask:0xf bound_ctrl:1
	v_add_f32_dpp v109, v109, v109 quad_perm:[1,0,3,2] row_mask:0xf bank_mask:0xf bound_ctrl:1
	v_add_f32_dpp v112, v112, v112 quad_perm:[1,0,3,2] row_mask:0xf bank_mask:0xf bound_ctrl:1
	v_add_f32_dpp v113, v113, v113 quad_perm:[1,0,3,2] row_mask:0xf bank_mask:0xf bound_ctrl:1
	s_waitcnt lgkmcnt(12)
	v_pk_mul_f32 v[124:125], v[104:105], v[84:85] op_sel_hi:[1,0]
	v_pk_mul_f32 v[126:127], v[104:105], v[84:85] op_sel:[0,1]
	v_pk_mul_f32 v[128:129], v[104:105], v[86:87] op_sel_hi:[1,0]
	v_pk_mul_f32 v[130:131], v[104:105], v[86:87] op_sel:[0,1]
	ds_read_b128 v[40:43], v225 offset:27664
	ds_read_b64 v[62:63], v134 offset:57440
	v_add_f32_dpp v108, v108, v108 quad_perm:[2,3,0,1] row_mask:0xf bank_mask:0xf bound_ctrl:1
	v_add_f32_dpp v109, v109, v109 quad_perm:[2,3,0,1] row_mask:0xf bank_mask:0xf bound_ctrl:1
	v_add_f32_dpp v112, v112, v112 quad_perm:[2,3,0,1] row_mask:0xf bank_mask:0xf bound_ctrl:1
	v_add_f32_dpp v113, v113, v113 quad_perm:[2,3,0,1] row_mask:0xf bank_mask:0xf bound_ctrl:1
	ds_read_b128 v[44:47], v225 offset:19456
	s_nop 0
	v_add_f32_dpp v108, v108, v108 row_half_mirror row_mask:0xf bank_mask:0xf bound_ctrl:1
	v_add_f32_dpp v109, v109, v109 row_half_mirror row_mask:0xf bank_mask:0xf bound_ctrl:1
	v_add_f32_dpp v112, v112, v112 row_half_mirror row_mask:0xf bank_mask:0xf bound_ctrl:1
	v_add_f32_dpp v113, v113, v113 row_half_mirror row_mask:0xf bank_mask:0xf bound_ctrl:1
	ds_read_b128 v[48:51], v225 offset:19472
	s_waitcnt lgkmcnt(13)
	s_nop 0
	v_pk_fma_f32 v[116:117], v[108:109], v[88:89], v[116:117] op_sel_hi:[1,0,1] neg_lo:[1,0,0] neg_hi:[1,0,0]
	v_pk_fma_f32 v[118:119], v[108:109], v[88:89], v[118:119] op_sel:[0,1,0] neg_lo:[1,0,0] neg_hi:[1,0,0]
	v_pk_fma_f32 v[120:121], v[108:109], v[90:91], v[120:121] op_sel_hi:[1,0,1] neg_lo:[1,0,0] neg_hi:[1,0,0]
	v_pk_fma_f32 v[122:123], v[108:109], v[90:91], v[122:123] op_sel:[0,1,0] neg_lo:[1,0,0] neg_hi:[1,0,0]
	v_pk_fma_f32 v[124:125], v[108:109], v[92:93], v[124:125] op_sel_hi:[1,0,1] neg_lo:[1,0,0] neg_hi:[1,0,0]
	v_pk_fma_f32 v[126:127], v[108:109], v[92:93], v[126:127] op_sel:[0,1,0] neg_lo:[1,0,0] neg_hi:[1,0,0]
	v_pk_fma_f32 v[128:129], v[108:109], v[94:95], v[128:129] op_sel_hi:[1,0,1] neg_lo:[1,0,0] neg_hi:[1,0,0]
	v_pk_fma_f32 v[130:131], v[108:109], v[94:95], v[130:131] op_sel:[0,1,0] neg_lo:[1,0,0] neg_hi:[1,0,0]
	ds_read_b128 v[52:55], v225 offset:11264
	v_pk_fma_f32 v[132:133], v[108:109], v[106:107], v[112:113] op_sel_hi:[1,0,1] neg_lo:[1,0,0] neg_hi:[1,0,0]
	ds_read_b128 v[56:59], v225 offset:11280
	s_waitcnt lgkmcnt(13)
	v_pk_fma_f32 v[2:3], v[2:3], v[96:97], v[116:117] op_sel_hi:[1,0,1]
	v_pk_fma_f32 v[4:5], v[4:5], v[96:97], v[118:119] op_sel:[0,1,0]
	v_pk_fma_f32 v[6:7], v[6:7], v[98:99], v[120:121] op_sel_hi:[1,0,1]
	v_pk_fma_f32 v[8:9], v[8:9], v[98:99], v[122:123] op_sel:[0,1,0]
	v_pk_fma_f32 v[132:133], v[104:105], v[106:107], v[132:133] op_sel:[0,1,0]
	v_pk_fma_f32 v[10:11], v[10:11], v[100:101], v[124:125] op_sel_hi:[1,0,1]
	v_pk_fma_f32 v[12:13], v[12:13], v[100:101], v[126:127] op_sel:[0,1,0]
	v_pk_fma_f32 v[14:15], v[14:15], v[102:103], v[128:129] op_sel_hi:[1,0,1]
	v_pk_fma_f32 v[16:17], v[16:17], v[102:103], v[130:131] op_sel:[0,1,0]
	ds_write_b64 v135, v[132:133] offset:51968
	s_waitcnt lgkmcnt(9)
	v_pk_mul_f32 v[108:109], v[2:3], v[20:21] op_sel_hi:[1,0]
	v_pk_mul_f32 v[110:111], v[4:5], v[20:21] op_sel:[0,1]
	v_pk_mul_f32 v[112:113], v[2:3], v[28:29] op_sel_hi:[1,0]
	v_pk_mul_f32 v[114:115], v[4:5], v[28:29] op_sel:[0,1]
	ds_read_b128 v[64:67], v225 offset:3328
	v_pk_fma_f32 v[108:109], v[6:7], v[22:23], v[108:109] op_sel_hi:[1,0,1]
	v_pk_fma_f32 v[110:111], v[8:9], v[22:23], v[110:111] op_sel:[0,1,0]
	v_pk_fma_f32 v[112:113], v[6:7], v[30:31], v[112:113] op_sel_hi:[1,0,1]
	v_pk_fma_f32 v[114:115], v[8:9], v[30:31], v[114:115] op_sel:[0,1,0]
	ds_read_b128 v[68:71], v225 offset:3344
	v_pk_fma_f32 v[108:109], v[10:11], v[24:25], v[108:109] op_sel_hi:[1,0,1]
	v_pk_fma_f32 v[110:111], v[12:13], v[24:25], v[110:111] op_sel:[0,1,0]
	v_pk_fma_f32 v[112:113], v[10:11], v[32:33], v[112:113] op_sel_hi:[1,0,1]
	v_pk_fma_f32 v[114:115], v[12:13], v[32:33], v[114:115] op_sel:[0,1,0]
	ds_read_b128 v[72:75], v225 offset:36096
	v_pk_fma_f32 v[108:109], v[14:15], v[26:27], v[108:109] op_sel_hi:[1,0,1]
	v_pk_fma_f32 v[110:111], v[16:17], v[26:27], v[110:111] op_sel:[0,1,0]
	v_pk_fma_f32 v[112:113], v[14:15], v[34:35], v[112:113] op_sel_hi:[1,0,1]
	v_pk_fma_f32 v[114:115], v[16:17], v[34:35], v[114:115] op_sel:[0,1,0]
	ds_read_b128 v[76:79], v225 offset:36112
	v_pk_add_f32 v[108:109], v[108:109], v[110:111]
	v_pk_add_f32 v[112:113], v[112:113], v[114:115]
	s_waitcnt lgkmcnt(11)
	v_pk_mul_f32 v[116:117], v[60:61], v[36:37] op_sel_hi:[1,0]
	v_pk_mul_f32 v[118:119], v[60:61], v[36:37] op_sel:[0,1]
	v_pk_mul_f32 v[120:121], v[60:61], v[38:39] op_sel_hi:[1,0]
	v_pk_mul_f32 v[122:123], v[60:61], v[38:39] op_sel:[0,1]
	ds_read_b64 v[104:105], v224 offset:44288
	ds_read_b128 v[80:83], v225 offset:27904
	v_add_f32_dpp v108, v108, v108 quad_perm:[1,0,3,2] row_mask:0xf bank_mask:0xf bound_ctrl:1
	v_add_f32_dpp v109, v109, v109 quad_perm:[1,0,3,2] row_mask:0xf bank_mask:0xf bound_ctrl:1
	v_add_f32_dpp v112, v112, v112 quad_perm:[1,0,3,2] row_mask:0xf bank_mask:0xf bound_ctrl:1
	v_add_f32_dpp v113, v113, v113 quad_perm:[1,0,3,2] row_mask:0xf bank_mask:0xf bound_ctrl:1
	s_waitcnt lgkmcnt(12)
	v_pk_mul_f32 v[124:125], v[60:61], v[40:41] op_sel_hi:[1,0]
	v_pk_mul_f32 v[126:127], v[60:61], v[40:41] op_sel:[0,1]
	v_pk_mul_f32 v[128:129], v[60:61], v[42:43] op_sel_hi:[1,0]
	v_pk_mul_f32 v[130:131], v[60:61], v[42:43] op_sel:[0,1]
	ds_read_b128 v[84:87], v225 offset:27920
	ds_read_b64 v[106:107], v134 offset:57448
	v_add_f32_dpp v108, v108, v108 quad_perm:[2,3,0,1] row_mask:0xf bank_mask:0xf bound_ctrl:1
	v_add_f32_dpp v109, v109, v109 quad_perm:[2,3,0,1] row_mask:0xf bank_mask:0xf bound_ctrl:1
	v_add_f32_dpp v112, v112, v112 quad_perm:[2,3,0,1] row_mask:0xf bank_mask:0xf bound_ctrl:1
	v_add_f32_dpp v113, v113, v113 quad_perm:[2,3,0,1] row_mask:0xf bank_mask:0xf bound_ctrl:1
	ds_read_b128 v[88:91], v225 offset:19712
	s_nop 0
	v_add_f32_dpp v108, v108, v108 row_half_mirror row_mask:0xf bank_mask:0xf bound_ctrl:1
	v_add_f32_dpp v109, v109, v109 row_half_mirror row_mask:0xf bank_mask:0xf bound_ctrl:1
	v_add_f32_dpp v112, v112, v112 row_half_mirror row_mask:0xf bank_mask:0xf bound_ctrl:1
	v_add_f32_dpp v113, v113, v113 row_half_mirror row_mask:0xf bank_mask:0xf bound_ctrl:1
	ds_read_b128 v[92:95], v225 offset:19728
	s_waitcnt lgkmcnt(13)
	s_nop 0
	v_pk_fma_f32 v[116:117], v[108:109], v[44:45], v[116:117] op_sel_hi:[1,0,1] neg_lo:[1,0,0] neg_hi:[1,0,0]
	v_pk_fma_f32 v[118:119], v[108:109], v[44:45], v[118:119] op_sel:[0,1,0] neg_lo:[1,0,0] neg_hi:[1,0,0]
	v_pk_fma_f32 v[120:121], v[108:109], v[46:47], v[120:121] op_sel_hi:[1,0,1] neg_lo:[1,0,0] neg_hi:[1,0,0]
	v_pk_fma_f32 v[122:123], v[108:109], v[46:47], v[122:123] op_sel:[0,1,0] neg_lo:[1,0,0] neg_hi:[1,0,0]
	v_pk_fma_f32 v[124:125], v[108:109], v[48:49], v[124:125] op_sel_hi:[1,0,1] neg_lo:[1,0,0] neg_hi:[1,0,0]
	v_pk_fma_f32 v[126:127], v[108:109], v[48:49], v[126:127] op_sel:[0,1,0] neg_lo:[1,0,0] neg_hi:[1,0,0]
	v_pk_fma_f32 v[128:129], v[108:109], v[50:51], v[128:129] op_sel_hi:[1,0,1] neg_lo:[1,0,0] neg_hi:[1,0,0]
	v_pk_fma_f32 v[130:131], v[108:109], v[50:51], v[130:131] op_sel:[0,1,0] neg_lo:[1,0,0] neg_hi:[1,0,0]
	ds_read_b128 v[96:99], v225 offset:11520
	v_pk_fma_f32 v[132:133], v[108:109], v[62:63], v[112:113] op_sel_hi:[1,0,1] neg_lo:[1,0,0] neg_hi:[1,0,0]
	ds_read_b128 v[100:103], v225 offset:11536
	s_waitcnt lgkmcnt(13)
	v_pk_fma_f32 v[2:3], v[2:3], v[52:53], v[116:117] op_sel_hi:[1,0,1]
	v_pk_fma_f32 v[4:5], v[4:5], v[52:53], v[118:119] op_sel:[0,1,0]
	v_pk_fma_f32 v[6:7], v[6:7], v[54:55], v[120:121] op_sel_hi:[1,0,1]
	v_pk_fma_f32 v[8:9], v[8:9], v[54:55], v[122:123] op_sel:[0,1,0]
	v_pk_fma_f32 v[132:133], v[60:61], v[62:63], v[132:133] op_sel:[0,1,0]
	v_pk_fma_f32 v[10:11], v[10:11], v[56:57], v[124:125] op_sel_hi:[1,0,1]
	v_pk_fma_f32 v[12:13], v[12:13], v[56:57], v[126:127] op_sel:[0,1,0]
	v_pk_fma_f32 v[14:15], v[14:15], v[58:59], v[128:129] op_sel_hi:[1,0,1]
	v_pk_fma_f32 v[16:17], v[16:17], v[58:59], v[130:131] op_sel:[0,1,0]
	ds_write_b64 v135, v[132:133] offset:52224
	s_waitcnt lgkmcnt(9)
	v_pk_mul_f32 v[108:109], v[2:3], v[64:65] op_sel_hi:[1,0]
	v_pk_mul_f32 v[110:111], v[4:5], v[64:65] op_sel:[0,1]
	v_pk_mul_f32 v[112:113], v[2:3], v[72:73] op_sel_hi:[1,0]
	v_pk_mul_f32 v[114:115], v[4:5], v[72:73] op_sel:[0,1]
	ds_read_b128 v[20:23], v225 offset:3584
	v_pk_fma_f32 v[108:109], v[6:7], v[66:67], v[108:109] op_sel_hi:[1,0,1]
	v_pk_fma_f32 v[110:111], v[8:9], v[66:67], v[110:111] op_sel:[0,1,0]
	v_pk_fma_f32 v[112:113], v[6:7], v[74:75], v[112:113] op_sel_hi:[1,0,1]
	v_pk_fma_f32 v[114:115], v[8:9], v[74:75], v[114:115] op_sel:[0,1,0]
	ds_read_b128 v[24:27], v225 offset:3600
	v_pk_fma_f32 v[108:109], v[10:11], v[68:69], v[108:109] op_sel_hi:[1,0,1]
	v_pk_fma_f32 v[110:111], v[12:13], v[68:69], v[110:111] op_sel:[0,1,0]
	v_pk_fma_f32 v[112:113], v[10:11], v[76:77], v[112:113] op_sel_hi:[1,0,1]
	v_pk_fma_f32 v[114:115], v[12:13], v[76:77], v[114:115] op_sel:[0,1,0]
	ds_read_b128 v[28:31], v225 offset:36352
	v_pk_fma_f32 v[108:109], v[14:15], v[70:71], v[108:109] op_sel_hi:[1,0,1]
	v_pk_fma_f32 v[110:111], v[16:17], v[70:71], v[110:111] op_sel:[0,1,0]
	v_pk_fma_f32 v[112:113], v[14:15], v[78:79], v[112:113] op_sel_hi:[1,0,1]
	v_pk_fma_f32 v[114:115], v[16:17], v[78:79], v[114:115] op_sel:[0,1,0]
	ds_read_b128 v[32:35], v225 offset:36368
	v_pk_add_f32 v[108:109], v[108:109], v[110:111]
	v_pk_add_f32 v[112:113], v[112:113], v[114:115]
	s_waitcnt lgkmcnt(11)
	v_pk_mul_f32 v[116:117], v[104:105], v[80:81] op_sel_hi:[1,0]
	v_pk_mul_f32 v[118:119], v[104:105], v[80:81] op_sel:[0,1]
	v_pk_mul_f32 v[120:121], v[104:105], v[82:83] op_sel_hi:[1,0]
	v_pk_mul_f32 v[122:123], v[104:105], v[82:83] op_sel:[0,1]
	ds_read_b64 v[60:61], v224 offset:44544
	ds_read_b128 v[36:39], v225 offset:28160
	v_add_f32_dpp v108, v108, v108 quad_perm:[1,0,3,2] row_mask:0xf bank_mask:0xf bound_ctrl:1
	v_add_f32_dpp v109, v109, v109 quad_perm:[1,0,3,2] row_mask:0xf bank_mask:0xf bound_ctrl:1
	v_add_f32_dpp v112, v112, v112 quad_perm:[1,0,3,2] row_mask:0xf bank_mask:0xf bound_ctrl:1
	v_add_f32_dpp v113, v113, v113 quad_perm:[1,0,3,2] row_mask:0xf bank_mask:0xf bound_ctrl:1
	s_waitcnt lgkmcnt(12)
	v_pk_mul_f32 v[124:125], v[104:105], v[84:85] op_sel_hi:[1,0]
	v_pk_mul_f32 v[126:127], v[104:105], v[84:85] op_sel:[0,1]
	v_pk_mul_f32 v[128:129], v[104:105], v[86:87] op_sel_hi:[1,0]
	v_pk_mul_f32 v[130:131], v[104:105], v[86:87] op_sel:[0,1]
	ds_read_b128 v[40:43], v225 offset:28176
	ds_read_b64 v[62:63], v134 offset:57456
	v_add_f32_dpp v108, v108, v108 quad_perm:[2,3,0,1] row_mask:0xf bank_mask:0xf bound_ctrl:1
	v_add_f32_dpp v109, v109, v109 quad_perm:[2,3,0,1] row_mask:0xf bank_mask:0xf bound_ctrl:1
	v_add_f32_dpp v112, v112, v112 quad_perm:[2,3,0,1] row_mask:0xf bank_mask:0xf bound_ctrl:1
	v_add_f32_dpp v113, v113, v113 quad_perm:[2,3,0,1] row_mask:0xf bank_mask:0xf bound_ctrl:1
	ds_read_b128 v[44:47], v225 offset:19968
	s_nop 0
	v_add_f32_dpp v108, v108, v108 row_half_mirror row_mask:0xf bank_mask:0xf bound_ctrl:1
	v_add_f32_dpp v109, v109, v109 row_half_mirror row_mask:0xf bank_mask:0xf bound_ctrl:1
	v_add_f32_dpp v112, v112, v112 row_half_mirror row_mask:0xf bank_mask:0xf bound_ctrl:1
	v_add_f32_dpp v113, v113, v113 row_half_mirror row_mask:0xf bank_mask:0xf bound_ctrl:1
	ds_read_b128 v[48:51], v225 offset:19984
	s_waitcnt lgkmcnt(13)
	s_nop 0
	v_pk_fma_f32 v[116:117], v[108:109], v[88:89], v[116:117] op_sel_hi:[1,0,1] neg_lo:[1,0,0] neg_hi:[1,0,0]
	v_pk_fma_f32 v[118:119], v[108:109], v[88:89], v[118:119] op_sel:[0,1,0] neg_lo:[1,0,0] neg_hi:[1,0,0]
	v_pk_fma_f32 v[120:121], v[108:109], v[90:91], v[120:121] op_sel_hi:[1,0,1] neg_lo:[1,0,0] neg_hi:[1,0,0]
	v_pk_fma_f32 v[122:123], v[108:109], v[90:91], v[122:123] op_sel:[0,1,0] neg_lo:[1,0,0] neg_hi:[1,0,0]
	v_pk_fma_f32 v[124:125], v[108:109], v[92:93], v[124:125] op_sel_hi:[1,0,1] neg_lo:[1,0,0] neg_hi:[1,0,0]
	v_pk_fma_f32 v[126:127], v[108:109], v[92:93], v[126:127] op_sel:[0,1,0] neg_lo:[1,0,0] neg_hi:[1,0,0]
	v_pk_fma_f32 v[128:129], v[108:109], v[94:95], v[128:129] op_sel_hi:[1,0,1] neg_lo:[1,0,0] neg_hi:[1,0,0]
	v_pk_fma_f32 v[130:131], v[108:109], v[94:95], v[130:131] op_sel:[0,1,0] neg_lo:[1,0,0] neg_hi:[1,0,0]
	ds_read_b128 v[52:55], v225 offset:11776
	v_pk_fma_f32 v[132:133], v[108:109], v[106:107], v[112:113] op_sel_hi:[1,0,1] neg_lo:[1,0,0] neg_hi:[1,0,0]
	ds_read_b128 v[56:59], v225 offset:11792
	s_waitcnt lgkmcnt(13)
	v_pk_fma_f32 v[2:3], v[2:3], v[96:97], v[116:117] op_sel_hi:[1,0,1]
	v_pk_fma_f32 v[4:5], v[4:5], v[96:97], v[118:119] op_sel:[0,1,0]
	v_pk_fma_f32 v[6:7], v[6:7], v[98:99], v[120:121] op_sel_hi:[1,0,1]
	v_pk_fma_f32 v[8:9], v[8:9], v[98:99], v[122:123] op_sel:[0,1,0]
	v_pk_fma_f32 v[132:133], v[104:105], v[106:107], v[132:133] op_sel:[0,1,0]
	v_pk_fma_f32 v[10:11], v[10:11], v[100:101], v[124:125] op_sel_hi:[1,0,1]
	v_pk_fma_f32 v[12:13], v[12:13], v[100:101], v[126:127] op_sel:[0,1,0]
	v_pk_fma_f32 v[14:15], v[14:15], v[102:103], v[128:129] op_sel_hi:[1,0,1]
	v_pk_fma_f32 v[16:17], v[16:17], v[102:103], v[130:131] op_sel:[0,1,0]
	ds_write_b64 v135, v[132:133] offset:52480
	s_waitcnt lgkmcnt(9)
	v_pk_mul_f32 v[108:109], v[2:3], v[20:21] op_sel_hi:[1,0]
	v_pk_mul_f32 v[110:111], v[4:5], v[20:21] op_sel:[0,1]
	v_pk_mul_f32 v[112:113], v[2:3], v[28:29] op_sel_hi:[1,0]
	v_pk_mul_f32 v[114:115], v[4:5], v[28:29] op_sel:[0,1]
	ds_read_b128 v[64:67], v225 offset:3840
	v_pk_fma_f32 v[108:109], v[6:7], v[22:23], v[108:109] op_sel_hi:[1,0,1]
	v_pk_fma_f32 v[110:111], v[8:9], v[22:23], v[110:111] op_sel:[0,1,0]
	v_pk_fma_f32 v[112:113], v[6:7], v[30:31], v[112:113] op_sel_hi:[1,0,1]
	v_pk_fma_f32 v[114:115], v[8:9], v[30:31], v[114:115] op_sel:[0,1,0]
	ds_read_b128 v[68:71], v225 offset:3856
	v_pk_fma_f32 v[108:109], v[10:11], v[24:25], v[108:109] op_sel_hi:[1,0,1]
	v_pk_fma_f32 v[110:111], v[12:13], v[24:25], v[110:111] op_sel:[0,1,0]
	v_pk_fma_f32 v[112:113], v[10:11], v[32:33], v[112:113] op_sel_hi:[1,0,1]
	v_pk_fma_f32 v[114:115], v[12:13], v[32:33], v[114:115] op_sel:[0,1,0]
	ds_read_b128 v[72:75], v225 offset:36608
	v_pk_fma_f32 v[108:109], v[14:15], v[26:27], v[108:109] op_sel_hi:[1,0,1]
	v_pk_fma_f32 v[110:111], v[16:17], v[26:27], v[110:111] op_sel:[0,1,0]
	v_pk_fma_f32 v[112:113], v[14:15], v[34:35], v[112:113] op_sel_hi:[1,0,1]
	v_pk_fma_f32 v[114:115], v[16:17], v[34:35], v[114:115] op_sel:[0,1,0]
	ds_read_b128 v[76:79], v225 offset:36624
	v_pk_add_f32 v[108:109], v[108:109], v[110:111]
	v_pk_add_f32 v[112:113], v[112:113], v[114:115]
	s_waitcnt lgkmcnt(11)
	v_pk_mul_f32 v[116:117], v[60:61], v[36:37] op_sel_hi:[1,0]
	v_pk_mul_f32 v[118:119], v[60:61], v[36:37] op_sel:[0,1]
	v_pk_mul_f32 v[120:121], v[60:61], v[38:39] op_sel_hi:[1,0]
	v_pk_mul_f32 v[122:123], v[60:61], v[38:39] op_sel:[0,1]
	ds_read_b64 v[104:105], v224 offset:44800
	ds_read_b128 v[80:83], v225 offset:28416
	v_add_f32_dpp v108, v108, v108 quad_perm:[1,0,3,2] row_mask:0xf bank_mask:0xf bound_ctrl:1
	v_add_f32_dpp v109, v109, v109 quad_perm:[1,0,3,2] row_mask:0xf bank_mask:0xf bound_ctrl:1
	v_add_f32_dpp v112, v112, v112 quad_perm:[1,0,3,2] row_mask:0xf bank_mask:0xf bound_ctrl:1
	v_add_f32_dpp v113, v113, v113 quad_perm:[1,0,3,2] row_mask:0xf bank_mask:0xf bound_ctrl:1
	s_waitcnt lgkmcnt(12)
	v_pk_mul_f32 v[124:125], v[60:61], v[40:41] op_sel_hi:[1,0]
	v_pk_mul_f32 v[126:127], v[60:61], v[40:41] op_sel:[0,1]
	v_pk_mul_f32 v[128:129], v[60:61], v[42:43] op_sel_hi:[1,0]
	v_pk_mul_f32 v[130:131], v[60:61], v[42:43] op_sel:[0,1]
	ds_read_b128 v[84:87], v225 offset:28432
	ds_read_b64 v[106:107], v134 offset:57464
	v_add_f32_dpp v108, v108, v108 quad_perm:[2,3,0,1] row_mask:0xf bank_mask:0xf bound_ctrl:1
	v_add_f32_dpp v109, v109, v109 quad_perm:[2,3,0,1] row_mask:0xf bank_mask:0xf bound_ctrl:1
	v_add_f32_dpp v112, v112, v112 quad_perm:[2,3,0,1] row_mask:0xf bank_mask:0xf bound_ctrl:1
	v_add_f32_dpp v113, v113, v113 quad_perm:[2,3,0,1] row_mask:0xf bank_mask:0xf bound_ctrl:1
	ds_read_b128 v[88:91], v225 offset:20224
	s_nop 0
	v_add_f32_dpp v108, v108, v108 row_half_mirror row_mask:0xf bank_mask:0xf bound_ctrl:1
	v_add_f32_dpp v109, v109, v109 row_half_mirror row_mask:0xf bank_mask:0xf bound_ctrl:1
	v_add_f32_dpp v112, v112, v112 row_half_mirror row_mask:0xf bank_mask:0xf bound_ctrl:1
	v_add_f32_dpp v113, v113, v113 row_half_mirror row_mask:0xf bank_mask:0xf bound_ctrl:1
	ds_read_b128 v[92:95], v225 offset:20240
	s_waitcnt lgkmcnt(13)
	s_nop 0
	v_pk_fma_f32 v[116:117], v[108:109], v[44:45], v[116:117] op_sel_hi:[1,0,1] neg_lo:[1,0,0] neg_hi:[1,0,0]
	v_pk_fma_f32 v[118:119], v[108:109], v[44:45], v[118:119] op_sel:[0,1,0] neg_lo:[1,0,0] neg_hi:[1,0,0]
	v_pk_fma_f32 v[120:121], v[108:109], v[46:47], v[120:121] op_sel_hi:[1,0,1] neg_lo:[1,0,0] neg_hi:[1,0,0]
	v_pk_fma_f32 v[122:123], v[108:109], v[46:47], v[122:123] op_sel:[0,1,0] neg_lo:[1,0,0] neg_hi:[1,0,0]
	v_pk_fma_f32 v[124:125], v[108:109], v[48:49], v[124:125] op_sel_hi:[1,0,1] neg_lo:[1,0,0] neg_hi:[1,0,0]
	v_pk_fma_f32 v[126:127], v[108:109], v[48:49], v[126:127] op_sel:[0,1,0] neg_lo:[1,0,0] neg_hi:[1,0,0]
	v_pk_fma_f32 v[128:129], v[108:109], v[50:51], v[128:129] op_sel_hi:[1,0,1] neg_lo:[1,0,0] neg_hi:[1,0,0]
	v_pk_fma_f32 v[130:131], v[108:109], v[50:51], v[130:131] op_sel:[0,1,0] neg_lo:[1,0,0] neg_hi:[1,0,0]
	ds_read_b128 v[96:99], v225 offset:12032
	v_pk_fma_f32 v[132:133], v[108:109], v[62:63], v[112:113] op_sel_hi:[1,0,1] neg_lo:[1,0,0] neg_hi:[1,0,0]
	ds_read_b128 v[100:103], v225 offset:12048
	s_waitcnt lgkmcnt(13)
	v_pk_fma_f32 v[2:3], v[2:3], v[52:53], v[116:117] op_sel_hi:[1,0,1]
	v_pk_fma_f32 v[4:5], v[4:5], v[52:53], v[118:119] op_sel:[0,1,0]
	v_pk_fma_f32 v[6:7], v[6:7], v[54:55], v[120:121] op_sel_hi:[1,0,1]
	v_pk_fma_f32 v[8:9], v[8:9], v[54:55], v[122:123] op_sel:[0,1,0]
	v_pk_fma_f32 v[132:133], v[60:61], v[62:63], v[132:133] op_sel:[0,1,0]
	v_pk_fma_f32 v[10:11], v[10:11], v[56:57], v[124:125] op_sel_hi:[1,0,1]
	v_pk_fma_f32 v[12:13], v[12:13], v[56:57], v[126:127] op_sel:[0,1,0]
	v_pk_fma_f32 v[14:15], v[14:15], v[58:59], v[128:129] op_sel_hi:[1,0,1]
	v_pk_fma_f32 v[16:17], v[16:17], v[58:59], v[130:131] op_sel:[0,1,0]
	ds_write_b64 v135, v[132:133] offset:52736
	s_waitcnt lgkmcnt(9)
	v_pk_mul_f32 v[108:109], v[2:3], v[64:65] op_sel_hi:[1,0]
	v_pk_mul_f32 v[110:111], v[4:5], v[64:65] op_sel:[0,1]
	v_pk_mul_f32 v[112:113], v[2:3], v[72:73] op_sel_hi:[1,0]
	v_pk_mul_f32 v[114:115], v[4:5], v[72:73] op_sel:[0,1]
	ds_read_b128 v[20:23], v225 offset:4096
	v_pk_fma_f32 v[108:109], v[6:7], v[66:67], v[108:109] op_sel_hi:[1,0,1]
	v_pk_fma_f32 v[110:111], v[8:9], v[66:67], v[110:111] op_sel:[0,1,0]
	v_pk_fma_f32 v[112:113], v[6:7], v[74:75], v[112:113] op_sel_hi:[1,0,1]
	v_pk_fma_f32 v[114:115], v[8:9], v[74:75], v[114:115] op_sel:[0,1,0]
	ds_read_b128 v[24:27], v225 offset:4112
	v_pk_fma_f32 v[108:109], v[10:11], v[68:69], v[108:109] op_sel_hi:[1,0,1]
	v_pk_fma_f32 v[110:111], v[12:13], v[68:69], v[110:111] op_sel:[0,1,0]
	v_pk_fma_f32 v[112:113], v[10:11], v[76:77], v[112:113] op_sel_hi:[1,0,1]
	v_pk_fma_f32 v[114:115], v[12:13], v[76:77], v[114:115] op_sel:[0,1,0]
	ds_read_b128 v[28:31], v225 offset:36864
	v_pk_fma_f32 v[108:109], v[14:15], v[70:71], v[108:109] op_sel_hi:[1,0,1]
	v_pk_fma_f32 v[110:111], v[16:17], v[70:71], v[110:111] op_sel:[0,1,0]
	v_pk_fma_f32 v[112:113], v[14:15], v[78:79], v[112:113] op_sel_hi:[1,0,1]
	v_pk_fma_f32 v[114:115], v[16:17], v[78:79], v[114:115] op_sel:[0,1,0]
	ds_read_b128 v[32:35], v225 offset:36880
	v_pk_add_f32 v[108:109], v[108:109], v[110:111]
	v_pk_add_f32 v[112:113], v[112:113], v[114:115]
	s_waitcnt lgkmcnt(11)
	v_pk_mul_f32 v[116:117], v[104:105], v[80:81] op_sel_hi:[1,0]
	v_pk_mul_f32 v[118:119], v[104:105], v[80:81] op_sel:[0,1]
	v_pk_mul_f32 v[120:121], v[104:105], v[82:83] op_sel_hi:[1,0]
	v_pk_mul_f32 v[122:123], v[104:105], v[82:83] op_sel:[0,1]
	ds_read_b64 v[60:61], v224 offset:45056
	ds_read_b128 v[36:39], v225 offset:28672
	v_add_f32_dpp v108, v108, v108 quad_perm:[1,0,3,2] row_mask:0xf bank_mask:0xf bound_ctrl:1
	v_add_f32_dpp v109, v109, v109 quad_perm:[1,0,3,2] row_mask:0xf bank_mask:0xf bound_ctrl:1
	v_add_f32_dpp v112, v112, v112 quad_perm:[1,0,3,2] row_mask:0xf bank_mask:0xf bound_ctrl:1
	v_add_f32_dpp v113, v113, v113 quad_perm:[1,0,3,2] row_mask:0xf bank_mask:0xf bound_ctrl:1
	s_waitcnt lgkmcnt(12)
	v_pk_mul_f32 v[124:125], v[104:105], v[84:85] op_sel_hi:[1,0]
	v_pk_mul_f32 v[126:127], v[104:105], v[84:85] op_sel:[0,1]
	v_pk_mul_f32 v[128:129], v[104:105], v[86:87] op_sel_hi:[1,0]
	v_pk_mul_f32 v[130:131], v[104:105], v[86:87] op_sel:[0,1]
	ds_read_b128 v[40:43], v225 offset:28688
	ds_read_b64 v[62:63], v134 offset:57472
	v_add_f32_dpp v108, v108, v108 quad_perm:[2,3,0,1] row_mask:0xf bank_mask:0xf bound_ctrl:1
	v_add_f32_dpp v109, v109, v109 quad_perm:[2,3,0,1] row_mask:0xf bank_mask:0xf bound_ctrl:1
	v_add_f32_dpp v112, v112, v112 quad_perm:[2,3,0,1] row_mask:0xf bank_mask:0xf bound_ctrl:1
	v_add_f32_dpp v113, v113, v113 quad_perm:[2,3,0,1] row_mask:0xf bank_mask:0xf bound_ctrl:1
	ds_read_b128 v[44:47], v225 offset:20480
	s_nop 0
	v_add_f32_dpp v108, v108, v108 row_half_mirror row_mask:0xf bank_mask:0xf bound_ctrl:1
	v_add_f32_dpp v109, v109, v109 row_half_mirror row_mask:0xf bank_mask:0xf bound_ctrl:1
	v_add_f32_dpp v112, v112, v112 row_half_mirror row_mask:0xf bank_mask:0xf bound_ctrl:1
	v_add_f32_dpp v113, v113, v113 row_half_mirror row_mask:0xf bank_mask:0xf bound_ctrl:1
	ds_read_b128 v[48:51], v225 offset:20496
	s_waitcnt lgkmcnt(13)
	s_nop 0
	v_pk_fma_f32 v[116:117], v[108:109], v[88:89], v[116:117] op_sel_hi:[1,0,1] neg_lo:[1,0,0] neg_hi:[1,0,0]
	v_pk_fma_f32 v[118:119], v[108:109], v[88:89], v[118:119] op_sel:[0,1,0] neg_lo:[1,0,0] neg_hi:[1,0,0]
	v_pk_fma_f32 v[120:121], v[108:109], v[90:91], v[120:121] op_sel_hi:[1,0,1] neg_lo:[1,0,0] neg_hi:[1,0,0]
	v_pk_fma_f32 v[122:123], v[108:109], v[90:91], v[122:123] op_sel:[0,1,0] neg_lo:[1,0,0] neg_hi:[1,0,0]
	v_pk_fma_f32 v[124:125], v[108:109], v[92:93], v[124:125] op_sel_hi:[1,0,1] neg_lo:[1,0,0] neg_hi:[1,0,0]
	v_pk_fma_f32 v[126:127], v[108:109], v[92:93], v[126:127] op_sel:[0,1,0] neg_lo:[1,0,0] neg_hi:[1,0,0]
	v_pk_fma_f32 v[128:129], v[108:109], v[94:95], v[128:129] op_sel_hi:[1,0,1] neg_lo:[1,0,0] neg_hi:[1,0,0]
	v_pk_fma_f32 v[130:131], v[108:109], v[94:95], v[130:131] op_sel:[0,1,0] neg_lo:[1,0,0] neg_hi:[1,0,0]
	ds_read_b128 v[52:55], v225 offset:12288
	v_pk_fma_f32 v[132:133], v[108:109], v[106:107], v[112:113] op_sel_hi:[1,0,1] neg_lo:[1,0,0] neg_hi:[1,0,0]
	ds_read_b128 v[56:59], v225 offset:12304
	s_waitcnt lgkmcnt(13)
	v_pk_fma_f32 v[2:3], v[2:3], v[96:97], v[116:117] op_sel_hi:[1,0,1]
	v_pk_fma_f32 v[4:5], v[4:5], v[96:97], v[118:119] op_sel:[0,1,0]
	v_pk_fma_f32 v[6:7], v[6:7], v[98:99], v[120:121] op_sel_hi:[1,0,1]
	v_pk_fma_f32 v[8:9], v[8:9], v[98:99], v[122:123] op_sel:[0,1,0]
	v_pk_fma_f32 v[132:133], v[104:105], v[106:107], v[132:133] op_sel:[0,1,0]
	v_pk_fma_f32 v[10:11], v[10:11], v[100:101], v[124:125] op_sel_hi:[1,0,1]
	v_pk_fma_f32 v[12:13], v[12:13], v[100:101], v[126:127] op_sel:[0,1,0]
	v_pk_fma_f32 v[14:15], v[14:15], v[102:103], v[128:129] op_sel_hi:[1,0,1]
	v_pk_fma_f32 v[16:17], v[16:17], v[102:103], v[130:131] op_sel:[0,1,0]
	ds_write_b64 v135, v[132:133] offset:52992
	s_waitcnt lgkmcnt(9)
	v_pk_mul_f32 v[108:109], v[2:3], v[20:21] op_sel_hi:[1,0]
	v_pk_mul_f32 v[110:111], v[4:5], v[20:21] op_sel:[0,1]
	v_pk_mul_f32 v[112:113], v[2:3], v[28:29] op_sel_hi:[1,0]
	v_pk_mul_f32 v[114:115], v[4:5], v[28:29] op_sel:[0,1]
	ds_read_b128 v[64:67], v225 offset:4352
	v_pk_fma_f32 v[108:109], v[6:7], v[22:23], v[108:109] op_sel_hi:[1,0,1]
	v_pk_fma_f32 v[110:111], v[8:9], v[22:23], v[110:111] op_sel:[0,1,0]
	v_pk_fma_f32 v[112:113], v[6:7], v[30:31], v[112:113] op_sel_hi:[1,0,1]
	v_pk_fma_f32 v[114:115], v[8:9], v[30:31], v[114:115] op_sel:[0,1,0]
	ds_read_b128 v[68:71], v225 offset:4368
	v_pk_fma_f32 v[108:109], v[10:11], v[24:25], v[108:109] op_sel_hi:[1,0,1]
	v_pk_fma_f32 v[110:111], v[12:13], v[24:25], v[110:111] op_sel:[0,1,0]
	v_pk_fma_f32 v[112:113], v[10:11], v[32:33], v[112:113] op_sel_hi:[1,0,1]
	v_pk_fma_f32 v[114:115], v[12:13], v[32:33], v[114:115] op_sel:[0,1,0]
	ds_read_b128 v[72:75], v225 offset:37120
	v_pk_fma_f32 v[108:109], v[14:15], v[26:27], v[108:109] op_sel_hi:[1,0,1]
	v_pk_fma_f32 v[110:111], v[16:17], v[26:27], v[110:111] op_sel:[0,1,0]
	v_pk_fma_f32 v[112:113], v[14:15], v[34:35], v[112:113] op_sel_hi:[1,0,1]
	v_pk_fma_f32 v[114:115], v[16:17], v[34:35], v[114:115] op_sel:[0,1,0]
	ds_read_b128 v[76:79], v225 offset:37136
	v_pk_add_f32 v[108:109], v[108:109], v[110:111]
	v_pk_add_f32 v[112:113], v[112:113], v[114:115]
	s_waitcnt lgkmcnt(11)
	v_pk_mul_f32 v[116:117], v[60:61], v[36:37] op_sel_hi:[1,0]
	v_pk_mul_f32 v[118:119], v[60:61], v[36:37] op_sel:[0,1]
	v_pk_mul_f32 v[120:121], v[60:61], v[38:39] op_sel_hi:[1,0]
	v_pk_mul_f32 v[122:123], v[60:61], v[38:39] op_sel:[0,1]
	ds_read_b64 v[104:105], v224 offset:45312
	ds_read_b128 v[80:83], v225 offset:28928
	v_add_f32_dpp v108, v108, v108 quad_perm:[1,0,3,2] row_mask:0xf bank_mask:0xf bound_ctrl:1
	v_add_f32_dpp v109, v109, v109 quad_perm:[1,0,3,2] row_mask:0xf bank_mask:0xf bound_ctrl:1
	v_add_f32_dpp v112, v112, v112 quad_perm:[1,0,3,2] row_mask:0xf bank_mask:0xf bound_ctrl:1
	v_add_f32_dpp v113, v113, v113 quad_perm:[1,0,3,2] row_mask:0xf bank_mask:0xf bound_ctrl:1
	s_waitcnt lgkmcnt(12)
	v_pk_mul_f32 v[124:125], v[60:61], v[40:41] op_sel_hi:[1,0]
	v_pk_mul_f32 v[126:127], v[60:61], v[40:41] op_sel:[0,1]
	v_pk_mul_f32 v[128:129], v[60:61], v[42:43] op_sel_hi:[1,0]
	v_pk_mul_f32 v[130:131], v[60:61], v[42:43] op_sel:[0,1]
	ds_read_b128 v[84:87], v225 offset:28944
	ds_read_b64 v[106:107], v134 offset:57480
	v_add_f32_dpp v108, v108, v108 quad_perm:[2,3,0,1] row_mask:0xf bank_mask:0xf bound_ctrl:1
	v_add_f32_dpp v109, v109, v109 quad_perm:[2,3,0,1] row_mask:0xf bank_mask:0xf bound_ctrl:1
	v_add_f32_dpp v112, v112, v112 quad_perm:[2,3,0,1] row_mask:0xf bank_mask:0xf bound_ctrl:1
	v_add_f32_dpp v113, v113, v113 quad_perm:[2,3,0,1] row_mask:0xf bank_mask:0xf bound_ctrl:1
	ds_read_b128 v[88:91], v225 offset:20736
	s_nop 0
	v_add_f32_dpp v108, v108, v108 row_half_mirror row_mask:0xf bank_mask:0xf bound_ctrl:1
	v_add_f32_dpp v109, v109, v109 row_half_mirror row_mask:0xf bank_mask:0xf bound_ctrl:1
	v_add_f32_dpp v112, v112, v112 row_half_mirror row_mask:0xf bank_mask:0xf bound_ctrl:1
	v_add_f32_dpp v113, v113, v113 row_half_mirror row_mask:0xf bank_mask:0xf bound_ctrl:1
	ds_read_b128 v[92:95], v225 offset:20752
	s_waitcnt lgkmcnt(13)
	s_nop 0
	v_pk_fma_f32 v[116:117], v[108:109], v[44:45], v[116:117] op_sel_hi:[1,0,1] neg_lo:[1,0,0] neg_hi:[1,0,0]
	v_pk_fma_f32 v[118:119], v[108:109], v[44:45], v[118:119] op_sel:[0,1,0] neg_lo:[1,0,0] neg_hi:[1,0,0]
	v_pk_fma_f32 v[120:121], v[108:109], v[46:47], v[120:121] op_sel_hi:[1,0,1] neg_lo:[1,0,0] neg_hi:[1,0,0]
	v_pk_fma_f32 v[122:123], v[108:109], v[46:47], v[122:123] op_sel:[0,1,0] neg_lo:[1,0,0] neg_hi:[1,0,0]
	v_pk_fma_f32 v[124:125], v[108:109], v[48:49], v[124:125] op_sel_hi:[1,0,1] neg_lo:[1,0,0] neg_hi:[1,0,0]
	v_pk_fma_f32 v[126:127], v[108:109], v[48:49], v[126:127] op_sel:[0,1,0] neg_lo:[1,0,0] neg_hi:[1,0,0]
	v_pk_fma_f32 v[128:129], v[108:109], v[50:51], v[128:129] op_sel_hi:[1,0,1] neg_lo:[1,0,0] neg_hi:[1,0,0]
	v_pk_fma_f32 v[130:131], v[108:109], v[50:51], v[130:131] op_sel:[0,1,0] neg_lo:[1,0,0] neg_hi:[1,0,0]
	ds_read_b128 v[96:99], v225 offset:12544
	v_pk_fma_f32 v[132:133], v[108:109], v[62:63], v[112:113] op_sel_hi:[1,0,1] neg_lo:[1,0,0] neg_hi:[1,0,0]
	ds_read_b128 v[100:103], v225 offset:12560
	s_waitcnt lgkmcnt(13)
	v_pk_fma_f32 v[2:3], v[2:3], v[52:53], v[116:117] op_sel_hi:[1,0,1]
	v_pk_fma_f32 v[4:5], v[4:5], v[52:53], v[118:119] op_sel:[0,1,0]
	v_pk_fma_f32 v[6:7], v[6:7], v[54:55], v[120:121] op_sel_hi:[1,0,1]
	v_pk_fma_f32 v[8:9], v[8:9], v[54:55], v[122:123] op_sel:[0,1,0]
	v_pk_fma_f32 v[132:133], v[60:61], v[62:63], v[132:133] op_sel:[0,1,0]
	v_pk_fma_f32 v[10:11], v[10:11], v[56:57], v[124:125] op_sel_hi:[1,0,1]
	v_pk_fma_f32 v[12:13], v[12:13], v[56:57], v[126:127] op_sel:[0,1,0]
	v_pk_fma_f32 v[14:15], v[14:15], v[58:59], v[128:129] op_sel_hi:[1,0,1]
	v_pk_fma_f32 v[16:17], v[16:17], v[58:59], v[130:131] op_sel:[0,1,0]
	ds_write_b64 v135, v[132:133] offset:53248
	s_waitcnt lgkmcnt(9)
	v_pk_mul_f32 v[108:109], v[2:3], v[64:65] op_sel_hi:[1,0]
	v_pk_mul_f32 v[110:111], v[4:5], v[64:65] op_sel:[0,1]
	v_pk_mul_f32 v[112:113], v[2:3], v[72:73] op_sel_hi:[1,0]
	v_pk_mul_f32 v[114:115], v[4:5], v[72:73] op_sel:[0,1]
	ds_read_b128 v[20:23], v225 offset:4608
	v_pk_fma_f32 v[108:109], v[6:7], v[66:67], v[108:109] op_sel_hi:[1,0,1]
	v_pk_fma_f32 v[110:111], v[8:9], v[66:67], v[110:111] op_sel:[0,1,0]
	v_pk_fma_f32 v[112:113], v[6:7], v[74:75], v[112:113] op_sel_hi:[1,0,1]
	v_pk_fma_f32 v[114:115], v[8:9], v[74:75], v[114:115] op_sel:[0,1,0]
	ds_read_b128 v[24:27], v225 offset:4624
	v_pk_fma_f32 v[108:109], v[10:11], v[68:69], v[108:109] op_sel_hi:[1,0,1]
	v_pk_fma_f32 v[110:111], v[12:13], v[68:69], v[110:111] op_sel:[0,1,0]
	v_pk_fma_f32 v[112:113], v[10:11], v[76:77], v[112:113] op_sel_hi:[1,0,1]
	v_pk_fma_f32 v[114:115], v[12:13], v[76:77], v[114:115] op_sel:[0,1,0]
	ds_read_b128 v[28:31], v225 offset:37376
	v_pk_fma_f32 v[108:109], v[14:15], v[70:71], v[108:109] op_sel_hi:[1,0,1]
	v_pk_fma_f32 v[110:111], v[16:17], v[70:71], v[110:111] op_sel:[0,1,0]
	v_pk_fma_f32 v[112:113], v[14:15], v[78:79], v[112:113] op_sel_hi:[1,0,1]
	v_pk_fma_f32 v[114:115], v[16:17], v[78:79], v[114:115] op_sel:[0,1,0]
	ds_read_b128 v[32:35], v225 offset:37392
	v_pk_add_f32 v[108:109], v[108:109], v[110:111]
	v_pk_add_f32 v[112:113], v[112:113], v[114:115]
	s_waitcnt lgkmcnt(11)
	v_pk_mul_f32 v[116:117], v[104:105], v[80:81] op_sel_hi:[1,0]
	v_pk_mul_f32 v[118:119], v[104:105], v[80:81] op_sel:[0,1]
	v_pk_mul_f32 v[120:121], v[104:105], v[82:83] op_sel_hi:[1,0]
	v_pk_mul_f32 v[122:123], v[104:105], v[82:83] op_sel:[0,1]
	ds_read_b64 v[60:61], v224 offset:45568
	ds_read_b128 v[36:39], v225 offset:29184
	v_add_f32_dpp v108, v108, v108 quad_perm:[1,0,3,2] row_mask:0xf bank_mask:0xf bound_ctrl:1
	v_add_f32_dpp v109, v109, v109 quad_perm:[1,0,3,2] row_mask:0xf bank_mask:0xf bound_ctrl:1
	v_add_f32_dpp v112, v112, v112 quad_perm:[1,0,3,2] row_mask:0xf bank_mask:0xf bound_ctrl:1
	v_add_f32_dpp v113, v113, v113 quad_perm:[1,0,3,2] row_mask:0xf bank_mask:0xf bound_ctrl:1
	s_waitcnt lgkmcnt(12)
	v_pk_mul_f32 v[124:125], v[104:105], v[84:85] op_sel_hi:[1,0]
	v_pk_mul_f32 v[126:127], v[104:105], v[84:85] op_sel:[0,1]
	v_pk_mul_f32 v[128:129], v[104:105], v[86:87] op_sel_hi:[1,0]
	v_pk_mul_f32 v[130:131], v[104:105], v[86:87] op_sel:[0,1]
	ds_read_b128 v[40:43], v225 offset:29200
	ds_read_b64 v[62:63], v134 offset:57488
	v_add_f32_dpp v108, v108, v108 quad_perm:[2,3,0,1] row_mask:0xf bank_mask:0xf bound_ctrl:1
	v_add_f32_dpp v109, v109, v109 quad_perm:[2,3,0,1] row_mask:0xf bank_mask:0xf bound_ctrl:1
	v_add_f32_dpp v112, v112, v112 quad_perm:[2,3,0,1] row_mask:0xf bank_mask:0xf bound_ctrl:1
	v_add_f32_dpp v113, v113, v113 quad_perm:[2,3,0,1] row_mask:0xf bank_mask:0xf bound_ctrl:1
	ds_read_b128 v[44:47], v225 offset:20992
	s_nop 0
	v_add_f32_dpp v108, v108, v108 row_half_mirror row_mask:0xf bank_mask:0xf bound_ctrl:1
	v_add_f32_dpp v109, v109, v109 row_half_mirror row_mask:0xf bank_mask:0xf bound_ctrl:1
	v_add_f32_dpp v112, v112, v112 row_half_mirror row_mask:0xf bank_mask:0xf bound_ctrl:1
	v_add_f32_dpp v113, v113, v113 row_half_mirror row_mask:0xf bank_mask:0xf bound_ctrl:1
	ds_read_b128 v[48:51], v225 offset:21008
	s_waitcnt lgkmcnt(13)
	s_nop 0
	v_pk_fma_f32 v[116:117], v[108:109], v[88:89], v[116:117] op_sel_hi:[1,0,1] neg_lo:[1,0,0] neg_hi:[1,0,0]
	v_pk_fma_f32 v[118:119], v[108:109], v[88:89], v[118:119] op_sel:[0,1,0] neg_lo:[1,0,0] neg_hi:[1,0,0]
	v_pk_fma_f32 v[120:121], v[108:109], v[90:91], v[120:121] op_sel_hi:[1,0,1] neg_lo:[1,0,0] neg_hi:[1,0,0]
	v_pk_fma_f32 v[122:123], v[108:109], v[90:91], v[122:123] op_sel:[0,1,0] neg_lo:[1,0,0] neg_hi:[1,0,0]
	v_pk_fma_f32 v[124:125], v[108:109], v[92:93], v[124:125] op_sel_hi:[1,0,1] neg_lo:[1,0,0] neg_hi:[1,0,0]
	v_pk_fma_f32 v[126:127], v[108:109], v[92:93], v[126:127] op_sel:[0,1,0] neg_lo:[1,0,0] neg_hi:[1,0,0]
	v_pk_fma_f32 v[128:129], v[108:109], v[94:95], v[128:129] op_sel_hi:[1,0,1] neg_lo:[1,0,0] neg_hi:[1,0,0]
	v_pk_fma_f32 v[130:131], v[108:109], v[94:95], v[130:131] op_sel:[0,1,0] neg_lo:[1,0,0] neg_hi:[1,0,0]
	ds_read_b128 v[52:55], v225 offset:12800
	v_pk_fma_f32 v[132:133], v[108:109], v[106:107], v[112:113] op_sel_hi:[1,0,1] neg_lo:[1,0,0] neg_hi:[1,0,0]
	ds_read_b128 v[56:59], v225 offset:12816
	s_waitcnt lgkmcnt(13)
	v_pk_fma_f32 v[2:3], v[2:3], v[96:97], v[116:117] op_sel_hi:[1,0,1]
	v_pk_fma_f32 v[4:5], v[4:5], v[96:97], v[118:119] op_sel:[0,1,0]
	v_pk_fma_f32 v[6:7], v[6:7], v[98:99], v[120:121] op_sel_hi:[1,0,1]
	v_pk_fma_f32 v[8:9], v[8:9], v[98:99], v[122:123] op_sel:[0,1,0]
	v_pk_fma_f32 v[132:133], v[104:105], v[106:107], v[132:133] op_sel:[0,1,0]
	v_pk_fma_f32 v[10:11], v[10:11], v[100:101], v[124:125] op_sel_hi:[1,0,1]
	v_pk_fma_f32 v[12:13], v[12:13], v[100:101], v[126:127] op_sel:[0,1,0]
	v_pk_fma_f32 v[14:15], v[14:15], v[102:103], v[128:129] op_sel_hi:[1,0,1]
	v_pk_fma_f32 v[16:17], v[16:17], v[102:103], v[130:131] op_sel:[0,1,0]
	ds_write_b64 v135, v[132:133] offset:53504
	s_waitcnt lgkmcnt(9)
	v_pk_mul_f32 v[108:109], v[2:3], v[20:21] op_sel_hi:[1,0]
	v_pk_mul_f32 v[110:111], v[4:5], v[20:21] op_sel:[0,1]
	v_pk_mul_f32 v[112:113], v[2:3], v[28:29] op_sel_hi:[1,0]
	v_pk_mul_f32 v[114:115], v[4:5], v[28:29] op_sel:[0,1]
	ds_read_b128 v[64:67], v225 offset:4864
	v_pk_fma_f32 v[108:109], v[6:7], v[22:23], v[108:109] op_sel_hi:[1,0,1]
	v_pk_fma_f32 v[110:111], v[8:9], v[22:23], v[110:111] op_sel:[0,1,0]
	v_pk_fma_f32 v[112:113], v[6:7], v[30:31], v[112:113] op_sel_hi:[1,0,1]
	v_pk_fma_f32 v[114:115], v[8:9], v[30:31], v[114:115] op_sel:[0,1,0]
	ds_read_b128 v[68:71], v225 offset:4880
	v_pk_fma_f32 v[108:109], v[10:11], v[24:25], v[108:109] op_sel_hi:[1,0,1]
	v_pk_fma_f32 v[110:111], v[12:13], v[24:25], v[110:111] op_sel:[0,1,0]
	v_pk_fma_f32 v[112:113], v[10:11], v[32:33], v[112:113] op_sel_hi:[1,0,1]
	v_pk_fma_f32 v[114:115], v[12:13], v[32:33], v[114:115] op_sel:[0,1,0]
	ds_read_b128 v[72:75], v225 offset:37632
	v_pk_fma_f32 v[108:109], v[14:15], v[26:27], v[108:109] op_sel_hi:[1,0,1]
	v_pk_fma_f32 v[110:111], v[16:17], v[26:27], v[110:111] op_sel:[0,1,0]
	v_pk_fma_f32 v[112:113], v[14:15], v[34:35], v[112:113] op_sel_hi:[1,0,1]
	v_pk_fma_f32 v[114:115], v[16:17], v[34:35], v[114:115] op_sel:[0,1,0]
	ds_read_b128 v[76:79], v225 offset:37648
	v_pk_add_f32 v[108:109], v[108:109], v[110:111]
	v_pk_add_f32 v[112:113], v[112:113], v[114:115]
	s_waitcnt lgkmcnt(11)
	v_pk_mul_f32 v[116:117], v[60:61], v[36:37] op_sel_hi:[1,0]
	v_pk_mul_f32 v[118:119], v[60:61], v[36:37] op_sel:[0,1]
	v_pk_mul_f32 v[120:121], v[60:61], v[38:39] op_sel_hi:[1,0]
	v_pk_mul_f32 v[122:123], v[60:61], v[38:39] op_sel:[0,1]
	ds_read_b64 v[104:105], v224 offset:45824
	ds_read_b128 v[80:83], v225 offset:29440
	v_add_f32_dpp v108, v108, v108 quad_perm:[1,0,3,2] row_mask:0xf bank_mask:0xf bound_ctrl:1
	v_add_f32_dpp v109, v109, v109 quad_perm:[1,0,3,2] row_mask:0xf bank_mask:0xf bound_ctrl:1
	v_add_f32_dpp v112, v112, v112 quad_perm:[1,0,3,2] row_mask:0xf bank_mask:0xf bound_ctrl:1
	v_add_f32_dpp v113, v113, v113 quad_perm:[1,0,3,2] row_mask:0xf bank_mask:0xf bound_ctrl:1
	s_waitcnt lgkmcnt(12)
	v_pk_mul_f32 v[124:125], v[60:61], v[40:41] op_sel_hi:[1,0]
	v_pk_mul_f32 v[126:127], v[60:61], v[40:41] op_sel:[0,1]
	v_pk_mul_f32 v[128:129], v[60:61], v[42:43] op_sel_hi:[1,0]
	v_pk_mul_f32 v[130:131], v[60:61], v[42:43] op_sel:[0,1]
	ds_read_b128 v[84:87], v225 offset:29456
	ds_read_b64 v[106:107], v134 offset:57496
	v_add_f32_dpp v108, v108, v108 quad_perm:[2,3,0,1] row_mask:0xf bank_mask:0xf bound_ctrl:1
	v_add_f32_dpp v109, v109, v109 quad_perm:[2,3,0,1] row_mask:0xf bank_mask:0xf bound_ctrl:1
	v_add_f32_dpp v112, v112, v112 quad_perm:[2,3,0,1] row_mask:0xf bank_mask:0xf bound_ctrl:1
	v_add_f32_dpp v113, v113, v113 quad_perm:[2,3,0,1] row_mask:0xf bank_mask:0xf bound_ctrl:1
	ds_read_b128 v[88:91], v225 offset:21248
	s_nop 0
	v_add_f32_dpp v108, v108, v108 row_half_mirror row_mask:0xf bank_mask:0xf bound_ctrl:1
	v_add_f32_dpp v109, v109, v109 row_half_mirror row_mask:0xf bank_mask:0xf bound_ctrl:1
	v_add_f32_dpp v112, v112, v112 row_half_mirror row_mask:0xf bank_mask:0xf bound_ctrl:1
	v_add_f32_dpp v113, v113, v113 row_half_mirror row_mask:0xf bank_mask:0xf bound_ctrl:1
	ds_read_b128 v[92:95], v225 offset:21264
	s_waitcnt lgkmcnt(13)
	s_nop 0
	v_pk_fma_f32 v[116:117], v[108:109], v[44:45], v[116:117] op_sel_hi:[1,0,1] neg_lo:[1,0,0] neg_hi:[1,0,0]
	v_pk_fma_f32 v[118:119], v[108:109], v[44:45], v[118:119] op_sel:[0,1,0] neg_lo:[1,0,0] neg_hi:[1,0,0]
	v_pk_fma_f32 v[120:121], v[108:109], v[46:47], v[120:121] op_sel_hi:[1,0,1] neg_lo:[1,0,0] neg_hi:[1,0,0]
	v_pk_fma_f32 v[122:123], v[108:109], v[46:47], v[122:123] op_sel:[0,1,0] neg_lo:[1,0,0] neg_hi:[1,0,0]
	v_pk_fma_f32 v[124:125], v[108:109], v[48:49], v[124:125] op_sel_hi:[1,0,1] neg_lo:[1,0,0] neg_hi:[1,0,0]
	v_pk_fma_f32 v[126:127], v[108:109], v[48:49], v[126:127] op_sel:[0,1,0] neg_lo:[1,0,0] neg_hi:[1,0,0]
	v_pk_fma_f32 v[128:129], v[108:109], v[50:51], v[128:129] op_sel_hi:[1,0,1] neg_lo:[1,0,0] neg_hi:[1,0,0]
	v_pk_fma_f32 v[130:131], v[108:109], v[50:51], v[130:131] op_sel:[0,1,0] neg_lo:[1,0,0] neg_hi:[1,0,0]
	ds_read_b128 v[96:99], v225 offset:13056
	v_pk_fma_f32 v[132:133], v[108:109], v[62:63], v[112:113] op_sel_hi:[1,0,1] neg_lo:[1,0,0] neg_hi:[1,0,0]
	ds_read_b128 v[100:103], v225 offset:13072
	s_waitcnt lgkmcnt(13)
	v_pk_fma_f32 v[2:3], v[2:3], v[52:53], v[116:117] op_sel_hi:[1,0,1]
	v_pk_fma_f32 v[4:5], v[4:5], v[52:53], v[118:119] op_sel:[0,1,0]
	v_pk_fma_f32 v[6:7], v[6:7], v[54:55], v[120:121] op_sel_hi:[1,0,1]
	v_pk_fma_f32 v[8:9], v[8:9], v[54:55], v[122:123] op_sel:[0,1,0]
	v_pk_fma_f32 v[132:133], v[60:61], v[62:63], v[132:133] op_sel:[0,1,0]
	v_pk_fma_f32 v[10:11], v[10:11], v[56:57], v[124:125] op_sel_hi:[1,0,1]
	v_pk_fma_f32 v[12:13], v[12:13], v[56:57], v[126:127] op_sel:[0,1,0]
	v_pk_fma_f32 v[14:15], v[14:15], v[58:59], v[128:129] op_sel_hi:[1,0,1]
	v_pk_fma_f32 v[16:17], v[16:17], v[58:59], v[130:131] op_sel:[0,1,0]
	ds_write_b64 v135, v[132:133] offset:53760
	s_waitcnt lgkmcnt(9)
	v_pk_mul_f32 v[108:109], v[2:3], v[64:65] op_sel_hi:[1,0]
	v_pk_mul_f32 v[110:111], v[4:5], v[64:65] op_sel:[0,1]
	v_pk_mul_f32 v[112:113], v[2:3], v[72:73] op_sel_hi:[1,0]
	v_pk_mul_f32 v[114:115], v[4:5], v[72:73] op_sel:[0,1]
	ds_read_b128 v[20:23], v225 offset:5120
	v_pk_fma_f32 v[108:109], v[6:7], v[66:67], v[108:109] op_sel_hi:[1,0,1]
	v_pk_fma_f32 v[110:111], v[8:9], v[66:67], v[110:111] op_sel:[0,1,0]
	v_pk_fma_f32 v[112:113], v[6:7], v[74:75], v[112:113] op_sel_hi:[1,0,1]
	v_pk_fma_f32 v[114:115], v[8:9], v[74:75], v[114:115] op_sel:[0,1,0]
	ds_read_b128 v[24:27], v225 offset:5136
	v_pk_fma_f32 v[108:109], v[10:11], v[68:69], v[108:109] op_sel_hi:[1,0,1]
	v_pk_fma_f32 v[110:111], v[12:13], v[68:69], v[110:111] op_sel:[0,1,0]
	v_pk_fma_f32 v[112:113], v[10:11], v[76:77], v[112:113] op_sel_hi:[1,0,1]
	v_pk_fma_f32 v[114:115], v[12:13], v[76:77], v[114:115] op_sel:[0,1,0]
	ds_read_b128 v[28:31], v225 offset:37888
	v_pk_fma_f32 v[108:109], v[14:15], v[70:71], v[108:109] op_sel_hi:[1,0,1]
	v_pk_fma_f32 v[110:111], v[16:17], v[70:71], v[110:111] op_sel:[0,1,0]
	v_pk_fma_f32 v[112:113], v[14:15], v[78:79], v[112:113] op_sel_hi:[1,0,1]
	v_pk_fma_f32 v[114:115], v[16:17], v[78:79], v[114:115] op_sel:[0,1,0]
	ds_read_b128 v[32:35], v225 offset:37904
	v_pk_add_f32 v[108:109], v[108:109], v[110:111]
	v_pk_add_f32 v[112:113], v[112:113], v[114:115]
	s_waitcnt lgkmcnt(11)
	v_pk_mul_f32 v[116:117], v[104:105], v[80:81] op_sel_hi:[1,0]
	v_pk_mul_f32 v[118:119], v[104:105], v[80:81] op_sel:[0,1]
	v_pk_mul_f32 v[120:121], v[104:105], v[82:83] op_sel_hi:[1,0]
	v_pk_mul_f32 v[122:123], v[104:105], v[82:83] op_sel:[0,1]
	ds_read_b64 v[60:61], v224 offset:46080
	ds_read_b128 v[36:39], v225 offset:29696
	v_add_f32_dpp v108, v108, v108 quad_perm:[1,0,3,2] row_mask:0xf bank_mask:0xf bound_ctrl:1
	v_add_f32_dpp v109, v109, v109 quad_perm:[1,0,3,2] row_mask:0xf bank_mask:0xf bound_ctrl:1
	v_add_f32_dpp v112, v112, v112 quad_perm:[1,0,3,2] row_mask:0xf bank_mask:0xf bound_ctrl:1
	v_add_f32_dpp v113, v113, v113 quad_perm:[1,0,3,2] row_mask:0xf bank_mask:0xf bound_ctrl:1
	s_waitcnt lgkmcnt(12)
	v_pk_mul_f32 v[124:125], v[104:105], v[84:85] op_sel_hi:[1,0]
	v_pk_mul_f32 v[126:127], v[104:105], v[84:85] op_sel:[0,1]
	v_pk_mul_f32 v[128:129], v[104:105], v[86:87] op_sel_hi:[1,0]
	v_pk_mul_f32 v[130:131], v[104:105], v[86:87] op_sel:[0,1]
	ds_read_b128 v[40:43], v225 offset:29712
	ds_read_b64 v[62:63], v134 offset:57504
	v_add_f32_dpp v108, v108, v108 quad_perm:[2,3,0,1] row_mask:0xf bank_mask:0xf bound_ctrl:1
	v_add_f32_dpp v109, v109, v109 quad_perm:[2,3,0,1] row_mask:0xf bank_mask:0xf bound_ctrl:1
	v_add_f32_dpp v112, v112, v112 quad_perm:[2,3,0,1] row_mask:0xf bank_mask:0xf bound_ctrl:1
	v_add_f32_dpp v113, v113, v113 quad_perm:[2,3,0,1] row_mask:0xf bank_mask:0xf bound_ctrl:1
	ds_read_b128 v[44:47], v225 offset:21504
	s_nop 0
	v_add_f32_dpp v108, v108, v108 row_half_mirror row_mask:0xf bank_mask:0xf bound_ctrl:1
	v_add_f32_dpp v109, v109, v109 row_half_mirror row_mask:0xf bank_mask:0xf bound_ctrl:1
	v_add_f32_dpp v112, v112, v112 row_half_mirror row_mask:0xf bank_mask:0xf bound_ctrl:1
	v_add_f32_dpp v113, v113, v113 row_half_mirror row_mask:0xf bank_mask:0xf bound_ctrl:1
	ds_read_b128 v[48:51], v225 offset:21520
	s_waitcnt lgkmcnt(13)
	s_nop 0
	v_pk_fma_f32 v[116:117], v[108:109], v[88:89], v[116:117] op_sel_hi:[1,0,1] neg_lo:[1,0,0] neg_hi:[1,0,0]
	v_pk_fma_f32 v[118:119], v[108:109], v[88:89], v[118:119] op_sel:[0,1,0] neg_lo:[1,0,0] neg_hi:[1,0,0]
	v_pk_fma_f32 v[120:121], v[108:109], v[90:91], v[120:121] op_sel_hi:[1,0,1] neg_lo:[1,0,0] neg_hi:[1,0,0]
	v_pk_fma_f32 v[122:123], v[108:109], v[90:91], v[122:123] op_sel:[0,1,0] neg_lo:[1,0,0] neg_hi:[1,0,0]
	v_pk_fma_f32 v[124:125], v[108:109], v[92:93], v[124:125] op_sel_hi:[1,0,1] neg_lo:[1,0,0] neg_hi:[1,0,0]
	v_pk_fma_f32 v[126:127], v[108:109], v[92:93], v[126:127] op_sel:[0,1,0] neg_lo:[1,0,0] neg_hi:[1,0,0]
	v_pk_fma_f32 v[128:129], v[108:109], v[94:95], v[128:129] op_sel_hi:[1,0,1] neg_lo:[1,0,0] neg_hi:[1,0,0]
	v_pk_fma_f32 v[130:131], v[108:109], v[94:95], v[130:131] op_sel:[0,1,0] neg_lo:[1,0,0] neg_hi:[1,0,0]
	ds_read_b128 v[52:55], v225 offset:13312
	v_pk_fma_f32 v[132:133], v[108:109], v[106:107], v[112:113] op_sel_hi:[1,0,1] neg_lo:[1,0,0] neg_hi:[1,0,0]
	ds_read_b128 v[56:59], v225 offset:13328
	s_waitcnt lgkmcnt(13)
	v_pk_fma_f32 v[2:3], v[2:3], v[96:97], v[116:117] op_sel_hi:[1,0,1]
	v_pk_fma_f32 v[4:5], v[4:5], v[96:97], v[118:119] op_sel:[0,1,0]
	v_pk_fma_f32 v[6:7], v[6:7], v[98:99], v[120:121] op_sel_hi:[1,0,1]
	v_pk_fma_f32 v[8:9], v[8:9], v[98:99], v[122:123] op_sel:[0,1,0]
	v_pk_fma_f32 v[132:133], v[104:105], v[106:107], v[132:133] op_sel:[0,1,0]
	v_pk_fma_f32 v[10:11], v[10:11], v[100:101], v[124:125] op_sel_hi:[1,0,1]
	v_pk_fma_f32 v[12:13], v[12:13], v[100:101], v[126:127] op_sel:[0,1,0]
	v_pk_fma_f32 v[14:15], v[14:15], v[102:103], v[128:129] op_sel_hi:[1,0,1]
	v_pk_fma_f32 v[16:17], v[16:17], v[102:103], v[130:131] op_sel:[0,1,0]
	ds_write_b64 v135, v[132:133] offset:54016
	s_waitcnt lgkmcnt(9)
	v_pk_mul_f32 v[108:109], v[2:3], v[20:21] op_sel_hi:[1,0]
	v_pk_mul_f32 v[110:111], v[4:5], v[20:21] op_sel:[0,1]
	v_pk_mul_f32 v[112:113], v[2:3], v[28:29] op_sel_hi:[1,0]
	v_pk_mul_f32 v[114:115], v[4:5], v[28:29] op_sel:[0,1]
	ds_read_b128 v[64:67], v225 offset:5376
	v_pk_fma_f32 v[108:109], v[6:7], v[22:23], v[108:109] op_sel_hi:[1,0,1]
	v_pk_fma_f32 v[110:111], v[8:9], v[22:23], v[110:111] op_sel:[0,1,0]
	v_pk_fma_f32 v[112:113], v[6:7], v[30:31], v[112:113] op_sel_hi:[1,0,1]
	v_pk_fma_f32 v[114:115], v[8:9], v[30:31], v[114:115] op_sel:[0,1,0]
	ds_read_b128 v[68:71], v225 offset:5392
	v_pk_fma_f32 v[108:109], v[10:11], v[24:25], v[108:109] op_sel_hi:[1,0,1]
	v_pk_fma_f32 v[110:111], v[12:13], v[24:25], v[110:111] op_sel:[0,1,0]
	v_pk_fma_f32 v[112:113], v[10:11], v[32:33], v[112:113] op_sel_hi:[1,0,1]
	v_pk_fma_f32 v[114:115], v[12:13], v[32:33], v[114:115] op_sel:[0,1,0]
	ds_read_b128 v[72:75], v225 offset:38144
	v_pk_fma_f32 v[108:109], v[14:15], v[26:27], v[108:109] op_sel_hi:[1,0,1]
	v_pk_fma_f32 v[110:111], v[16:17], v[26:27], v[110:111] op_sel:[0,1,0]
	v_pk_fma_f32 v[112:113], v[14:15], v[34:35], v[112:113] op_sel_hi:[1,0,1]
	v_pk_fma_f32 v[114:115], v[16:17], v[34:35], v[114:115] op_sel:[0,1,0]
	ds_read_b128 v[76:79], v225 offset:38160
	v_pk_add_f32 v[108:109], v[108:109], v[110:111]
	v_pk_add_f32 v[112:113], v[112:113], v[114:115]
	s_waitcnt lgkmcnt(11)
	v_pk_mul_f32 v[116:117], v[60:61], v[36:37] op_sel_hi:[1,0]
	v_pk_mul_f32 v[118:119], v[60:61], v[36:37] op_sel:[0,1]
	v_pk_mul_f32 v[120:121], v[60:61], v[38:39] op_sel_hi:[1,0]
	v_pk_mul_f32 v[122:123], v[60:61], v[38:39] op_sel:[0,1]
	ds_read_b64 v[104:105], v224 offset:46336
	ds_read_b128 v[80:83], v225 offset:29952
	v_add_f32_dpp v108, v108, v108 quad_perm:[1,0,3,2] row_mask:0xf bank_mask:0xf bound_ctrl:1
	v_add_f32_dpp v109, v109, v109 quad_perm:[1,0,3,2] row_mask:0xf bank_mask:0xf bound_ctrl:1
	v_add_f32_dpp v112, v112, v112 quad_perm:[1,0,3,2] row_mask:0xf bank_mask:0xf bound_ctrl:1
	v_add_f32_dpp v113, v113, v113 quad_perm:[1,0,3,2] row_mask:0xf bank_mask:0xf bound_ctrl:1
	s_waitcnt lgkmcnt(12)
	v_pk_mul_f32 v[124:125], v[60:61], v[40:41] op_sel_hi:[1,0]
	v_pk_mul_f32 v[126:127], v[60:61], v[40:41] op_sel:[0,1]
	v_pk_mul_f32 v[128:129], v[60:61], v[42:43] op_sel_hi:[1,0]
	v_pk_mul_f32 v[130:131], v[60:61], v[42:43] op_sel:[0,1]
	ds_read_b128 v[84:87], v225 offset:29968
	ds_read_b64 v[106:107], v134 offset:57512
	v_add_f32_dpp v108, v108, v108 quad_perm:[2,3,0,1] row_mask:0xf bank_mask:0xf bound_ctrl:1
	v_add_f32_dpp v109, v109, v109 quad_perm:[2,3,0,1] row_mask:0xf bank_mask:0xf bound_ctrl:1
	v_add_f32_dpp v112, v112, v112 quad_perm:[2,3,0,1] row_mask:0xf bank_mask:0xf bound_ctrl:1
	v_add_f32_dpp v113, v113, v113 quad_perm:[2,3,0,1] row_mask:0xf bank_mask:0xf bound_ctrl:1
	ds_read_b128 v[88:91], v225 offset:21760
	s_nop 0
	v_add_f32_dpp v108, v108, v108 row_half_mirror row_mask:0xf bank_mask:0xf bound_ctrl:1
	v_add_f32_dpp v109, v109, v109 row_half_mirror row_mask:0xf bank_mask:0xf bound_ctrl:1
	v_add_f32_dpp v112, v112, v112 row_half_mirror row_mask:0xf bank_mask:0xf bound_ctrl:1
	v_add_f32_dpp v113, v113, v113 row_half_mirror row_mask:0xf bank_mask:0xf bound_ctrl:1
	ds_read_b128 v[92:95], v225 offset:21776
	s_waitcnt lgkmcnt(13)
	s_nop 0
	v_pk_fma_f32 v[116:117], v[108:109], v[44:45], v[116:117] op_sel_hi:[1,0,1] neg_lo:[1,0,0] neg_hi:[1,0,0]
	v_pk_fma_f32 v[118:119], v[108:109], v[44:45], v[118:119] op_sel:[0,1,0] neg_lo:[1,0,0] neg_hi:[1,0,0]
	v_pk_fma_f32 v[120:121], v[108:109], v[46:47], v[120:121] op_sel_hi:[1,0,1] neg_lo:[1,0,0] neg_hi:[1,0,0]
	v_pk_fma_f32 v[122:123], v[108:109], v[46:47], v[122:123] op_sel:[0,1,0] neg_lo:[1,0,0] neg_hi:[1,0,0]
	v_pk_fma_f32 v[124:125], v[108:109], v[48:49], v[124:125] op_sel_hi:[1,0,1] neg_lo:[1,0,0] neg_hi:[1,0,0]
	v_pk_fma_f32 v[126:127], v[108:109], v[48:49], v[126:127] op_sel:[0,1,0] neg_lo:[1,0,0] neg_hi:[1,0,0]
	v_pk_fma_f32 v[128:129], v[108:109], v[50:51], v[128:129] op_sel_hi:[1,0,1] neg_lo:[1,0,0] neg_hi:[1,0,0]
	v_pk_fma_f32 v[130:131], v[108:109], v[50:51], v[130:131] op_sel:[0,1,0] neg_lo:[1,0,0] neg_hi:[1,0,0]
	ds_read_b128 v[96:99], v225 offset:13568
	v_pk_fma_f32 v[132:133], v[108:109], v[62:63], v[112:113] op_sel_hi:[1,0,1] neg_lo:[1,0,0] neg_hi:[1,0,0]
	ds_read_b128 v[100:103], v225 offset:13584
	s_waitcnt lgkmcnt(13)
	v_pk_fma_f32 v[2:3], v[2:3], v[52:53], v[116:117] op_sel_hi:[1,0,1]
	v_pk_fma_f32 v[4:5], v[4:5], v[52:53], v[118:119] op_sel:[0,1,0]
	v_pk_fma_f32 v[6:7], v[6:7], v[54:55], v[120:121] op_sel_hi:[1,0,1]
	v_pk_fma_f32 v[8:9], v[8:9], v[54:55], v[122:123] op_sel:[0,1,0]
	v_pk_fma_f32 v[132:133], v[60:61], v[62:63], v[132:133] op_sel:[0,1,0]
	v_pk_fma_f32 v[10:11], v[10:11], v[56:57], v[124:125] op_sel_hi:[1,0,1]
	v_pk_fma_f32 v[12:13], v[12:13], v[56:57], v[126:127] op_sel:[0,1,0]
	v_pk_fma_f32 v[14:15], v[14:15], v[58:59], v[128:129] op_sel_hi:[1,0,1]
	v_pk_fma_f32 v[16:17], v[16:17], v[58:59], v[130:131] op_sel:[0,1,0]
	ds_write_b64 v135, v[132:133] offset:54272
	s_waitcnt lgkmcnt(9)
	v_pk_mul_f32 v[108:109], v[2:3], v[64:65] op_sel_hi:[1,0]
	v_pk_mul_f32 v[110:111], v[4:5], v[64:65] op_sel:[0,1]
	v_pk_mul_f32 v[112:113], v[2:3], v[72:73] op_sel_hi:[1,0]
	v_pk_mul_f32 v[114:115], v[4:5], v[72:73] op_sel:[0,1]
	ds_read_b128 v[20:23], v225 offset:5632
	v_pk_fma_f32 v[108:109], v[6:7], v[66:67], v[108:109] op_sel_hi:[1,0,1]
	v_pk_fma_f32 v[110:111], v[8:9], v[66:67], v[110:111] op_sel:[0,1,0]
	v_pk_fma_f32 v[112:113], v[6:7], v[74:75], v[112:113] op_sel_hi:[1,0,1]
	v_pk_fma_f32 v[114:115], v[8:9], v[74:75], v[114:115] op_sel:[0,1,0]
	ds_read_b128 v[24:27], v225 offset:5648
	v_pk_fma_f32 v[108:109], v[10:11], v[68:69], v[108:109] op_sel_hi:[1,0,1]
	v_pk_fma_f32 v[110:111], v[12:13], v[68:69], v[110:111] op_sel:[0,1,0]
	v_pk_fma_f32 v[112:113], v[10:11], v[76:77], v[112:113] op_sel_hi:[1,0,1]
	v_pk_fma_f32 v[114:115], v[12:13], v[76:77], v[114:115] op_sel:[0,1,0]
	ds_read_b128 v[28:31], v225 offset:38400
	v_pk_fma_f32 v[108:109], v[14:15], v[70:71], v[108:109] op_sel_hi:[1,0,1]
	v_pk_fma_f32 v[110:111], v[16:17], v[70:71], v[110:111] op_sel:[0,1,0]
	v_pk_fma_f32 v[112:113], v[14:15], v[78:79], v[112:113] op_sel_hi:[1,0,1]
	v_pk_fma_f32 v[114:115], v[16:17], v[78:79], v[114:115] op_sel:[0,1,0]
	ds_read_b128 v[32:35], v225 offset:38416
	v_pk_add_f32 v[108:109], v[108:109], v[110:111]
	v_pk_add_f32 v[112:113], v[112:113], v[114:115]
	s_waitcnt lgkmcnt(11)
	v_pk_mul_f32 v[116:117], v[104:105], v[80:81] op_sel_hi:[1,0]
	v_pk_mul_f32 v[118:119], v[104:105], v[80:81] op_sel:[0,1]
	v_pk_mul_f32 v[120:121], v[104:105], v[82:83] op_sel_hi:[1,0]
	v_pk_mul_f32 v[122:123], v[104:105], v[82:83] op_sel:[0,1]
	ds_read_b64 v[60:61], v224 offset:46592
	ds_read_b128 v[36:39], v225 offset:30208
	v_add_f32_dpp v108, v108, v108 quad_perm:[1,0,3,2] row_mask:0xf bank_mask:0xf bound_ctrl:1
	v_add_f32_dpp v109, v109, v109 quad_perm:[1,0,3,2] row_mask:0xf bank_mask:0xf bound_ctrl:1
	v_add_f32_dpp v112, v112, v112 quad_perm:[1,0,3,2] row_mask:0xf bank_mask:0xf bound_ctrl:1
	v_add_f32_dpp v113, v113, v113 quad_perm:[1,0,3,2] row_mask:0xf bank_mask:0xf bound_ctrl:1
	s_waitcnt lgkmcnt(12)
	v_pk_mul_f32 v[124:125], v[104:105], v[84:85] op_sel_hi:[1,0]
	v_pk_mul_f32 v[126:127], v[104:105], v[84:85] op_sel:[0,1]
	v_pk_mul_f32 v[128:129], v[104:105], v[86:87] op_sel_hi:[1,0]
	v_pk_mul_f32 v[130:131], v[104:105], v[86:87] op_sel:[0,1]
	ds_read_b128 v[40:43], v225 offset:30224
	ds_read_b64 v[62:63], v134 offset:57520
	v_add_f32_dpp v108, v108, v108 quad_perm:[2,3,0,1] row_mask:0xf bank_mask:0xf bound_ctrl:1
	v_add_f32_dpp v109, v109, v109 quad_perm:[2,3,0,1] row_mask:0xf bank_mask:0xf bound_ctrl:1
	v_add_f32_dpp v112, v112, v112 quad_perm:[2,3,0,1] row_mask:0xf bank_mask:0xf bound_ctrl:1
	v_add_f32_dpp v113, v113, v113 quad_perm:[2,3,0,1] row_mask:0xf bank_mask:0xf bound_ctrl:1
	ds_read_b128 v[44:47], v225 offset:22016
	s_nop 0
	v_add_f32_dpp v108, v108, v108 row_half_mirror row_mask:0xf bank_mask:0xf bound_ctrl:1
	v_add_f32_dpp v109, v109, v109 row_half_mirror row_mask:0xf bank_mask:0xf bound_ctrl:1
	v_add_f32_dpp v112, v112, v112 row_half_mirror row_mask:0xf bank_mask:0xf bound_ctrl:1
	v_add_f32_dpp v113, v113, v113 row_half_mirror row_mask:0xf bank_mask:0xf bound_ctrl:1
	ds_read_b128 v[48:51], v225 offset:22032
	s_waitcnt lgkmcnt(13)
	s_nop 0
	v_pk_fma_f32 v[116:117], v[108:109], v[88:89], v[116:117] op_sel_hi:[1,0,1] neg_lo:[1,0,0] neg_hi:[1,0,0]
	v_pk_fma_f32 v[118:119], v[108:109], v[88:89], v[118:119] op_sel:[0,1,0] neg_lo:[1,0,0] neg_hi:[1,0,0]
	v_pk_fma_f32 v[120:121], v[108:109], v[90:91], v[120:121] op_sel_hi:[1,0,1] neg_lo:[1,0,0] neg_hi:[1,0,0]
	v_pk_fma_f32 v[122:123], v[108:109], v[90:91], v[122:123] op_sel:[0,1,0] neg_lo:[1,0,0] neg_hi:[1,0,0]
	v_pk_fma_f32 v[124:125], v[108:109], v[92:93], v[124:125] op_sel_hi:[1,0,1] neg_lo:[1,0,0] neg_hi:[1,0,0]
	v_pk_fma_f32 v[126:127], v[108:109], v[92:93], v[126:127] op_sel:[0,1,0] neg_lo:[1,0,0] neg_hi:[1,0,0]
	v_pk_fma_f32 v[128:129], v[108:109], v[94:95], v[128:129] op_sel_hi:[1,0,1] neg_lo:[1,0,0] neg_hi:[1,0,0]
	v_pk_fma_f32 v[130:131], v[108:109], v[94:95], v[130:131] op_sel:[0,1,0] neg_lo:[1,0,0] neg_hi:[1,0,0]
	ds_read_b128 v[52:55], v225 offset:13824
	v_pk_fma_f32 v[132:133], v[108:109], v[106:107], v[112:113] op_sel_hi:[1,0,1] neg_lo:[1,0,0] neg_hi:[1,0,0]
	ds_read_b128 v[56:59], v225 offset:13840
	s_waitcnt lgkmcnt(13)
	v_pk_fma_f32 v[2:3], v[2:3], v[96:97], v[116:117] op_sel_hi:[1,0,1]
	v_pk_fma_f32 v[4:5], v[4:5], v[96:97], v[118:119] op_sel:[0,1,0]
	v_pk_fma_f32 v[6:7], v[6:7], v[98:99], v[120:121] op_sel_hi:[1,0,1]
	v_pk_fma_f32 v[8:9], v[8:9], v[98:99], v[122:123] op_sel:[0,1,0]
	v_pk_fma_f32 v[132:133], v[104:105], v[106:107], v[132:133] op_sel:[0,1,0]
	v_pk_fma_f32 v[10:11], v[10:11], v[100:101], v[124:125] op_sel_hi:[1,0,1]
	v_pk_fma_f32 v[12:13], v[12:13], v[100:101], v[126:127] op_sel:[0,1,0]
	v_pk_fma_f32 v[14:15], v[14:15], v[102:103], v[128:129] op_sel_hi:[1,0,1]
	v_pk_fma_f32 v[16:17], v[16:17], v[102:103], v[130:131] op_sel:[0,1,0]
	ds_write_b64 v135, v[132:133] offset:54528
	s_waitcnt lgkmcnt(9)
	v_pk_mul_f32 v[108:109], v[2:3], v[20:21] op_sel_hi:[1,0]
	v_pk_mul_f32 v[110:111], v[4:5], v[20:21] op_sel:[0,1]
	v_pk_mul_f32 v[112:113], v[2:3], v[28:29] op_sel_hi:[1,0]
	v_pk_mul_f32 v[114:115], v[4:5], v[28:29] op_sel:[0,1]
	ds_read_b128 v[64:67], v225 offset:5888
	v_pk_fma_f32 v[108:109], v[6:7], v[22:23], v[108:109] op_sel_hi:[1,0,1]
	v_pk_fma_f32 v[110:111], v[8:9], v[22:23], v[110:111] op_sel:[0,1,0]
	v_pk_fma_f32 v[112:113], v[6:7], v[30:31], v[112:113] op_sel_hi:[1,0,1]
	v_pk_fma_f32 v[114:115], v[8:9], v[30:31], v[114:115] op_sel:[0,1,0]
	ds_read_b128 v[68:71], v225 offset:5904
	v_pk_fma_f32 v[108:109], v[10:11], v[24:25], v[108:109] op_sel_hi:[1,0,1]
	v_pk_fma_f32 v[110:111], v[12:13], v[24:25], v[110:111] op_sel:[0,1,0]
	v_pk_fma_f32 v[112:113], v[10:11], v[32:33], v[112:113] op_sel_hi:[1,0,1]
	v_pk_fma_f32 v[114:115], v[12:13], v[32:33], v[114:115] op_sel:[0,1,0]
	ds_read_b128 v[72:75], v225 offset:38656
	v_pk_fma_f32 v[108:109], v[14:15], v[26:27], v[108:109] op_sel_hi:[1,0,1]
	v_pk_fma_f32 v[110:111], v[16:17], v[26:27], v[110:111] op_sel:[0,1,0]
	v_pk_fma_f32 v[112:113], v[14:15], v[34:35], v[112:113] op_sel_hi:[1,0,1]
	v_pk_fma_f32 v[114:115], v[16:17], v[34:35], v[114:115] op_sel:[0,1,0]
	ds_read_b128 v[76:79], v225 offset:38672
	v_pk_add_f32 v[108:109], v[108:109], v[110:111]
	v_pk_add_f32 v[112:113], v[112:113], v[114:115]
	s_waitcnt lgkmcnt(11)
	v_pk_mul_f32 v[116:117], v[60:61], v[36:37] op_sel_hi:[1,0]
	v_pk_mul_f32 v[118:119], v[60:61], v[36:37] op_sel:[0,1]
	v_pk_mul_f32 v[120:121], v[60:61], v[38:39] op_sel_hi:[1,0]
	v_pk_mul_f32 v[122:123], v[60:61], v[38:39] op_sel:[0,1]
	ds_read_b64 v[104:105], v224 offset:46848
	ds_read_b128 v[80:83], v225 offset:30464
	v_add_f32_dpp v108, v108, v108 quad_perm:[1,0,3,2] row_mask:0xf bank_mask:0xf bound_ctrl:1
	v_add_f32_dpp v109, v109, v109 quad_perm:[1,0,3,2] row_mask:0xf bank_mask:0xf bound_ctrl:1
	v_add_f32_dpp v112, v112, v112 quad_perm:[1,0,3,2] row_mask:0xf bank_mask:0xf bound_ctrl:1
	v_add_f32_dpp v113, v113, v113 quad_perm:[1,0,3,2] row_mask:0xf bank_mask:0xf bound_ctrl:1
	s_waitcnt lgkmcnt(12)
	v_pk_mul_f32 v[124:125], v[60:61], v[40:41] op_sel_hi:[1,0]
	v_pk_mul_f32 v[126:127], v[60:61], v[40:41] op_sel:[0,1]
	v_pk_mul_f32 v[128:129], v[60:61], v[42:43] op_sel_hi:[1,0]
	v_pk_mul_f32 v[130:131], v[60:61], v[42:43] op_sel:[0,1]
	ds_read_b128 v[84:87], v225 offset:30480
	ds_read_b64 v[106:107], v134 offset:57528
	v_add_f32_dpp v108, v108, v108 quad_perm:[2,3,0,1] row_mask:0xf bank_mask:0xf bound_ctrl:1
	v_add_f32_dpp v109, v109, v109 quad_perm:[2,3,0,1] row_mask:0xf bank_mask:0xf bound_ctrl:1
	v_add_f32_dpp v112, v112, v112 quad_perm:[2,3,0,1] row_mask:0xf bank_mask:0xf bound_ctrl:1
	v_add_f32_dpp v113, v113, v113 quad_perm:[2,3,0,1] row_mask:0xf bank_mask:0xf bound_ctrl:1
	ds_read_b128 v[88:91], v225 offset:22272
	s_nop 0
	v_add_f32_dpp v108, v108, v108 row_half_mirror row_mask:0xf bank_mask:0xf bound_ctrl:1
	v_add_f32_dpp v109, v109, v109 row_half_mirror row_mask:0xf bank_mask:0xf bound_ctrl:1
	v_add_f32_dpp v112, v112, v112 row_half_mirror row_mask:0xf bank_mask:0xf bound_ctrl:1
	v_add_f32_dpp v113, v113, v113 row_half_mirror row_mask:0xf bank_mask:0xf bound_ctrl:1
	ds_read_b128 v[92:95], v225 offset:22288
	s_waitcnt lgkmcnt(13)
	s_nop 0
	v_pk_fma_f32 v[116:117], v[108:109], v[44:45], v[116:117] op_sel_hi:[1,0,1] neg_lo:[1,0,0] neg_hi:[1,0,0]
	v_pk_fma_f32 v[118:119], v[108:109], v[44:45], v[118:119] op_sel:[0,1,0] neg_lo:[1,0,0] neg_hi:[1,0,0]
	v_pk_fma_f32 v[120:121], v[108:109], v[46:47], v[120:121] op_sel_hi:[1,0,1] neg_lo:[1,0,0] neg_hi:[1,0,0]
	v_pk_fma_f32 v[122:123], v[108:109], v[46:47], v[122:123] op_sel:[0,1,0] neg_lo:[1,0,0] neg_hi:[1,0,0]
	v_pk_fma_f32 v[124:125], v[108:109], v[48:49], v[124:125] op_sel_hi:[1,0,1] neg_lo:[1,0,0] neg_hi:[1,0,0]
	v_pk_fma_f32 v[126:127], v[108:109], v[48:49], v[126:127] op_sel:[0,1,0] neg_lo:[1,0,0] neg_hi:[1,0,0]
	v_pk_fma_f32 v[128:129], v[108:109], v[50:51], v[128:129] op_sel_hi:[1,0,1] neg_lo:[1,0,0] neg_hi:[1,0,0]
	v_pk_fma_f32 v[130:131], v[108:109], v[50:51], v[130:131] op_sel:[0,1,0] neg_lo:[1,0,0] neg_hi:[1,0,0]
	ds_read_b128 v[96:99], v225 offset:14080
	v_pk_fma_f32 v[132:133], v[108:109], v[62:63], v[112:113] op_sel_hi:[1,0,1] neg_lo:[1,0,0] neg_hi:[1,0,0]
	ds_read_b128 v[100:103], v225 offset:14096
	s_waitcnt lgkmcnt(13)
	v_pk_fma_f32 v[2:3], v[2:3], v[52:53], v[116:117] op_sel_hi:[1,0,1]
	v_pk_fma_f32 v[4:5], v[4:5], v[52:53], v[118:119] op_sel:[0,1,0]
	v_pk_fma_f32 v[6:7], v[6:7], v[54:55], v[120:121] op_sel_hi:[1,0,1]
	v_pk_fma_f32 v[8:9], v[8:9], v[54:55], v[122:123] op_sel:[0,1,0]
	v_pk_fma_f32 v[132:133], v[60:61], v[62:63], v[132:133] op_sel:[0,1,0]
	v_pk_fma_f32 v[10:11], v[10:11], v[56:57], v[124:125] op_sel_hi:[1,0,1]
	v_pk_fma_f32 v[12:13], v[12:13], v[56:57], v[126:127] op_sel:[0,1,0]
	v_pk_fma_f32 v[14:15], v[14:15], v[58:59], v[128:129] op_sel_hi:[1,0,1]
	v_pk_fma_f32 v[16:17], v[16:17], v[58:59], v[130:131] op_sel:[0,1,0]
	ds_write_b64 v135, v[132:133] offset:54784
	s_waitcnt lgkmcnt(9)
	v_pk_mul_f32 v[108:109], v[2:3], v[64:65] op_sel_hi:[1,0]
	v_pk_mul_f32 v[110:111], v[4:5], v[64:65] op_sel:[0,1]
	v_pk_mul_f32 v[112:113], v[2:3], v[72:73] op_sel_hi:[1,0]
	v_pk_mul_f32 v[114:115], v[4:5], v[72:73] op_sel:[0,1]
	ds_read_b128 v[20:23], v225 offset:6144
	v_pk_fma_f32 v[108:109], v[6:7], v[66:67], v[108:109] op_sel_hi:[1,0,1]
	v_pk_fma_f32 v[110:111], v[8:9], v[66:67], v[110:111] op_sel:[0,1,0]
	v_pk_fma_f32 v[112:113], v[6:7], v[74:75], v[112:113] op_sel_hi:[1,0,1]
	v_pk_fma_f32 v[114:115], v[8:9], v[74:75], v[114:115] op_sel:[0,1,0]
	ds_read_b128 v[24:27], v225 offset:6160
	v_pk_fma_f32 v[108:109], v[10:11], v[68:69], v[108:109] op_sel_hi:[1,0,1]
	v_pk_fma_f32 v[110:111], v[12:13], v[68:69], v[110:111] op_sel:[0,1,0]
	v_pk_fma_f32 v[112:113], v[10:11], v[76:77], v[112:113] op_sel_hi:[1,0,1]
	v_pk_fma_f32 v[114:115], v[12:13], v[76:77], v[114:115] op_sel:[0,1,0]
	ds_read_b128 v[28:31], v225 offset:38912
	v_pk_fma_f32 v[108:109], v[14:15], v[70:71], v[108:109] op_sel_hi:[1,0,1]
	v_pk_fma_f32 v[110:111], v[16:17], v[70:71], v[110:111] op_sel:[0,1,0]
	v_pk_fma_f32 v[112:113], v[14:15], v[78:79], v[112:113] op_sel_hi:[1,0,1]
	v_pk_fma_f32 v[114:115], v[16:17], v[78:79], v[114:115] op_sel:[0,1,0]
	ds_read_b128 v[32:35], v225 offset:38928
	v_pk_add_f32 v[108:109], v[108:109], v[110:111]
	v_pk_add_f32 v[112:113], v[112:113], v[114:115]
	s_waitcnt lgkmcnt(11)
	v_pk_mul_f32 v[116:117], v[104:105], v[80:81] op_sel_hi:[1,0]
	v_pk_mul_f32 v[118:119], v[104:105], v[80:81] op_sel:[0,1]
	v_pk_mul_f32 v[120:121], v[104:105], v[82:83] op_sel_hi:[1,0]
	v_pk_mul_f32 v[122:123], v[104:105], v[82:83] op_sel:[0,1]
	ds_read_b64 v[60:61], v224 offset:47104
	ds_read_b128 v[36:39], v225 offset:30720
	v_add_f32_dpp v108, v108, v108 quad_perm:[1,0,3,2] row_mask:0xf bank_mask:0xf bound_ctrl:1
	v_add_f32_dpp v109, v109, v109 quad_perm:[1,0,3,2] row_mask:0xf bank_mask:0xf bound_ctrl:1
	v_add_f32_dpp v112, v112, v112 quad_perm:[1,0,3,2] row_mask:0xf bank_mask:0xf bound_ctrl:1
	v_add_f32_dpp v113, v113, v113 quad_perm:[1,0,3,2] row_mask:0xf bank_mask:0xf bound_ctrl:1
	s_waitcnt lgkmcnt(12)
	v_pk_mul_f32 v[124:125], v[104:105], v[84:85] op_sel_hi:[1,0]
	v_pk_mul_f32 v[126:127], v[104:105], v[84:85] op_sel:[0,1]
	v_pk_mul_f32 v[128:129], v[104:105], v[86:87] op_sel_hi:[1,0]
	v_pk_mul_f32 v[130:131], v[104:105], v[86:87] op_sel:[0,1]
	ds_read_b128 v[40:43], v225 offset:30736
	ds_read_b64 v[62:63], v134 offset:57536
	v_add_f32_dpp v108, v108, v108 quad_perm:[2,3,0,1] row_mask:0xf bank_mask:0xf bound_ctrl:1
	v_add_f32_dpp v109, v109, v109 quad_perm:[2,3,0,1] row_mask:0xf bank_mask:0xf bound_ctrl:1
	v_add_f32_dpp v112, v112, v112 quad_perm:[2,3,0,1] row_mask:0xf bank_mask:0xf bound_ctrl:1
	v_add_f32_dpp v113, v113, v113 quad_perm:[2,3,0,1] row_mask:0xf bank_mask:0xf bound_ctrl:1
	ds_read_b128 v[44:47], v225 offset:22528
	s_nop 0
	v_add_f32_dpp v108, v108, v108 row_half_mirror row_mask:0xf bank_mask:0xf bound_ctrl:1
	v_add_f32_dpp v109, v109, v109 row_half_mirror row_mask:0xf bank_mask:0xf bound_ctrl:1
	v_add_f32_dpp v112, v112, v112 row_half_mirror row_mask:0xf bank_mask:0xf bound_ctrl:1
	v_add_f32_dpp v113, v113, v113 row_half_mirror row_mask:0xf bank_mask:0xf bound_ctrl:1
	ds_read_b128 v[48:51], v225 offset:22544
	s_waitcnt lgkmcnt(13)
	s_nop 0
	v_pk_fma_f32 v[116:117], v[108:109], v[88:89], v[116:117] op_sel_hi:[1,0,1] neg_lo:[1,0,0] neg_hi:[1,0,0]
	v_pk_fma_f32 v[118:119], v[108:109], v[88:89], v[118:119] op_sel:[0,1,0] neg_lo:[1,0,0] neg_hi:[1,0,0]
	v_pk_fma_f32 v[120:121], v[108:109], v[90:91], v[120:121] op_sel_hi:[1,0,1] neg_lo:[1,0,0] neg_hi:[1,0,0]
	v_pk_fma_f32 v[122:123], v[108:109], v[90:91], v[122:123] op_sel:[0,1,0] neg_lo:[1,0,0] neg_hi:[1,0,0]
	v_pk_fma_f32 v[124:125], v[108:109], v[92:93], v[124:125] op_sel_hi:[1,0,1] neg_lo:[1,0,0] neg_hi:[1,0,0]
	v_pk_fma_f32 v[126:127], v[108:109], v[92:93], v[126:127] op_sel:[0,1,0] neg_lo:[1,0,0] neg_hi:[1,0,0]
	v_pk_fma_f32 v[128:129], v[108:109], v[94:95], v[128:129] op_sel_hi:[1,0,1] neg_lo:[1,0,0] neg_hi:[1,0,0]
	v_pk_fma_f32 v[130:131], v[108:109], v[94:95], v[130:131] op_sel:[0,1,0] neg_lo:[1,0,0] neg_hi:[1,0,0]
	ds_read_b128 v[52:55], v225 offset:14336
	v_pk_fma_f32 v[132:133], v[108:109], v[106:107], v[112:113] op_sel_hi:[1,0,1] neg_lo:[1,0,0] neg_hi:[1,0,0]
	ds_read_b128 v[56:59], v225 offset:14352
	s_waitcnt lgkmcnt(13)
	v_pk_fma_f32 v[2:3], v[2:3], v[96:97], v[116:117] op_sel_hi:[1,0,1]
	v_pk_fma_f32 v[4:5], v[4:5], v[96:97], v[118:119] op_sel:[0,1,0]
	v_pk_fma_f32 v[6:7], v[6:7], v[98:99], v[120:121] op_sel_hi:[1,0,1]
	v_pk_fma_f32 v[8:9], v[8:9], v[98:99], v[122:123] op_sel:[0,1,0]
	v_pk_fma_f32 v[132:133], v[104:105], v[106:107], v[132:133] op_sel:[0,1,0]
	v_pk_fma_f32 v[10:11], v[10:11], v[100:101], v[124:125] op_sel_hi:[1,0,1]
	v_pk_fma_f32 v[12:13], v[12:13], v[100:101], v[126:127] op_sel:[0,1,0]
	v_pk_fma_f32 v[14:15], v[14:15], v[102:103], v[128:129] op_sel_hi:[1,0,1]
	v_pk_fma_f32 v[16:17], v[16:17], v[102:103], v[130:131] op_sel:[0,1,0]
	ds_write_b64 v135, v[132:133] offset:55040
	s_waitcnt lgkmcnt(9)
	v_pk_mul_f32 v[108:109], v[2:3], v[20:21] op_sel_hi:[1,0]
	v_pk_mul_f32 v[110:111], v[4:5], v[20:21] op_sel:[0,1]
	v_pk_mul_f32 v[112:113], v[2:3], v[28:29] op_sel_hi:[1,0]
	v_pk_mul_f32 v[114:115], v[4:5], v[28:29] op_sel:[0,1]
	ds_read_b128 v[64:67], v225 offset:6400
	v_pk_fma_f32 v[108:109], v[6:7], v[22:23], v[108:109] op_sel_hi:[1,0,1]
	v_pk_fma_f32 v[110:111], v[8:9], v[22:23], v[110:111] op_sel:[0,1,0]
	v_pk_fma_f32 v[112:113], v[6:7], v[30:31], v[112:113] op_sel_hi:[1,0,1]
	v_pk_fma_f32 v[114:115], v[8:9], v[30:31], v[114:115] op_sel:[0,1,0]
	ds_read_b128 v[68:71], v225 offset:6416
	v_pk_fma_f32 v[108:109], v[10:11], v[24:25], v[108:109] op_sel_hi:[1,0,1]
	v_pk_fma_f32 v[110:111], v[12:13], v[24:25], v[110:111] op_sel:[0,1,0]
	v_pk_fma_f32 v[112:113], v[10:11], v[32:33], v[112:113] op_sel_hi:[1,0,1]
	v_pk_fma_f32 v[114:115], v[12:13], v[32:33], v[114:115] op_sel:[0,1,0]
	ds_read_b128 v[72:75], v225 offset:39168
	v_pk_fma_f32 v[108:109], v[14:15], v[26:27], v[108:109] op_sel_hi:[1,0,1]
	v_pk_fma_f32 v[110:111], v[16:17], v[26:27], v[110:111] op_sel:[0,1,0]
	v_pk_fma_f32 v[112:113], v[14:15], v[34:35], v[112:113] op_sel_hi:[1,0,1]
	v_pk_fma_f32 v[114:115], v[16:17], v[34:35], v[114:115] op_sel:[0,1,0]
	ds_read_b128 v[76:79], v225 offset:39184
	v_pk_add_f32 v[108:109], v[108:109], v[110:111]
	v_pk_add_f32 v[112:113], v[112:113], v[114:115]
	s_waitcnt lgkmcnt(11)
	v_pk_mul_f32 v[116:117], v[60:61], v[36:37] op_sel_hi:[1,0]
	v_pk_mul_f32 v[118:119], v[60:61], v[36:37] op_sel:[0,1]
	v_pk_mul_f32 v[120:121], v[60:61], v[38:39] op_sel_hi:[1,0]
	v_pk_mul_f32 v[122:123], v[60:61], v[38:39] op_sel:[0,1]
	ds_read_b64 v[104:105], v224 offset:47360
	ds_read_b128 v[80:83], v225 offset:30976
	v_add_f32_dpp v108, v108, v108 quad_perm:[1,0,3,2] row_mask:0xf bank_mask:0xf bound_ctrl:1
	v_add_f32_dpp v109, v109, v109 quad_perm:[1,0,3,2] row_mask:0xf bank_mask:0xf bound_ctrl:1
	v_add_f32_dpp v112, v112, v112 quad_perm:[1,0,3,2] row_mask:0xf bank_mask:0xf bound_ctrl:1
	v_add_f32_dpp v113, v113, v113 quad_perm:[1,0,3,2] row_mask:0xf bank_mask:0xf bound_ctrl:1
	s_waitcnt lgkmcnt(12)
	v_pk_mul_f32 v[124:125], v[60:61], v[40:41] op_sel_hi:[1,0]
	v_pk_mul_f32 v[126:127], v[60:61], v[40:41] op_sel:[0,1]
	v_pk_mul_f32 v[128:129], v[60:61], v[42:43] op_sel_hi:[1,0]
	v_pk_mul_f32 v[130:131], v[60:61], v[42:43] op_sel:[0,1]
	ds_read_b128 v[84:87], v225 offset:30992
	ds_read_b64 v[106:107], v134 offset:57544
	v_add_f32_dpp v108, v108, v108 quad_perm:[2,3,0,1] row_mask:0xf bank_mask:0xf bound_ctrl:1
	v_add_f32_dpp v109, v109, v109 quad_perm:[2,3,0,1] row_mask:0xf bank_mask:0xf bound_ctrl:1
	v_add_f32_dpp v112, v112, v112 quad_perm:[2,3,0,1] row_mask:0xf bank_mask:0xf bound_ctrl:1
	v_add_f32_dpp v113, v113, v113 quad_perm:[2,3,0,1] row_mask:0xf bank_mask:0xf bound_ctrl:1
	ds_read_b128 v[88:91], v225 offset:22784
	s_nop 0
	v_add_f32_dpp v108, v108, v108 row_half_mirror row_mask:0xf bank_mask:0xf bound_ctrl:1
	v_add_f32_dpp v109, v109, v109 row_half_mirror row_mask:0xf bank_mask:0xf bound_ctrl:1
	v_add_f32_dpp v112, v112, v112 row_half_mirror row_mask:0xf bank_mask:0xf bound_ctrl:1
	v_add_f32_dpp v113, v113, v113 row_half_mirror row_mask:0xf bank_mask:0xf bound_ctrl:1
	ds_read_b128 v[92:95], v225 offset:22800
	s_waitcnt lgkmcnt(13)
	s_nop 0
	v_pk_fma_f32 v[116:117], v[108:109], v[44:45], v[116:117] op_sel_hi:[1,0,1] neg_lo:[1,0,0] neg_hi:[1,0,0]
	v_pk_fma_f32 v[118:119], v[108:109], v[44:45], v[118:119] op_sel:[0,1,0] neg_lo:[1,0,0] neg_hi:[1,0,0]
	v_pk_fma_f32 v[120:121], v[108:109], v[46:47], v[120:121] op_sel_hi:[1,0,1] neg_lo:[1,0,0] neg_hi:[1,0,0]
	v_pk_fma_f32 v[122:123], v[108:109], v[46:47], v[122:123] op_sel:[0,1,0] neg_lo:[1,0,0] neg_hi:[1,0,0]
	v_pk_fma_f32 v[124:125], v[108:109], v[48:49], v[124:125] op_sel_hi:[1,0,1] neg_lo:[1,0,0] neg_hi:[1,0,0]
	v_pk_fma_f32 v[126:127], v[108:109], v[48:49], v[126:127] op_sel:[0,1,0] neg_lo:[1,0,0] neg_hi:[1,0,0]
	v_pk_fma_f32 v[128:129], v[108:109], v[50:51], v[128:129] op_sel_hi:[1,0,1] neg_lo:[1,0,0] neg_hi:[1,0,0]
	v_pk_fma_f32 v[130:131], v[108:109], v[50:51], v[130:131] op_sel:[0,1,0] neg_lo:[1,0,0] neg_hi:[1,0,0]
	ds_read_b128 v[96:99], v225 offset:14592
	v_pk_fma_f32 v[132:133], v[108:109], v[62:63], v[112:113] op_sel_hi:[1,0,1] neg_lo:[1,0,0] neg_hi:[1,0,0]
	ds_read_b128 v[100:103], v225 offset:14608
	s_waitcnt lgkmcnt(13)
	v_pk_fma_f32 v[2:3], v[2:3], v[52:53], v[116:117] op_sel_hi:[1,0,1]
	v_pk_fma_f32 v[4:5], v[4:5], v[52:53], v[118:119] op_sel:[0,1,0]
	v_pk_fma_f32 v[6:7], v[6:7], v[54:55], v[120:121] op_sel_hi:[1,0,1]
	v_pk_fma_f32 v[8:9], v[8:9], v[54:55], v[122:123] op_sel:[0,1,0]
	v_pk_fma_f32 v[132:133], v[60:61], v[62:63], v[132:133] op_sel:[0,1,0]
	v_pk_fma_f32 v[10:11], v[10:11], v[56:57], v[124:125] op_sel_hi:[1,0,1]
	v_pk_fma_f32 v[12:13], v[12:13], v[56:57], v[126:127] op_sel:[0,1,0]
	v_pk_fma_f32 v[14:15], v[14:15], v[58:59], v[128:129] op_sel_hi:[1,0,1]
	v_pk_fma_f32 v[16:17], v[16:17], v[58:59], v[130:131] op_sel:[0,1,0]
	ds_write_b64 v135, v[132:133] offset:55296
	s_waitcnt lgkmcnt(9)
	v_pk_mul_f32 v[108:109], v[2:3], v[64:65] op_sel_hi:[1,0]
	v_pk_mul_f32 v[110:111], v[4:5], v[64:65] op_sel:[0,1]
	v_pk_mul_f32 v[112:113], v[2:3], v[72:73] op_sel_hi:[1,0]
	v_pk_mul_f32 v[114:115], v[4:5], v[72:73] op_sel:[0,1]
	ds_read_b128 v[20:23], v225 offset:6656
	v_pk_fma_f32 v[108:109], v[6:7], v[66:67], v[108:109] op_sel_hi:[1,0,1]
	v_pk_fma_f32 v[110:111], v[8:9], v[66:67], v[110:111] op_sel:[0,1,0]
	v_pk_fma_f32 v[112:113], v[6:7], v[74:75], v[112:113] op_sel_hi:[1,0,1]
	v_pk_fma_f32 v[114:115], v[8:9], v[74:75], v[114:115] op_sel:[0,1,0]
	ds_read_b128 v[24:27], v225 offset:6672
	v_pk_fma_f32 v[108:109], v[10:11], v[68:69], v[108:109] op_sel_hi:[1,0,1]
	v_pk_fma_f32 v[110:111], v[12:13], v[68:69], v[110:111] op_sel:[0,1,0]
	v_pk_fma_f32 v[112:113], v[10:11], v[76:77], v[112:113] op_sel_hi:[1,0,1]
	v_pk_fma_f32 v[114:115], v[12:13], v[76:77], v[114:115] op_sel:[0,1,0]
	ds_read_b128 v[28:31], v225 offset:39424
	v_pk_fma_f32 v[108:109], v[14:15], v[70:71], v[108:109] op_sel_hi:[1,0,1]
	v_pk_fma_f32 v[110:111], v[16:17], v[70:71], v[110:111] op_sel:[0,1,0]
	v_pk_fma_f32 v[112:113], v[14:15], v[78:79], v[112:113] op_sel_hi:[1,0,1]
	v_pk_fma_f32 v[114:115], v[16:17], v[78:79], v[114:115] op_sel:[0,1,0]
	ds_read_b128 v[32:35], v225 offset:39440
	v_pk_add_f32 v[108:109], v[108:109], v[110:111]
	v_pk_add_f32 v[112:113], v[112:113], v[114:115]
	s_waitcnt lgkmcnt(11)
	v_pk_mul_f32 v[116:117], v[104:105], v[80:81] op_sel_hi:[1,0]
	v_pk_mul_f32 v[118:119], v[104:105], v[80:81] op_sel:[0,1]
	v_pk_mul_f32 v[120:121], v[104:105], v[82:83] op_sel_hi:[1,0]
	v_pk_mul_f32 v[122:123], v[104:105], v[82:83] op_sel:[0,1]
	ds_read_b64 v[60:61], v224 offset:47616
	ds_read_b128 v[36:39], v225 offset:31232
	v_add_f32_dpp v108, v108, v108 quad_perm:[1,0,3,2] row_mask:0xf bank_mask:0xf bound_ctrl:1
	v_add_f32_dpp v109, v109, v109 quad_perm:[1,0,3,2] row_mask:0xf bank_mask:0xf bound_ctrl:1
	v_add_f32_dpp v112, v112, v112 quad_perm:[1,0,3,2] row_mask:0xf bank_mask:0xf bound_ctrl:1
	v_add_f32_dpp v113, v113, v113 quad_perm:[1,0,3,2] row_mask:0xf bank_mask:0xf bound_ctrl:1
	s_waitcnt lgkmcnt(12)
	v_pk_mul_f32 v[124:125], v[104:105], v[84:85] op_sel_hi:[1,0]
	v_pk_mul_f32 v[126:127], v[104:105], v[84:85] op_sel:[0,1]
	v_pk_mul_f32 v[128:129], v[104:105], v[86:87] op_sel_hi:[1,0]
	v_pk_mul_f32 v[130:131], v[104:105], v[86:87] op_sel:[0,1]
	ds_read_b128 v[40:43], v225 offset:31248
	ds_read_b64 v[62:63], v134 offset:57552
	v_add_f32_dpp v108, v108, v108 quad_perm:[2,3,0,1] row_mask:0xf bank_mask:0xf bound_ctrl:1
	v_add_f32_dpp v109, v109, v109 quad_perm:[2,3,0,1] row_mask:0xf bank_mask:0xf bound_ctrl:1
	v_add_f32_dpp v112, v112, v112 quad_perm:[2,3,0,1] row_mask:0xf bank_mask:0xf bound_ctrl:1
	v_add_f32_dpp v113, v113, v113 quad_perm:[2,3,0,1] row_mask:0xf bank_mask:0xf bound_ctrl:1
	ds_read_b128 v[44:47], v225 offset:23040
	s_nop 0
	v_add_f32_dpp v108, v108, v108 row_half_mirror row_mask:0xf bank_mask:0xf bound_ctrl:1
	v_add_f32_dpp v109, v109, v109 row_half_mirror row_mask:0xf bank_mask:0xf bound_ctrl:1
	v_add_f32_dpp v112, v112, v112 row_half_mirror row_mask:0xf bank_mask:0xf bound_ctrl:1
	v_add_f32_dpp v113, v113, v113 row_half_mirror row_mask:0xf bank_mask:0xf bound_ctrl:1
	ds_read_b128 v[48:51], v225 offset:23056
	s_waitcnt lgkmcnt(13)
	s_nop 0
	v_pk_fma_f32 v[116:117], v[108:109], v[88:89], v[116:117] op_sel_hi:[1,0,1] neg_lo:[1,0,0] neg_hi:[1,0,0]
	v_pk_fma_f32 v[118:119], v[108:109], v[88:89], v[118:119] op_sel:[0,1,0] neg_lo:[1,0,0] neg_hi:[1,0,0]
	v_pk_fma_f32 v[120:121], v[108:109], v[90:91], v[120:121] op_sel_hi:[1,0,1] neg_lo:[1,0,0] neg_hi:[1,0,0]
	v_pk_fma_f32 v[122:123], v[108:109], v[90:91], v[122:123] op_sel:[0,1,0] neg_lo:[1,0,0] neg_hi:[1,0,0]
	v_pk_fma_f32 v[124:125], v[108:109], v[92:93], v[124:125] op_sel_hi:[1,0,1] neg_lo:[1,0,0] neg_hi:[1,0,0]
	v_pk_fma_f32 v[126:127], v[108:109], v[92:93], v[126:127] op_sel:[0,1,0] neg_lo:[1,0,0] neg_hi:[1,0,0]
	v_pk_fma_f32 v[128:129], v[108:109], v[94:95], v[128:129] op_sel_hi:[1,0,1] neg_lo:[1,0,0] neg_hi:[1,0,0]
	v_pk_fma_f32 v[130:131], v[108:109], v[94:95], v[130:131] op_sel:[0,1,0] neg_lo:[1,0,0] neg_hi:[1,0,0]
	ds_read_b128 v[52:55], v225 offset:14848
	v_pk_fma_f32 v[132:133], v[108:109], v[106:107], v[112:113] op_sel_hi:[1,0,1] neg_lo:[1,0,0] neg_hi:[1,0,0]
	ds_read_b128 v[56:59], v225 offset:14864
	s_waitcnt lgkmcnt(13)
	v_pk_fma_f32 v[2:3], v[2:3], v[96:97], v[116:117] op_sel_hi:[1,0,1]
	v_pk_fma_f32 v[4:5], v[4:5], v[96:97], v[118:119] op_sel:[0,1,0]
	v_pk_fma_f32 v[6:7], v[6:7], v[98:99], v[120:121] op_sel_hi:[1,0,1]
	v_pk_fma_f32 v[8:9], v[8:9], v[98:99], v[122:123] op_sel:[0,1,0]
	v_pk_fma_f32 v[132:133], v[104:105], v[106:107], v[132:133] op_sel:[0,1,0]
	v_pk_fma_f32 v[10:11], v[10:11], v[100:101], v[124:125] op_sel_hi:[1,0,1]
	v_pk_fma_f32 v[12:13], v[12:13], v[100:101], v[126:127] op_sel:[0,1,0]
	v_pk_fma_f32 v[14:15], v[14:15], v[102:103], v[128:129] op_sel_hi:[1,0,1]
	v_pk_fma_f32 v[16:17], v[16:17], v[102:103], v[130:131] op_sel:[0,1,0]
	ds_write_b64 v135, v[132:133] offset:55552
	s_waitcnt lgkmcnt(9)
	v_pk_mul_f32 v[108:109], v[2:3], v[20:21] op_sel_hi:[1,0]
	v_pk_mul_f32 v[110:111], v[4:5], v[20:21] op_sel:[0,1]
	v_pk_mul_f32 v[112:113], v[2:3], v[28:29] op_sel_hi:[1,0]
	v_pk_mul_f32 v[114:115], v[4:5], v[28:29] op_sel:[0,1]
	ds_read_b128 v[64:67], v225 offset:6912
	v_pk_fma_f32 v[108:109], v[6:7], v[22:23], v[108:109] op_sel_hi:[1,0,1]
	v_pk_fma_f32 v[110:111], v[8:9], v[22:23], v[110:111] op_sel:[0,1,0]
	v_pk_fma_f32 v[112:113], v[6:7], v[30:31], v[112:113] op_sel_hi:[1,0,1]
	v_pk_fma_f32 v[114:115], v[8:9], v[30:31], v[114:115] op_sel:[0,1,0]
	ds_read_b128 v[68:71], v225 offset:6928
	v_pk_fma_f32 v[108:109], v[10:11], v[24:25], v[108:109] op_sel_hi:[1,0,1]
	v_pk_fma_f32 v[110:111], v[12:13], v[24:25], v[110:111] op_sel:[0,1,0]
	v_pk_fma_f32 v[112:113], v[10:11], v[32:33], v[112:113] op_sel_hi:[1,0,1]
	v_pk_fma_f32 v[114:115], v[12:13], v[32:33], v[114:115] op_sel:[0,1,0]
	ds_read_b128 v[72:75], v225 offset:39680
	v_pk_fma_f32 v[108:109], v[14:15], v[26:27], v[108:109] op_sel_hi:[1,0,1]
	v_pk_fma_f32 v[110:111], v[16:17], v[26:27], v[110:111] op_sel:[0,1,0]
	v_pk_fma_f32 v[112:113], v[14:15], v[34:35], v[112:113] op_sel_hi:[1,0,1]
	v_pk_fma_f32 v[114:115], v[16:17], v[34:35], v[114:115] op_sel:[0,1,0]
	ds_read_b128 v[76:79], v225 offset:39696
	v_pk_add_f32 v[108:109], v[108:109], v[110:111]
	v_pk_add_f32 v[112:113], v[112:113], v[114:115]
	s_waitcnt lgkmcnt(11)
	v_pk_mul_f32 v[116:117], v[60:61], v[36:37] op_sel_hi:[1,0]
	v_pk_mul_f32 v[118:119], v[60:61], v[36:37] op_sel:[0,1]
	v_pk_mul_f32 v[120:121], v[60:61], v[38:39] op_sel_hi:[1,0]
	v_pk_mul_f32 v[122:123], v[60:61], v[38:39] op_sel:[0,1]
	ds_read_b64 v[104:105], v224 offset:47872
	ds_read_b128 v[80:83], v225 offset:31488
	v_add_f32_dpp v108, v108, v108 quad_perm:[1,0,3,2] row_mask:0xf bank_mask:0xf bound_ctrl:1
	v_add_f32_dpp v109, v109, v109 quad_perm:[1,0,3,2] row_mask:0xf bank_mask:0xf bound_ctrl:1
	v_add_f32_dpp v112, v112, v112 quad_perm:[1,0,3,2] row_mask:0xf bank_mask:0xf bound_ctrl:1
	v_add_f32_dpp v113, v113, v113 quad_perm:[1,0,3,2] row_mask:0xf bank_mask:0xf bound_ctrl:1
	s_waitcnt lgkmcnt(12)
	v_pk_mul_f32 v[124:125], v[60:61], v[40:41] op_sel_hi:[1,0]
	v_pk_mul_f32 v[126:127], v[60:61], v[40:41] op_sel:[0,1]
	v_pk_mul_f32 v[128:129], v[60:61], v[42:43] op_sel_hi:[1,0]
	v_pk_mul_f32 v[130:131], v[60:61], v[42:43] op_sel:[0,1]
	ds_read_b128 v[84:87], v225 offset:31504
	ds_read_b64 v[106:107], v134 offset:57560
	v_add_f32_dpp v108, v108, v108 quad_perm:[2,3,0,1] row_mask:0xf bank_mask:0xf bound_ctrl:1
	v_add_f32_dpp v109, v109, v109 quad_perm:[2,3,0,1] row_mask:0xf bank_mask:0xf bound_ctrl:1
	v_add_f32_dpp v112, v112, v112 quad_perm:[2,3,0,1] row_mask:0xf bank_mask:0xf bound_ctrl:1
	v_add_f32_dpp v113, v113, v113 quad_perm:[2,3,0,1] row_mask:0xf bank_mask:0xf bound_ctrl:1
	ds_read_b128 v[88:91], v225 offset:23296
	s_nop 0
	v_add_f32_dpp v108, v108, v108 row_half_mirror row_mask:0xf bank_mask:0xf bound_ctrl:1
	v_add_f32_dpp v109, v109, v109 row_half_mirror row_mask:0xf bank_mask:0xf bound_ctrl:1
	v_add_f32_dpp v112, v112, v112 row_half_mirror row_mask:0xf bank_mask:0xf bound_ctrl:1
	v_add_f32_dpp v113, v113, v113 row_half_mirror row_mask:0xf bank_mask:0xf bound_ctrl:1
	ds_read_b128 v[92:95], v225 offset:23312
	s_waitcnt lgkmcnt(13)
	s_nop 0
	v_pk_fma_f32 v[116:117], v[108:109], v[44:45], v[116:117] op_sel_hi:[1,0,1] neg_lo:[1,0,0] neg_hi:[1,0,0]
	v_pk_fma_f32 v[118:119], v[108:109], v[44:45], v[118:119] op_sel:[0,1,0] neg_lo:[1,0,0] neg_hi:[1,0,0]
	v_pk_fma_f32 v[120:121], v[108:109], v[46:47], v[120:121] op_sel_hi:[1,0,1] neg_lo:[1,0,0] neg_hi:[1,0,0]
	v_pk_fma_f32 v[122:123], v[108:109], v[46:47], v[122:123] op_sel:[0,1,0] neg_lo:[1,0,0] neg_hi:[1,0,0]
	v_pk_fma_f32 v[124:125], v[108:109], v[48:49], v[124:125] op_sel_hi:[1,0,1] neg_lo:[1,0,0] neg_hi:[1,0,0]
	v_pk_fma_f32 v[126:127], v[108:109], v[48:49], v[126:127] op_sel:[0,1,0] neg_lo:[1,0,0] neg_hi:[1,0,0]
	v_pk_fma_f32 v[128:129], v[108:109], v[50:51], v[128:129] op_sel_hi:[1,0,1] neg_lo:[1,0,0] neg_hi:[1,0,0]
	v_pk_fma_f32 v[130:131], v[108:109], v[50:51], v[130:131] op_sel:[0,1,0] neg_lo:[1,0,0] neg_hi:[1,0,0]
	ds_read_b128 v[96:99], v225 offset:15104
	v_pk_fma_f32 v[132:133], v[108:109], v[62:63], v[112:113] op_sel_hi:[1,0,1] neg_lo:[1,0,0] neg_hi:[1,0,0]
	ds_read_b128 v[100:103], v225 offset:15120
	s_waitcnt lgkmcnt(13)
	v_pk_fma_f32 v[2:3], v[2:3], v[52:53], v[116:117] op_sel_hi:[1,0,1]
	v_pk_fma_f32 v[4:5], v[4:5], v[52:53], v[118:119] op_sel:[0,1,0]
	v_pk_fma_f32 v[6:7], v[6:7], v[54:55], v[120:121] op_sel_hi:[1,0,1]
	v_pk_fma_f32 v[8:9], v[8:9], v[54:55], v[122:123] op_sel:[0,1,0]
	v_pk_fma_f32 v[132:133], v[60:61], v[62:63], v[132:133] op_sel:[0,1,0]
	v_pk_fma_f32 v[10:11], v[10:11], v[56:57], v[124:125] op_sel_hi:[1,0,1]
	v_pk_fma_f32 v[12:13], v[12:13], v[56:57], v[126:127] op_sel:[0,1,0]
	v_pk_fma_f32 v[14:15], v[14:15], v[58:59], v[128:129] op_sel_hi:[1,0,1]
	v_pk_fma_f32 v[16:17], v[16:17], v[58:59], v[130:131] op_sel:[0,1,0]
	ds_write_b64 v135, v[132:133] offset:55808
	s_waitcnt lgkmcnt(9)
	v_pk_mul_f32 v[108:109], v[2:3], v[64:65] op_sel_hi:[1,0]
	v_pk_mul_f32 v[110:111], v[4:5], v[64:65] op_sel:[0,1]
	v_pk_mul_f32 v[112:113], v[2:3], v[72:73] op_sel_hi:[1,0]
	v_pk_mul_f32 v[114:115], v[4:5], v[72:73] op_sel:[0,1]
	ds_read_b128 v[20:23], v225 offset:7168
	v_pk_fma_f32 v[108:109], v[6:7], v[66:67], v[108:109] op_sel_hi:[1,0,1]
	v_pk_fma_f32 v[110:111], v[8:9], v[66:67], v[110:111] op_sel:[0,1,0]
	v_pk_fma_f32 v[112:113], v[6:7], v[74:75], v[112:113] op_sel_hi:[1,0,1]
	v_pk_fma_f32 v[114:115], v[8:9], v[74:75], v[114:115] op_sel:[0,1,0]
	ds_read_b128 v[24:27], v225 offset:7184
	v_pk_fma_f32 v[108:109], v[10:11], v[68:69], v[108:109] op_sel_hi:[1,0,1]
	v_pk_fma_f32 v[110:111], v[12:13], v[68:69], v[110:111] op_sel:[0,1,0]
	v_pk_fma_f32 v[112:113], v[10:11], v[76:77], v[112:113] op_sel_hi:[1,0,1]
	v_pk_fma_f32 v[114:115], v[12:13], v[76:77], v[114:115] op_sel:[0,1,0]
	ds_read_b128 v[28:31], v225 offset:39936
	v_pk_fma_f32 v[108:109], v[14:15], v[70:71], v[108:109] op_sel_hi:[1,0,1]
	v_pk_fma_f32 v[110:111], v[16:17], v[70:71], v[110:111] op_sel:[0,1,0]
	v_pk_fma_f32 v[112:113], v[14:15], v[78:79], v[112:113] op_sel_hi:[1,0,1]
	v_pk_fma_f32 v[114:115], v[16:17], v[78:79], v[114:115] op_sel:[0,1,0]
	ds_read_b128 v[32:35], v225 offset:39952
	v_pk_add_f32 v[108:109], v[108:109], v[110:111]
	v_pk_add_f32 v[112:113], v[112:113], v[114:115]
	s_waitcnt lgkmcnt(11)
	v_pk_mul_f32 v[116:117], v[104:105], v[80:81] op_sel_hi:[1,0]
	v_pk_mul_f32 v[118:119], v[104:105], v[80:81] op_sel:[0,1]
	v_pk_mul_f32 v[120:121], v[104:105], v[82:83] op_sel_hi:[1,0]
	v_pk_mul_f32 v[122:123], v[104:105], v[82:83] op_sel:[0,1]
	ds_read_b64 v[60:61], v224 offset:48128
	ds_read_b128 v[36:39], v225 offset:31744
	v_add_f32_dpp v108, v108, v108 quad_perm:[1,0,3,2] row_mask:0xf bank_mask:0xf bound_ctrl:1
	v_add_f32_dpp v109, v109, v109 quad_perm:[1,0,3,2] row_mask:0xf bank_mask:0xf bound_ctrl:1
	v_add_f32_dpp v112, v112, v112 quad_perm:[1,0,3,2] row_mask:0xf bank_mask:0xf bound_ctrl:1
	v_add_f32_dpp v113, v113, v113 quad_perm:[1,0,3,2] row_mask:0xf bank_mask:0xf bound_ctrl:1
	s_waitcnt lgkmcnt(12)
	v_pk_mul_f32 v[124:125], v[104:105], v[84:85] op_sel_hi:[1,0]
	v_pk_mul_f32 v[126:127], v[104:105], v[84:85] op_sel:[0,1]
	v_pk_mul_f32 v[128:129], v[104:105], v[86:87] op_sel_hi:[1,0]
	v_pk_mul_f32 v[130:131], v[104:105], v[86:87] op_sel:[0,1]
	ds_read_b128 v[40:43], v225 offset:31760
	ds_read_b64 v[62:63], v134 offset:57568
	v_add_f32_dpp v108, v108, v108 quad_perm:[2,3,0,1] row_mask:0xf bank_mask:0xf bound_ctrl:1
	v_add_f32_dpp v109, v109, v109 quad_perm:[2,3,0,1] row_mask:0xf bank_mask:0xf bound_ctrl:1
	v_add_f32_dpp v112, v112, v112 quad_perm:[2,3,0,1] row_mask:0xf bank_mask:0xf bound_ctrl:1
	v_add_f32_dpp v113, v113, v113 quad_perm:[2,3,0,1] row_mask:0xf bank_mask:0xf bound_ctrl:1
	ds_read_b128 v[44:47], v225 offset:23552
	s_nop 0
	v_add_f32_dpp v108, v108, v108 row_half_mirror row_mask:0xf bank_mask:0xf bound_ctrl:1
	v_add_f32_dpp v109, v109, v109 row_half_mirror row_mask:0xf bank_mask:0xf bound_ctrl:1
	v_add_f32_dpp v112, v112, v112 row_half_mirror row_mask:0xf bank_mask:0xf bound_ctrl:1
	v_add_f32_dpp v113, v113, v113 row_half_mirror row_mask:0xf bank_mask:0xf bound_ctrl:1
	ds_read_b128 v[48:51], v225 offset:23568
	s_waitcnt lgkmcnt(13)
	s_nop 0
	v_pk_fma_f32 v[116:117], v[108:109], v[88:89], v[116:117] op_sel_hi:[1,0,1] neg_lo:[1,0,0] neg_hi:[1,0,0]
	v_pk_fma_f32 v[118:119], v[108:109], v[88:89], v[118:119] op_sel:[0,1,0] neg_lo:[1,0,0] neg_hi:[1,0,0]
	v_pk_fma_f32 v[120:121], v[108:109], v[90:91], v[120:121] op_sel_hi:[1,0,1] neg_lo:[1,0,0] neg_hi:[1,0,0]
	v_pk_fma_f32 v[122:123], v[108:109], v[90:91], v[122:123] op_sel:[0,1,0] neg_lo:[1,0,0] neg_hi:[1,0,0]
	v_pk_fma_f32 v[124:125], v[108:109], v[92:93], v[124:125] op_sel_hi:[1,0,1] neg_lo:[1,0,0] neg_hi:[1,0,0]
	v_pk_fma_f32 v[126:127], v[108:109], v[92:93], v[126:127] op_sel:[0,1,0] neg_lo:[1,0,0] neg_hi:[1,0,0]
	v_pk_fma_f32 v[128:129], v[108:109], v[94:95], v[128:129] op_sel_hi:[1,0,1] neg_lo:[1,0,0] neg_hi:[1,0,0]
	v_pk_fma_f32 v[130:131], v[108:109], v[94:95], v[130:131] op_sel:[0,1,0] neg_lo:[1,0,0] neg_hi:[1,0,0]
	ds_read_b128 v[52:55], v225 offset:15360
	v_pk_fma_f32 v[132:133], v[108:109], v[106:107], v[112:113] op_sel_hi:[1,0,1] neg_lo:[1,0,0] neg_hi:[1,0,0]
	ds_read_b128 v[56:59], v225 offset:15376
	s_waitcnt lgkmcnt(13)
	v_pk_fma_f32 v[2:3], v[2:3], v[96:97], v[116:117] op_sel_hi:[1,0,1]
	v_pk_fma_f32 v[4:5], v[4:5], v[96:97], v[118:119] op_sel:[0,1,0]
	v_pk_fma_f32 v[6:7], v[6:7], v[98:99], v[120:121] op_sel_hi:[1,0,1]
	v_pk_fma_f32 v[8:9], v[8:9], v[98:99], v[122:123] op_sel:[0,1,0]
	v_pk_fma_f32 v[132:133], v[104:105], v[106:107], v[132:133] op_sel:[0,1,0]
	v_pk_fma_f32 v[10:11], v[10:11], v[100:101], v[124:125] op_sel_hi:[1,0,1]
	v_pk_fma_f32 v[12:13], v[12:13], v[100:101], v[126:127] op_sel:[0,1,0]
	v_pk_fma_f32 v[14:15], v[14:15], v[102:103], v[128:129] op_sel_hi:[1,0,1]
	v_pk_fma_f32 v[16:17], v[16:17], v[102:103], v[130:131] op_sel:[0,1,0]
	ds_write_b64 v135, v[132:133] offset:56064
	s_waitcnt lgkmcnt(9)
	v_pk_mul_f32 v[108:109], v[2:3], v[20:21] op_sel_hi:[1,0]
	v_pk_mul_f32 v[110:111], v[4:5], v[20:21] op_sel:[0,1]
	v_pk_mul_f32 v[112:113], v[2:3], v[28:29] op_sel_hi:[1,0]
	v_pk_mul_f32 v[114:115], v[4:5], v[28:29] op_sel:[0,1]
	ds_read_b128 v[64:67], v225 offset:7424
	v_pk_fma_f32 v[108:109], v[6:7], v[22:23], v[108:109] op_sel_hi:[1,0,1]
	v_pk_fma_f32 v[110:111], v[8:9], v[22:23], v[110:111] op_sel:[0,1,0]
	v_pk_fma_f32 v[112:113], v[6:7], v[30:31], v[112:113] op_sel_hi:[1,0,1]
	v_pk_fma_f32 v[114:115], v[8:9], v[30:31], v[114:115] op_sel:[0,1,0]
	ds_read_b128 v[68:71], v225 offset:7440
	v_pk_fma_f32 v[108:109], v[10:11], v[24:25], v[108:109] op_sel_hi:[1,0,1]
	v_pk_fma_f32 v[110:111], v[12:13], v[24:25], v[110:111] op_sel:[0,1,0]
	v_pk_fma_f32 v[112:113], v[10:11], v[32:33], v[112:113] op_sel_hi:[1,0,1]
	v_pk_fma_f32 v[114:115], v[12:13], v[32:33], v[114:115] op_sel:[0,1,0]
	ds_read_b128 v[72:75], v225 offset:40192
	v_pk_fma_f32 v[108:109], v[14:15], v[26:27], v[108:109] op_sel_hi:[1,0,1]
	v_pk_fma_f32 v[110:111], v[16:17], v[26:27], v[110:111] op_sel:[0,1,0]
	v_pk_fma_f32 v[112:113], v[14:15], v[34:35], v[112:113] op_sel_hi:[1,0,1]
	v_pk_fma_f32 v[114:115], v[16:17], v[34:35], v[114:115] op_sel:[0,1,0]
	ds_read_b128 v[76:79], v225 offset:40208
	v_pk_add_f32 v[108:109], v[108:109], v[110:111]
	v_pk_add_f32 v[112:113], v[112:113], v[114:115]
	s_waitcnt lgkmcnt(11)
	v_pk_mul_f32 v[116:117], v[60:61], v[36:37] op_sel_hi:[1,0]
	v_pk_mul_f32 v[118:119], v[60:61], v[36:37] op_sel:[0,1]
	v_pk_mul_f32 v[120:121], v[60:61], v[38:39] op_sel_hi:[1,0]
	v_pk_mul_f32 v[122:123], v[60:61], v[38:39] op_sel:[0,1]
	ds_read_b64 v[104:105], v224 offset:48384
	ds_read_b128 v[80:83], v225 offset:32000
	v_add_f32_dpp v108, v108, v108 quad_perm:[1,0,3,2] row_mask:0xf bank_mask:0xf bound_ctrl:1
	v_add_f32_dpp v109, v109, v109 quad_perm:[1,0,3,2] row_mask:0xf bank_mask:0xf bound_ctrl:1
	v_add_f32_dpp v112, v112, v112 quad_perm:[1,0,3,2] row_mask:0xf bank_mask:0xf bound_ctrl:1
	v_add_f32_dpp v113, v113, v113 quad_perm:[1,0,3,2] row_mask:0xf bank_mask:0xf bound_ctrl:1
	s_waitcnt lgkmcnt(12)
	v_pk_mul_f32 v[124:125], v[60:61], v[40:41] op_sel_hi:[1,0]
	v_pk_mul_f32 v[126:127], v[60:61], v[40:41] op_sel:[0,1]
	v_pk_mul_f32 v[128:129], v[60:61], v[42:43] op_sel_hi:[1,0]
	v_pk_mul_f32 v[130:131], v[60:61], v[42:43] op_sel:[0,1]
	ds_read_b128 v[84:87], v225 offset:32016
	ds_read_b64 v[106:107], v134 offset:57576
	v_add_f32_dpp v108, v108, v108 quad_perm:[2,3,0,1] row_mask:0xf bank_mask:0xf bound_ctrl:1
	v_add_f32_dpp v109, v109, v109 quad_perm:[2,3,0,1] row_mask:0xf bank_mask:0xf bound_ctrl:1
	v_add_f32_dpp v112, v112, v112 quad_perm:[2,3,0,1] row_mask:0xf bank_mask:0xf bound_ctrl:1
	v_add_f32_dpp v113, v113, v113 quad_perm:[2,3,0,1] row_mask:0xf bank_mask:0xf bound_ctrl:1
	ds_read_b128 v[88:91], v225 offset:23808
	s_nop 0
	v_add_f32_dpp v108, v108, v108 row_half_mirror row_mask:0xf bank_mask:0xf bound_ctrl:1
	v_add_f32_dpp v109, v109, v109 row_half_mirror row_mask:0xf bank_mask:0xf bound_ctrl:1
	v_add_f32_dpp v112, v112, v112 row_half_mirror row_mask:0xf bank_mask:0xf bound_ctrl:1
	v_add_f32_dpp v113, v113, v113 row_half_mirror row_mask:0xf bank_mask:0xf bound_ctrl:1
	ds_read_b128 v[92:95], v225 offset:23824
	s_waitcnt lgkmcnt(13)
	s_nop 0
	v_pk_fma_f32 v[116:117], v[108:109], v[44:45], v[116:117] op_sel_hi:[1,0,1] neg_lo:[1,0,0] neg_hi:[1,0,0]
	v_pk_fma_f32 v[118:119], v[108:109], v[44:45], v[118:119] op_sel:[0,1,0] neg_lo:[1,0,0] neg_hi:[1,0,0]
	v_pk_fma_f32 v[120:121], v[108:109], v[46:47], v[120:121] op_sel_hi:[1,0,1] neg_lo:[1,0,0] neg_hi:[1,0,0]
	v_pk_fma_f32 v[122:123], v[108:109], v[46:47], v[122:123] op_sel:[0,1,0] neg_lo:[1,0,0] neg_hi:[1,0,0]
	v_pk_fma_f32 v[124:125], v[108:109], v[48:49], v[124:125] op_sel_hi:[1,0,1] neg_lo:[1,0,0] neg_hi:[1,0,0]
	v_pk_fma_f32 v[126:127], v[108:109], v[48:49], v[126:127] op_sel:[0,1,0] neg_lo:[1,0,0] neg_hi:[1,0,0]
	v_pk_fma_f32 v[128:129], v[108:109], v[50:51], v[128:129] op_sel_hi:[1,0,1] neg_lo:[1,0,0] neg_hi:[1,0,0]
	v_pk_fma_f32 v[130:131], v[108:109], v[50:51], v[130:131] op_sel:[0,1,0] neg_lo:[1,0,0] neg_hi:[1,0,0]
	ds_read_b128 v[96:99], v225 offset:15616
	v_pk_fma_f32 v[132:133], v[108:109], v[62:63], v[112:113] op_sel_hi:[1,0,1] neg_lo:[1,0,0] neg_hi:[1,0,0]
	ds_read_b128 v[100:103], v225 offset:15632
	s_waitcnt lgkmcnt(13)
	v_pk_fma_f32 v[2:3], v[2:3], v[52:53], v[116:117] op_sel_hi:[1,0,1]
	v_pk_fma_f32 v[4:5], v[4:5], v[52:53], v[118:119] op_sel:[0,1,0]
	v_pk_fma_f32 v[6:7], v[6:7], v[54:55], v[120:121] op_sel_hi:[1,0,1]
	v_pk_fma_f32 v[8:9], v[8:9], v[54:55], v[122:123] op_sel:[0,1,0]
	v_pk_fma_f32 v[132:133], v[60:61], v[62:63], v[132:133] op_sel:[0,1,0]
	v_pk_fma_f32 v[10:11], v[10:11], v[56:57], v[124:125] op_sel_hi:[1,0,1]
	v_pk_fma_f32 v[12:13], v[12:13], v[56:57], v[126:127] op_sel:[0,1,0]
	v_pk_fma_f32 v[14:15], v[14:15], v[58:59], v[128:129] op_sel_hi:[1,0,1]
	v_pk_fma_f32 v[16:17], v[16:17], v[58:59], v[130:131] op_sel:[0,1,0]
	ds_write_b64 v135, v[132:133] offset:56320
	s_waitcnt lgkmcnt(9)
	v_pk_mul_f32 v[108:109], v[2:3], v[64:65] op_sel_hi:[1,0]
	v_pk_mul_f32 v[110:111], v[4:5], v[64:65] op_sel:[0,1]
	v_pk_mul_f32 v[112:113], v[2:3], v[72:73] op_sel_hi:[1,0]
	v_pk_mul_f32 v[114:115], v[4:5], v[72:73] op_sel:[0,1]
	ds_read_b128 v[20:23], v225 offset:7680
	v_pk_fma_f32 v[108:109], v[6:7], v[66:67], v[108:109] op_sel_hi:[1,0,1]
	v_pk_fma_f32 v[110:111], v[8:9], v[66:67], v[110:111] op_sel:[0,1,0]
	v_pk_fma_f32 v[112:113], v[6:7], v[74:75], v[112:113] op_sel_hi:[1,0,1]
	v_pk_fma_f32 v[114:115], v[8:9], v[74:75], v[114:115] op_sel:[0,1,0]
	ds_read_b128 v[24:27], v225 offset:7696
	v_pk_fma_f32 v[108:109], v[10:11], v[68:69], v[108:109] op_sel_hi:[1,0,1]
	v_pk_fma_f32 v[110:111], v[12:13], v[68:69], v[110:111] op_sel:[0,1,0]
	v_pk_fma_f32 v[112:113], v[10:11], v[76:77], v[112:113] op_sel_hi:[1,0,1]
	v_pk_fma_f32 v[114:115], v[12:13], v[76:77], v[114:115] op_sel:[0,1,0]
	ds_read_b128 v[28:31], v225 offset:40448
	v_pk_fma_f32 v[108:109], v[14:15], v[70:71], v[108:109] op_sel_hi:[1,0,1]
	v_pk_fma_f32 v[110:111], v[16:17], v[70:71], v[110:111] op_sel:[0,1,0]
	v_pk_fma_f32 v[112:113], v[14:15], v[78:79], v[112:113] op_sel_hi:[1,0,1]
	v_pk_fma_f32 v[114:115], v[16:17], v[78:79], v[114:115] op_sel:[0,1,0]
	ds_read_b128 v[32:35], v225 offset:40464
	v_pk_add_f32 v[108:109], v[108:109], v[110:111]
	v_pk_add_f32 v[112:113], v[112:113], v[114:115]
	s_waitcnt lgkmcnt(11)
	v_pk_mul_f32 v[116:117], v[104:105], v[80:81] op_sel_hi:[1,0]
	v_pk_mul_f32 v[118:119], v[104:105], v[80:81] op_sel:[0,1]
	v_pk_mul_f32 v[120:121], v[104:105], v[82:83] op_sel_hi:[1,0]
	v_pk_mul_f32 v[122:123], v[104:105], v[82:83] op_sel:[0,1]
	ds_read_b64 v[60:61], v224 offset:48640
	ds_read_b128 v[36:39], v225 offset:32256
	v_add_f32_dpp v108, v108, v108 quad_perm:[1,0,3,2] row_mask:0xf bank_mask:0xf bound_ctrl:1
	v_add_f32_dpp v109, v109, v109 quad_perm:[1,0,3,2] row_mask:0xf bank_mask:0xf bound_ctrl:1
	v_add_f32_dpp v112, v112, v112 quad_perm:[1,0,3,2] row_mask:0xf bank_mask:0xf bound_ctrl:1
	v_add_f32_dpp v113, v113, v113 quad_perm:[1,0,3,2] row_mask:0xf bank_mask:0xf bound_ctrl:1
	s_waitcnt lgkmcnt(12)
	v_pk_mul_f32 v[124:125], v[104:105], v[84:85] op_sel_hi:[1,0]
	v_pk_mul_f32 v[126:127], v[104:105], v[84:85] op_sel:[0,1]
	v_pk_mul_f32 v[128:129], v[104:105], v[86:87] op_sel_hi:[1,0]
	v_pk_mul_f32 v[130:131], v[104:105], v[86:87] op_sel:[0,1]
	ds_read_b128 v[40:43], v225 offset:32272
	ds_read_b64 v[62:63], v134 offset:57584
	v_add_f32_dpp v108, v108, v108 quad_perm:[2,3,0,1] row_mask:0xf bank_mask:0xf bound_ctrl:1
	v_add_f32_dpp v109, v109, v109 quad_perm:[2,3,0,1] row_mask:0xf bank_mask:0xf bound_ctrl:1
	v_add_f32_dpp v112, v112, v112 quad_perm:[2,3,0,1] row_mask:0xf bank_mask:0xf bound_ctrl:1
	v_add_f32_dpp v113, v113, v113 quad_perm:[2,3,0,1] row_mask:0xf bank_mask:0xf bound_ctrl:1
	ds_read_b128 v[44:47], v225 offset:24064
	s_nop 0
	v_add_f32_dpp v108, v108, v108 row_half_mirror row_mask:0xf bank_mask:0xf bound_ctrl:1
	v_add_f32_dpp v109, v109, v109 row_half_mirror row_mask:0xf bank_mask:0xf bound_ctrl:1
	v_add_f32_dpp v112, v112, v112 row_half_mirror row_mask:0xf bank_mask:0xf bound_ctrl:1
	v_add_f32_dpp v113, v113, v113 row_half_mirror row_mask:0xf bank_mask:0xf bound_ctrl:1
	ds_read_b128 v[48:51], v225 offset:24080
	s_waitcnt lgkmcnt(13)
	s_nop 0
	v_pk_fma_f32 v[116:117], v[108:109], v[88:89], v[116:117] op_sel_hi:[1,0,1] neg_lo:[1,0,0] neg_hi:[1,0,0]
	v_pk_fma_f32 v[118:119], v[108:109], v[88:89], v[118:119] op_sel:[0,1,0] neg_lo:[1,0,0] neg_hi:[1,0,0]
	v_pk_fma_f32 v[120:121], v[108:109], v[90:91], v[120:121] op_sel_hi:[1,0,1] neg_lo:[1,0,0] neg_hi:[1,0,0]
	v_pk_fma_f32 v[122:123], v[108:109], v[90:91], v[122:123] op_sel:[0,1,0] neg_lo:[1,0,0] neg_hi:[1,0,0]
	v_pk_fma_f32 v[124:125], v[108:109], v[92:93], v[124:125] op_sel_hi:[1,0,1] neg_lo:[1,0,0] neg_hi:[1,0,0]
	v_pk_fma_f32 v[126:127], v[108:109], v[92:93], v[126:127] op_sel:[0,1,0] neg_lo:[1,0,0] neg_hi:[1,0,0]
	v_pk_fma_f32 v[128:129], v[108:109], v[94:95], v[128:129] op_sel_hi:[1,0,1] neg_lo:[1,0,0] neg_hi:[1,0,0]
	v_pk_fma_f32 v[130:131], v[108:109], v[94:95], v[130:131] op_sel:[0,1,0] neg_lo:[1,0,0] neg_hi:[1,0,0]
	ds_read_b128 v[52:55], v225 offset:15872
	v_pk_fma_f32 v[132:133], v[108:109], v[106:107], v[112:113] op_sel_hi:[1,0,1] neg_lo:[1,0,0] neg_hi:[1,0,0]
	ds_read_b128 v[56:59], v225 offset:15888
	s_waitcnt lgkmcnt(13)
	v_pk_fma_f32 v[2:3], v[2:3], v[96:97], v[116:117] op_sel_hi:[1,0,1]
	v_pk_fma_f32 v[4:5], v[4:5], v[96:97], v[118:119] op_sel:[0,1,0]
	v_pk_fma_f32 v[6:7], v[6:7], v[98:99], v[120:121] op_sel_hi:[1,0,1]
	v_pk_fma_f32 v[8:9], v[8:9], v[98:99], v[122:123] op_sel:[0,1,0]
	v_pk_fma_f32 v[132:133], v[104:105], v[106:107], v[132:133] op_sel:[0,1,0]
	v_pk_fma_f32 v[10:11], v[10:11], v[100:101], v[124:125] op_sel_hi:[1,0,1]
	v_pk_fma_f32 v[12:13], v[12:13], v[100:101], v[126:127] op_sel:[0,1,0]
	v_pk_fma_f32 v[14:15], v[14:15], v[102:103], v[128:129] op_sel_hi:[1,0,1]
	v_pk_fma_f32 v[16:17], v[16:17], v[102:103], v[130:131] op_sel:[0,1,0]
	ds_write_b64 v135, v[132:133] offset:56576
	s_waitcnt lgkmcnt(9)
	v_pk_mul_f32 v[108:109], v[2:3], v[20:21] op_sel_hi:[1,0]
	v_pk_mul_f32 v[110:111], v[4:5], v[20:21] op_sel:[0,1]
	v_pk_mul_f32 v[112:113], v[2:3], v[28:29] op_sel_hi:[1,0]
	v_pk_mul_f32 v[114:115], v[4:5], v[28:29] op_sel:[0,1]
	ds_read_b128 v[64:67], v225 offset:7936
	v_pk_fma_f32 v[108:109], v[6:7], v[22:23], v[108:109] op_sel_hi:[1,0,1]
	v_pk_fma_f32 v[110:111], v[8:9], v[22:23], v[110:111] op_sel:[0,1,0]
	v_pk_fma_f32 v[112:113], v[6:7], v[30:31], v[112:113] op_sel_hi:[1,0,1]
	v_pk_fma_f32 v[114:115], v[8:9], v[30:31], v[114:115] op_sel:[0,1,0]
	ds_read_b128 v[68:71], v225 offset:7952
	v_pk_fma_f32 v[108:109], v[10:11], v[24:25], v[108:109] op_sel_hi:[1,0,1]
	v_pk_fma_f32 v[110:111], v[12:13], v[24:25], v[110:111] op_sel:[0,1,0]
	v_pk_fma_f32 v[112:113], v[10:11], v[32:33], v[112:113] op_sel_hi:[1,0,1]
	v_pk_fma_f32 v[114:115], v[12:13], v[32:33], v[114:115] op_sel:[0,1,0]
	ds_read_b128 v[72:75], v225 offset:40704
	v_pk_fma_f32 v[108:109], v[14:15], v[26:27], v[108:109] op_sel_hi:[1,0,1]
	v_pk_fma_f32 v[110:111], v[16:17], v[26:27], v[110:111] op_sel:[0,1,0]
	v_pk_fma_f32 v[112:113], v[14:15], v[34:35], v[112:113] op_sel_hi:[1,0,1]
	v_pk_fma_f32 v[114:115], v[16:17], v[34:35], v[114:115] op_sel:[0,1,0]
	ds_read_b128 v[76:79], v225 offset:40720
	v_pk_add_f32 v[108:109], v[108:109], v[110:111]
	v_pk_add_f32 v[112:113], v[112:113], v[114:115]
	s_waitcnt lgkmcnt(11)
	v_pk_mul_f32 v[116:117], v[60:61], v[36:37] op_sel_hi:[1,0]
	v_pk_mul_f32 v[118:119], v[60:61], v[36:37] op_sel:[0,1]
	v_pk_mul_f32 v[120:121], v[60:61], v[38:39] op_sel_hi:[1,0]
	v_pk_mul_f32 v[122:123], v[60:61], v[38:39] op_sel:[0,1]
	ds_read_b64 v[104:105], v224 offset:48896
	ds_read_b128 v[80:83], v225 offset:32512
	v_add_f32_dpp v108, v108, v108 quad_perm:[1,0,3,2] row_mask:0xf bank_mask:0xf bound_ctrl:1
	v_add_f32_dpp v109, v109, v109 quad_perm:[1,0,3,2] row_mask:0xf bank_mask:0xf bound_ctrl:1
	v_add_f32_dpp v112, v112, v112 quad_perm:[1,0,3,2] row_mask:0xf bank_mask:0xf bound_ctrl:1
	v_add_f32_dpp v113, v113, v113 quad_perm:[1,0,3,2] row_mask:0xf bank_mask:0xf bound_ctrl:1
	s_waitcnt lgkmcnt(12)
	v_pk_mul_f32 v[124:125], v[60:61], v[40:41] op_sel_hi:[1,0]
	v_pk_mul_f32 v[126:127], v[60:61], v[40:41] op_sel:[0,1]
	v_pk_mul_f32 v[128:129], v[60:61], v[42:43] op_sel_hi:[1,0]
	v_pk_mul_f32 v[130:131], v[60:61], v[42:43] op_sel:[0,1]
	ds_read_b128 v[84:87], v225 offset:32528
	ds_read_b64 v[106:107], v134 offset:57592
	v_add_f32_dpp v108, v108, v108 quad_perm:[2,3,0,1] row_mask:0xf bank_mask:0xf bound_ctrl:1
	v_add_f32_dpp v109, v109, v109 quad_perm:[2,3,0,1] row_mask:0xf bank_mask:0xf bound_ctrl:1
	v_add_f32_dpp v112, v112, v112 quad_perm:[2,3,0,1] row_mask:0xf bank_mask:0xf bound_ctrl:1
	v_add_f32_dpp v113, v113, v113 quad_perm:[2,3,0,1] row_mask:0xf bank_mask:0xf bound_ctrl:1
	ds_read_b128 v[88:91], v225 offset:24320
	s_nop 0
	v_add_f32_dpp v108, v108, v108 row_half_mirror row_mask:0xf bank_mask:0xf bound_ctrl:1
	v_add_f32_dpp v109, v109, v109 row_half_mirror row_mask:0xf bank_mask:0xf bound_ctrl:1
	v_add_f32_dpp v112, v112, v112 row_half_mirror row_mask:0xf bank_mask:0xf bound_ctrl:1
	v_add_f32_dpp v113, v113, v113 row_half_mirror row_mask:0xf bank_mask:0xf bound_ctrl:1
	ds_read_b128 v[92:95], v225 offset:24336
	s_waitcnt lgkmcnt(13)
	s_nop 0
	v_pk_fma_f32 v[116:117], v[108:109], v[44:45], v[116:117] op_sel_hi:[1,0,1] neg_lo:[1,0,0] neg_hi:[1,0,0]
	v_pk_fma_f32 v[118:119], v[108:109], v[44:45], v[118:119] op_sel:[0,1,0] neg_lo:[1,0,0] neg_hi:[1,0,0]
	v_pk_fma_f32 v[120:121], v[108:109], v[46:47], v[120:121] op_sel_hi:[1,0,1] neg_lo:[1,0,0] neg_hi:[1,0,0]
	v_pk_fma_f32 v[122:123], v[108:109], v[46:47], v[122:123] op_sel:[0,1,0] neg_lo:[1,0,0] neg_hi:[1,0,0]
	v_pk_fma_f32 v[124:125], v[108:109], v[48:49], v[124:125] op_sel_hi:[1,0,1] neg_lo:[1,0,0] neg_hi:[1,0,0]
	v_pk_fma_f32 v[126:127], v[108:109], v[48:49], v[126:127] op_sel:[0,1,0] neg_lo:[1,0,0] neg_hi:[1,0,0]
	v_pk_fma_f32 v[128:129], v[108:109], v[50:51], v[128:129] op_sel_hi:[1,0,1] neg_lo:[1,0,0] neg_hi:[1,0,0]
	v_pk_fma_f32 v[130:131], v[108:109], v[50:51], v[130:131] op_sel:[0,1,0] neg_lo:[1,0,0] neg_hi:[1,0,0]
	ds_read_b128 v[96:99], v225 offset:16128
	v_pk_fma_f32 v[132:133], v[108:109], v[62:63], v[112:113] op_sel_hi:[1,0,1] neg_lo:[1,0,0] neg_hi:[1,0,0]
	ds_read_b128 v[100:103], v225 offset:16144
	s_waitcnt lgkmcnt(13)
	v_pk_fma_f32 v[2:3], v[2:3], v[52:53], v[116:117] op_sel_hi:[1,0,1]
	v_pk_fma_f32 v[4:5], v[4:5], v[52:53], v[118:119] op_sel:[0,1,0]
	v_pk_fma_f32 v[6:7], v[6:7], v[54:55], v[120:121] op_sel_hi:[1,0,1]
	v_pk_fma_f32 v[8:9], v[8:9], v[54:55], v[122:123] op_sel:[0,1,0]
	v_pk_fma_f32 v[132:133], v[60:61], v[62:63], v[132:133] op_sel:[0,1,0]
	v_pk_fma_f32 v[10:11], v[10:11], v[56:57], v[124:125] op_sel_hi:[1,0,1]
	v_pk_fma_f32 v[12:13], v[12:13], v[56:57], v[126:127] op_sel:[0,1,0]
	v_pk_fma_f32 v[14:15], v[14:15], v[58:59], v[128:129] op_sel_hi:[1,0,1]
	v_pk_fma_f32 v[16:17], v[16:17], v[58:59], v[130:131] op_sel:[0,1,0]
	ds_write_b64 v135, v[132:133] offset:56832
	s_waitcnt lgkmcnt(9)
	v_pk_mul_f32 v[108:109], v[2:3], v[64:65] op_sel_hi:[1,0]
	v_pk_mul_f32 v[110:111], v[4:5], v[64:65] op_sel:[0,1]
	v_pk_mul_f32 v[112:113], v[2:3], v[72:73] op_sel_hi:[1,0]
	v_pk_mul_f32 v[114:115], v[4:5], v[72:73] op_sel:[0,1]
	v_pk_fma_f32 v[108:109], v[6:7], v[66:67], v[108:109] op_sel_hi:[1,0,1]
	v_pk_fma_f32 v[110:111], v[8:9], v[66:67], v[110:111] op_sel:[0,1,0]
	v_pk_fma_f32 v[112:113], v[6:7], v[74:75], v[112:113] op_sel_hi:[1,0,1]
	v_pk_fma_f32 v[114:115], v[8:9], v[74:75], v[114:115] op_sel:[0,1,0]
	v_pk_fma_f32 v[108:109], v[10:11], v[68:69], v[108:109] op_sel_hi:[1,0,1]
	v_pk_fma_f32 v[110:111], v[12:13], v[68:69], v[110:111] op_sel:[0,1,0]
	v_pk_fma_f32 v[112:113], v[10:11], v[76:77], v[112:113] op_sel_hi:[1,0,1]
	v_pk_fma_f32 v[114:115], v[12:13], v[76:77], v[114:115] op_sel:[0,1,0]
	v_pk_fma_f32 v[108:109], v[14:15], v[70:71], v[108:109] op_sel_hi:[1,0,1]
	v_pk_fma_f32 v[110:111], v[16:17], v[70:71], v[110:111] op_sel:[0,1,0]
	v_pk_fma_f32 v[112:113], v[14:15], v[78:79], v[112:113] op_sel_hi:[1,0,1]
	v_pk_fma_f32 v[114:115], v[16:17], v[78:79], v[114:115] op_sel:[0,1,0]
	v_pk_add_f32 v[108:109], v[108:109], v[110:111]
	v_pk_add_f32 v[112:113], v[112:113], v[114:115]
	s_waitcnt lgkmcnt(7)
	v_pk_mul_f32 v[116:117], v[104:105], v[80:81] op_sel_hi:[1,0]
	v_pk_mul_f32 v[118:119], v[104:105], v[80:81] op_sel:[0,1]
	v_pk_mul_f32 v[120:121], v[104:105], v[82:83] op_sel_hi:[1,0]
	v_pk_mul_f32 v[122:123], v[104:105], v[82:83] op_sel:[0,1]
	v_add_f32_dpp v108, v108, v108 quad_perm:[1,0,3,2] row_mask:0xf bank_mask:0xf bound_ctrl:1
	v_add_f32_dpp v109, v109, v109 quad_perm:[1,0,3,2] row_mask:0xf bank_mask:0xf bound_ctrl:1
	v_add_f32_dpp v112, v112, v112 quad_perm:[1,0,3,2] row_mask:0xf bank_mask:0xf bound_ctrl:1
	v_add_f32_dpp v113, v113, v113 quad_perm:[1,0,3,2] row_mask:0xf bank_mask:0xf bound_ctrl:1
	s_waitcnt lgkmcnt(6)
	v_pk_mul_f32 v[124:125], v[104:105], v[84:85] op_sel_hi:[1,0]
	v_pk_mul_f32 v[126:127], v[104:105], v[84:85] op_sel:[0,1]
	v_pk_mul_f32 v[128:129], v[104:105], v[86:87] op_sel_hi:[1,0]
	v_pk_mul_f32 v[130:131], v[104:105], v[86:87] op_sel:[0,1]
	v_add_f32_dpp v108, v108, v108 quad_perm:[2,3,0,1] row_mask:0xf bank_mask:0xf bound_ctrl:1
	v_add_f32_dpp v109, v109, v109 quad_perm:[2,3,0,1] row_mask:0xf bank_mask:0xf bound_ctrl:1
	v_add_f32_dpp v112, v112, v112 quad_perm:[2,3,0,1] row_mask:0xf bank_mask:0xf bound_ctrl:1
	v_add_f32_dpp v113, v113, v113 quad_perm:[2,3,0,1] row_mask:0xf bank_mask:0xf bound_ctrl:1
	s_nop 0
	v_add_f32_dpp v108, v108, v108 row_half_mirror row_mask:0xf bank_mask:0xf bound_ctrl:1
	v_add_f32_dpp v109, v109, v109 row_half_mirror row_mask:0xf bank_mask:0xf bound_ctrl:1
	v_add_f32_dpp v112, v112, v112 row_half_mirror row_mask:0xf bank_mask:0xf bound_ctrl:1
	v_add_f32_dpp v113, v113, v113 row_half_mirror row_mask:0xf bank_mask:0xf bound_ctrl:1
	s_waitcnt lgkmcnt(3)
	s_nop 0
	v_pk_fma_f32 v[116:117], v[108:109], v[88:89], v[116:117] op_sel_hi:[1,0,1] neg_lo:[1,0,0] neg_hi:[1,0,0]
	v_pk_fma_f32 v[118:119], v[108:109], v[88:89], v[118:119] op_sel:[0,1,0] neg_lo:[1,0,0] neg_hi:[1,0,0]
	v_pk_fma_f32 v[120:121], v[108:109], v[90:91], v[120:121] op_sel_hi:[1,0,1] neg_lo:[1,0,0] neg_hi:[1,0,0]
	v_pk_fma_f32 v[122:123], v[108:109], v[90:91], v[122:123] op_sel:[0,1,0] neg_lo:[1,0,0] neg_hi:[1,0,0]
	v_pk_fma_f32 v[124:125], v[108:109], v[92:93], v[124:125] op_sel_hi:[1,0,1] neg_lo:[1,0,0] neg_hi:[1,0,0]
	v_pk_fma_f32 v[126:127], v[108:109], v[92:93], v[126:127] op_sel:[0,1,0] neg_lo:[1,0,0] neg_hi:[1,0,0]
	v_pk_fma_f32 v[128:129], v[108:109], v[94:95], v[128:129] op_sel_hi:[1,0,1] neg_lo:[1,0,0] neg_hi:[1,0,0]
	v_pk_fma_f32 v[130:131], v[108:109], v[94:95], v[130:131] op_sel:[0,1,0] neg_lo:[1,0,0] neg_hi:[1,0,0]
	v_pk_fma_f32 v[132:133], v[108:109], v[106:107], v[112:113] op_sel_hi:[1,0,1] neg_lo:[1,0,0] neg_hi:[1,0,0]
	s_waitcnt lgkmcnt(1)
	v_pk_fma_f32 v[2:3], v[2:3], v[96:97], v[116:117] op_sel_hi:[1,0,1]
	v_pk_fma_f32 v[4:5], v[4:5], v[96:97], v[118:119] op_sel:[0,1,0]
	v_pk_fma_f32 v[6:7], v[6:7], v[98:99], v[120:121] op_sel_hi:[1,0,1]
	v_pk_fma_f32 v[8:9], v[8:9], v[98:99], v[122:123] op_sel:[0,1,0]
	v_pk_fma_f32 v[132:133], v[104:105], v[106:107], v[132:133] op_sel:[0,1,0]
	v_pk_fma_f32 v[10:11], v[10:11], v[100:101], v[124:125] op_sel_hi:[1,0,1]
	v_pk_fma_f32 v[12:13], v[12:13], v[100:101], v[126:127] op_sel:[0,1,0]
	v_pk_fma_f32 v[14:15], v[14:15], v[102:103], v[128:129] op_sel_hi:[1,0,1]
	v_pk_fma_f32 v[16:17], v[16:17], v[102:103], v[130:131] op_sel:[0,1,0]
	ds_write_b64 v135, v[132:133] offset:57088
	s_add_i32 s13, s13, 1
	s_cmpk_eq_i32 s13, 0x80
	s_cbranch_scc0 .Lscan_chunk

.LBB0_1797:
	s_bitcmp1_b32 s10, 0
	s_cselect_b32 s10, 0x5800, 0
	s_add_i32 s56, s10, 0
	v_add3_u32 v0, s56, v204, v205
	ds_read_b128 v[50:53], v0
	ds_read_b128 v[178:181], v0 offset:32
	ds_read_b128 v[182:185], v0 offset:6656
	ds_read_b128 v[186:189], v0 offset:6688
	s_waitcnt lgkmcnt(3)
	v_mfma_f32_32x32x16_bf16 v[66:81], v[50:53], v[82:85], v[34:49]
	s_waitcnt lgkmcnt(1)
	v_mfma_f32_32x32x16_bf16 v[50:65], v[182:185], v[82:85], v[34:49]
	v_mfma_f32_32x32x16_bf16 v[66:81], v[178:181], v[86:89], v[66:81]
	ds_read_b128 v[178:181], v0 offset:64
	ds_read_b128 v[182:185], v0 offset:96
	s_waitcnt lgkmcnt(2)
	v_mfma_f32_32x32x16_bf16 v[50:65], v[186:189], v[86:89], v[50:65]
	s_waitcnt lgkmcnt(1)
	v_mfma_f32_32x32x16_bf16 v[66:81], v[178:181], v[90:93], v[66:81]
	ds_read_b128 v[178:181], v0 offset:6720
	ds_read_b128 v[186:189], v0 offset:6752
	s_waitcnt lgkmcnt(1)
	v_mfma_f32_32x32x16_bf16 v[50:65], v[178:181], v[90:93], v[50:65]
	v_mfma_f32_32x32x16_bf16 v[66:81], v[182:185], v[94:97], v[66:81]
	ds_read_b128 v[178:181], v0 offset:128
	ds_read_b128 v[182:185], v0 offset:160
	s_waitcnt lgkmcnt(2)
	v_mfma_f32_32x32x16_bf16 v[50:65], v[186:189], v[94:97], v[50:65]
	s_waitcnt lgkmcnt(1)
	v_mfma_f32_32x32x16_bf16 v[66:81], v[178:181], v[98:101], v[66:81]
	ds_read_b128 v[178:181], v0 offset:6784
	ds_read_b128 v[186:189], v0 offset:6816
	s_waitcnt lgkmcnt(1)
	v_mfma_f32_32x32x16_bf16 v[50:65], v[178:181], v[98:101], v[50:65]
	v_mfma_f32_32x32x16_bf16 v[66:81], v[182:185], v[102:105], v[66:81]
	s_waitcnt lgkmcnt(0)
	v_mfma_f32_32x32x16_bf16 v[50:65], v[186:189], v[102:105], v[50:65]
	s_nop 15
	s_nop 7
	s_nop 0
	v_max3_f32 v0, v66, v67, v50
	v_max3_f32 v178, v68, v69, v51
	s_nop 0
	v_max3_f32 v0, v0, v52, v53
	v_max3_f32 v178, v178, v72, v73
	s_nop 0
	v_max3_f32 v0, v0, v70, v71
	v_max3_f32 v178, v178, v56, v57
	s_nop 0
	v_max3_f32 v0, v0, v54, v55
	v_max3_f32 v178, v178, v76, v77
	s_nop 0
	v_max3_f32 v0, v0, v74, v75
	v_max3_f32 v178, v178, v60, v61
	s_nop 0
	v_max3_f32 v0, v0, v58, v59
	v_max3_f32 v178, v178, v80, v81
	s_nop 0
	v_max3_f32 v0, v0, v78, v79
	v_max3_f32 v178, v178, v64, v65
	s_nop 0
	v_max3_f32 v0, v0, v62, v63
	v_max_f32_e32 v178, v178, v178
	v_max_f32_e32 v0, v0, v0
	v_max_f32_e32 v0, v0, v178
	ds_bpermute_b32 v178, v206, v0
	s_waitcnt lgkmcnt(0)
	v_max_f32_e32 v178, v178, v178
	v_max_f32_e32 v0, v0, v178
	v_cmp_lt_f32_e32 vcc, 0x41000000, v0
	s_cbranch_vccz .LBB0_1801
	v_max_f32_e32 v0, v0, v0
	v_max_f32_e32 v0, 0, v0
	v_exp_f32_e64 v225, -v0
	s_and_saveexec_b64 s[10:11], s[6:7]
	ds_write_b32 v207, v225 offset:45056
	s_or_b64 exec, exec, s[10:11]
	v_add_f32_e32 v173, v173, v0
	v_pk_add_f32 v[66:67], v[66:67], v[0:1] op_sel_hi:[1,0] neg_lo:[0,1] neg_hi:[0,1]
	v_pk_add_f32 v[50:51], v[50:51], v[0:1] op_sel_hi:[1,0] neg_lo:[0,1] neg_hi:[0,1]
	v_pk_add_f32 v[68:69], v[68:69], v[0:1] op_sel_hi:[1,0] neg_lo:[0,1] neg_hi:[0,1]
	v_pk_add_f32 v[52:53], v[52:53], v[0:1] op_sel_hi:[1,0] neg_lo:[0,1] neg_hi:[0,1]
	v_pk_add_f32 v[70:71], v[70:71], v[0:1] op_sel_hi:[1,0] neg_lo:[0,1] neg_hi:[0,1]
	v_pk_add_f32 v[54:55], v[54:55], v[0:1] op_sel_hi:[1,0] neg_lo:[0,1] neg_hi:[0,1]
	v_pk_add_f32 v[72:73], v[72:73], v[0:1] op_sel_hi:[1,0] neg_lo:[0,1] neg_hi:[0,1]
	v_pk_add_f32 v[56:57], v[56:57], v[0:1] op_sel_hi:[1,0] neg_lo:[0,1] neg_hi:[0,1]
	v_pk_add_f32 v[74:75], v[74:75], v[0:1] op_sel_hi:[1,0] neg_lo:[0,1] neg_hi:[0,1]
	v_pk_add_f32 v[58:59], v[58:59], v[0:1] op_sel_hi:[1,0] neg_lo:[0,1] neg_hi:[0,1]
	v_pk_add_f32 v[76:77], v[76:77], v[0:1] op_sel_hi:[1,0] neg_lo:[0,1] neg_hi:[0,1]
	v_pk_add_f32 v[60:61], v[60:61], v[0:1] op_sel_hi:[1,0] neg_lo:[0,1] neg_hi:[0,1]
	v_pk_add_f32 v[78:79], v[78:79], v[0:1] op_sel_hi:[1,0] neg_lo:[0,1] neg_hi:[0,1]
	v_pk_add_f32 v[62:63], v[62:63], v[0:1] op_sel_hi:[1,0] neg_lo:[0,1] neg_hi:[0,1]
	v_pk_add_f32 v[80:81], v[80:81], v[0:1] op_sel_hi:[1,0] neg_lo:[0,1] neg_hi:[0,1]
	v_pk_add_f32 v[64:65], v[64:65], v[0:1] op_sel_hi:[1,0] neg_lo:[0,1] neg_hi:[0,1]
	s_waitcnt lgkmcnt(0)
	v_add_u32_e32 v0, s50, v205
	ds_read_b128 v[178:181], v0 offset:45120
	ds_read_b128 v[182:185], v0 offset:45152
	ds_read_b128 v[186:189], v0 offset:45056
	ds_read_b128 v[190:193], v0 offset:45088
	v_xor_b32_e32 v34, 0x80000000, v173
	v_mov_b32_e32 v35, v34
	v_mov_b32_e32 v36, v34
	v_mov_b32_e32 v37, v34
	v_mov_b32_e32 v38, v34
	v_mov_b32_e32 v39, v34
	v_mov_b32_e32 v40, v34
	v_mov_b32_e32 v41, v34
	v_mov_b32_e32 v42, v34
	v_mov_b32_e32 v43, v34
	v_mov_b32_e32 v44, v34
	v_mov_b32_e32 v45, v34
	v_mov_b32_e32 v46, v34
	v_mov_b32_e32 v47, v34
	v_mov_b32_e32 v48, v34
	v_mov_b32_e32 v49, v34
	v_mul_f32_e32 v224, v224, v225
	s_waitcnt lgkmcnt(2)
	v_pk_mul_f32 v[30:31], v[30:31], v[182:183]
	v_pk_mul_f32 v[26:27], v[26:27], v[178:179]
	s_waitcnt lgkmcnt(0)
	v_pk_mul_f32 v[22:23], v[22:23], v[190:191]
	v_pk_mul_f32 v[32:33], v[32:33], v[184:185]
	v_pk_mul_f32 v[28:29], v[28:29], v[180:181]
	v_pk_mul_f32 v[24:25], v[24:25], v[192:193]
	v_pk_mul_f32 v[20:21], v[20:21], v[188:189]
	v_pk_mul_f32 v[18:19], v[18:19], v[186:187]
	v_pk_mul_f32 v[14:15], v[14:15], v[182:183]
	v_pk_mul_f32 v[10:11], v[10:11], v[178:179]
	v_pk_mul_f32 v[6:7], v[6:7], v[190:191]
	v_pk_mul_f32 v[16:17], v[16:17], v[184:185]
	v_pk_mul_f32 v[12:13], v[12:13], v[180:181]
	v_pk_mul_f32 v[8:9], v[8:9], v[192:193]
	v_pk_mul_f32 v[4:5], v[4:5], v[188:189]
	v_pk_mul_f32 v[2:3], v[2:3], v[186:187]
